# v28 with sc1 write-through on hand-written epilogue stores
# baseline (speedup 1.0000x reference)
.LBB0_1051:
	ds_read_b128 v[152:155], v149
	ds_read_b128 v[156:159], v149 offset:1024
	ds_read_b128 v[160:163], v149 offset:2048
	ds_read_b128 v[164:167], v149 offset:3072
	s_add_u32 s4, s18, 0x100
	s_addc_u32 s5, s19, 0
	s_cmp_eq_u32 s45, 12
	s_cselect_b32 s23, s15, s5
	s_cselect_b32 s22, s14, s4
	s_cselect_b32 s21, s13, s44
	s_cselect_b32 s20, s42, s43
	v_lshl_add_u64 v[168:169], s[18:19], 0, v[140:141]
	s_add_i32 m0, s29, 0xc000
	ds_read_b128 v[172:175], v150
	ds_read_b128 v[176:179], v150 offset:1024
	ds_read_b128 v[180:183], v150 offset:2048
	ds_read_b128 v[184:187], v150 offset:3072
	ds_read_b128 v[188:191], v150 offset:4096
	ds_read_b128 v[192:195], v150 offset:5120
	ds_read_b128 v[196:199], v150 offset:6144
	ds_read_b128 v[200:203], v150 offset:7168
	global_load_lds_dwordx4 v[168:169], off
	v_lshl_add_u64 v[168:169], s[18:19], 0, v[138:139]
	s_add_i32 m0, s29, 0xe000
	s_nop 0
	global_load_lds_dwordx4 v[168:169], off
	s_waitcnt lgkmcnt(8)
	s_barrier
	s_waitcnt lgkmcnt(0)
	s_setprio 1
	s_waitcnt lgkmcnt(0)
	v_mfma_f32_16x16x32_bf16 v[124:127], v[152:155], v[172:175], v[124:127]
	v_mfma_f32_16x16x32_bf16 v[120:123], v[160:163], v[172:175], v[120:123]
	v_mfma_f32_16x16x32_bf16 v[116:119], v[152:155], v[180:183], v[116:119]
	v_mfma_f32_16x16x32_bf16 v[108:111], v[160:163], v[180:183], v[108:111]
	v_mfma_f32_16x16x32_bf16 v[100:103], v[152:155], v[188:191], v[100:103]
	v_mfma_f32_16x16x32_bf16 v[92:95], v[160:163], v[188:191], v[92:95]
	v_mfma_f32_16x16x32_bf16 v[84:87], v[152:155], v[196:199], v[84:87]
	v_mfma_f32_16x16x32_bf16 v[76:79], v[160:163], v[196:199], v[76:79]
	v_mfma_f32_16x16x32_bf16 v[124:127], v[156:159], v[176:179], v[124:127]
	v_mfma_f32_16x16x32_bf16 v[120:123], v[164:167], v[176:179], v[120:123]
	v_mfma_f32_16x16x32_bf16 v[116:119], v[156:159], v[184:187], v[116:119]
	v_mfma_f32_16x16x32_bf16 v[108:111], v[164:167], v[184:187], v[108:111]
	v_mfma_f32_16x16x32_bf16 v[100:103], v[156:159], v[192:195], v[100:103]
	v_mfma_f32_16x16x32_bf16 v[92:95], v[164:167], v[192:195], v[92:95]
	v_mfma_f32_16x16x32_bf16 v[84:87], v[156:159], v[200:203], v[84:87]
	v_mfma_f32_16x16x32_bf16 v[76:79], v[164:167], v[200:203], v[76:79]
	s_setprio 0
	s_barrier
	s_add_i32 s18, s36, s28
	v_lshl_add_u64 v[168:169], s[20:21], 0, v[132:133]
	s_mov_b32 m0, s18
	ds_read_b128 v[204:207], v151
	ds_read_b128 v[208:211], v151 offset:1024
	ds_read_b128 v[212:215], v151 offset:2048
	ds_read_b128 v[216:219], v151 offset:3072
	global_load_lds_dwordx4 v[168:169], off
	v_lshl_add_u64 v[220:221], s[20:21], 0, v[128:129]
	s_add_i32 m0, s18, 0x2000
	s_nop 0
	global_load_lds_dwordx4 v[220:221], off
	s_barrier
	s_waitcnt lgkmcnt(0)
	s_setprio 1
	s_waitcnt lgkmcnt(0)
	v_mfma_f32_16x16x32_bf16 v[112:115], v[204:207], v[172:175], v[112:115]
	v_mfma_f32_16x16x32_bf16 v[104:107], v[212:215], v[172:175], v[104:107]
	v_mfma_f32_16x16x32_bf16 v[96:99], v[204:207], v[180:183], v[96:99]
	v_mfma_f32_16x16x32_bf16 v[88:91], v[212:215], v[180:183], v[88:91]
	v_mfma_f32_16x16x32_bf16 v[80:83], v[204:207], v[188:191], v[80:83]
	v_mfma_f32_16x16x32_bf16 v[72:75], v[212:215], v[188:191], v[72:75]
	v_mfma_f32_16x16x32_bf16 v[68:71], v[204:207], v[196:199], v[68:71]
	v_mfma_f32_16x16x32_bf16 v[64:67], v[212:215], v[196:199], v[64:67]
	v_mfma_f32_16x16x32_bf16 v[112:115], v[208:211], v[176:179], v[112:115]
	v_mfma_f32_16x16x32_bf16 v[104:107], v[216:219], v[176:179], v[104:107]
	v_mfma_f32_16x16x32_bf16 v[96:99], v[208:211], v[184:187], v[96:99]
	v_mfma_f32_16x16x32_bf16 v[88:91], v[216:219], v[184:187], v[88:91]
	v_mfma_f32_16x16x32_bf16 v[80:83], v[208:211], v[192:195], v[80:83]
	v_mfma_f32_16x16x32_bf16 v[72:75], v[216:219], v[192:195], v[72:75]
	v_mfma_f32_16x16x32_bf16 v[68:71], v[208:211], v[200:203], v[68:71]
	v_mfma_f32_16x16x32_bf16 v[64:67], v[216:219], v[200:203], v[64:67]
	s_setprio 0
	s_mov_b32 m0, s29
	v_lshl_add_u64 v[222:223], s[22:23], 0, v[134:135]
	s_barrier
	ds_read_b128 v[172:175], v150 offset:16384
	ds_read_b128 v[176:179], v150 offset:17408
	ds_read_b128 v[180:183], v150 offset:18432
	ds_read_b128 v[184:187], v150 offset:19456
	ds_read_b128 v[188:191], v150 offset:20480
	ds_read_b128 v[192:195], v150 offset:21504
	ds_read_b128 v[196:199], v150 offset:22528
	ds_read_b128 v[200:203], v150 offset:23552
	global_load_lds_dwordx4 v[222:223], off
	v_lshl_add_u64 v[224:225], s[22:23], 0, v[130:131]
	s_mov_b32 m0, s30
	s_nop 0
	global_load_lds_dwordx4 v[224:225], off
	s_barrier
	s_waitcnt lgkmcnt(0)
	s_setprio 1
	s_waitcnt lgkmcnt(0)
	v_mfma_f32_16x16x32_bf16 v[60:63], v[152:155], v[172:175], v[60:63]
	v_mfma_f32_16x16x32_bf16 v[56:59], v[160:163], v[172:175], v[56:59]
	v_mfma_f32_16x16x32_bf16 v[52:55], v[152:155], v[180:183], v[52:55]
	v_mfma_f32_16x16x32_bf16 v[44:47], v[160:163], v[180:183], v[44:47]
	v_mfma_f32_16x16x32_bf16 v[36:39], v[152:155], v[188:191], v[36:39]
	v_mfma_f32_16x16x32_bf16 v[28:31], v[160:163], v[188:191], v[28:31]
	v_mfma_f32_16x16x32_bf16 v[20:23], v[152:155], v[196:199], v[20:23]
	v_mfma_f32_16x16x32_bf16 v[12:15], v[160:163], v[196:199], v[12:15]
	v_mfma_f32_16x16x32_bf16 v[60:63], v[156:159], v[176:179], v[60:63]
	v_mfma_f32_16x16x32_bf16 v[56:59], v[164:167], v[176:179], v[56:59]
	v_mfma_f32_16x16x32_bf16 v[52:55], v[156:159], v[184:187], v[52:55]
	v_mfma_f32_16x16x32_bf16 v[44:47], v[164:167], v[184:187], v[44:47]
	v_mfma_f32_16x16x32_bf16 v[36:39], v[156:159], v[192:195], v[36:39]
	v_mfma_f32_16x16x32_bf16 v[28:31], v[164:167], v[192:195], v[28:31]
	v_mfma_f32_16x16x32_bf16 v[20:23], v[156:159], v[200:203], v[20:23]
	v_mfma_f32_16x16x32_bf16 v[12:15], v[164:167], v[200:203], v[12:15]
	s_setprio 0
	s_barrier
	s_add_u32 s18, s20, 0x40000
	s_addc_u32 s19, s21, 0
	s_add_i32 s46, s37, s28
	v_lshl_add_u64 v[152:153], s[18:19], 0, v[132:133]
	s_mov_b32 m0, s46
	s_nop 0
	global_load_lds_dwordx4 v[152:153], off
	v_lshl_add_u64 v[152:153], s[18:19], 0, v[128:129]
	s_add_i32 m0, s46, 0x2000
	s_nop 0
	global_load_lds_dwordx4 v[152:153], off
	s_waitcnt vmcnt(6)
	s_barrier
	s_setprio 1
	v_mfma_f32_16x16x32_bf16 v[48:51], v[204:207], v[172:175], v[48:51]
	v_mfma_f32_16x16x32_bf16 v[40:43], v[212:215], v[172:175], v[40:43]
	v_mfma_f32_16x16x32_bf16 v[32:35], v[204:207], v[180:183], v[32:35]
	v_mfma_f32_16x16x32_bf16 v[24:27], v[212:215], v[180:183], v[24:27]
	v_mfma_f32_16x16x32_bf16 v[16:19], v[204:207], v[188:191], v[16:19]
	v_mfma_f32_16x16x32_bf16 v[8:11], v[212:215], v[188:191], v[8:11]
	v_mfma_f32_16x16x32_bf16 v[4:7], v[204:207], v[196:199], v[4:7]
	v_mfma_f32_16x16x32_bf16 v[0:3], v[212:215], v[196:199], v[0:3]
	v_mfma_f32_16x16x32_bf16 v[48:51], v[208:211], v[176:179], v[48:51]
	v_mfma_f32_16x16x32_bf16 v[40:43], v[216:219], v[176:179], v[40:43]
	v_mfma_f32_16x16x32_bf16 v[32:35], v[208:211], v[184:187], v[32:35]
	v_mfma_f32_16x16x32_bf16 v[24:27], v[216:219], v[184:187], v[24:27]
	v_mfma_f32_16x16x32_bf16 v[16:19], v[208:211], v[192:195], v[16:19]
	v_mfma_f32_16x16x32_bf16 v[8:11], v[216:219], v[192:195], v[8:11]
	v_mfma_f32_16x16x32_bf16 v[4:7], v[208:211], v[200:203], v[4:7]
	v_mfma_f32_16x16x32_bf16 v[0:3], v[216:219], v[200:203], v[0:3]
	s_setprio 0
	s_add_i32 s46, 0, 0x18000
	v_add_u32_e32 v164, s46, v148
	s_barrier
	ds_read_b128 v[152:155], v164
	ds_read_b128 v[156:159], v164 offset:1024
	ds_read_b128 v[160:163], v164 offset:2048
	ds_read_b128 v[164:167], v164 offset:3072
	s_add_u32 s18, s22, 0xea000
	s_addc_u32 s19, s23, 0
	s_mov_b32 m0, s31
	v_lshl_add_u64 v[204:205], s[18:19], 0, v[134:135]
	ds_read_b128 v[172:175], v150 offset:32768
	ds_read_b128 v[176:179], v150 offset:33792
	ds_read_b128 v[180:183], v150 offset:34816
	ds_read_b128 v[184:187], v150 offset:35840
	ds_read_b128 v[188:191], v150 offset:36864
	ds_read_b128 v[192:195], v150 offset:37888
	ds_read_b128 v[196:199], v150 offset:38912
	ds_read_b128 v[200:203], v150 offset:39936
	global_load_lds_dwordx4 v[204:205], off
	v_lshl_add_u64 v[204:205], s[18:19], 0, v[130:131]
	s_mov_b32 m0, s33
	s_nop 0
	global_load_lds_dwordx4 v[204:205], off
	s_waitcnt lgkmcnt(8)
	s_barrier
	s_waitcnt lgkmcnt(0)
	s_setprio 1
	s_waitcnt lgkmcnt(0)
	v_mfma_f32_16x16x32_bf16 v[124:127], v[152:155], v[172:175], v[124:127]
	v_mfma_f32_16x16x32_bf16 v[120:123], v[160:163], v[172:175], v[120:123]
	v_mfma_f32_16x16x32_bf16 v[116:119], v[152:155], v[180:183], v[116:119]
	v_mfma_f32_16x16x32_bf16 v[108:111], v[160:163], v[180:183], v[108:111]
	v_mfma_f32_16x16x32_bf16 v[100:103], v[152:155], v[188:191], v[100:103]
	v_mfma_f32_16x16x32_bf16 v[92:95], v[160:163], v[188:191], v[92:95]
	v_mfma_f32_16x16x32_bf16 v[84:87], v[152:155], v[196:199], v[84:87]
	v_mfma_f32_16x16x32_bf16 v[76:79], v[160:163], v[196:199], v[76:79]
	v_mfma_f32_16x16x32_bf16 v[124:127], v[156:159], v[176:179], v[124:127]
	v_mfma_f32_16x16x32_bf16 v[120:123], v[164:167], v[176:179], v[120:123]
	v_mfma_f32_16x16x32_bf16 v[116:119], v[156:159], v[184:187], v[116:119]
	v_mfma_f32_16x16x32_bf16 v[108:111], v[164:167], v[184:187], v[108:111]
	v_mfma_f32_16x16x32_bf16 v[100:103], v[156:159], v[192:195], v[100:103]
	v_mfma_f32_16x16x32_bf16 v[92:95], v[164:167], v[192:195], v[92:95]
	v_mfma_f32_16x16x32_bf16 v[84:87], v[156:159], v[200:203], v[84:87]
	v_mfma_f32_16x16x32_bf16 v[76:79], v[164:167], v[200:203], v[76:79]
	s_setprio 0
	s_barrier
	s_add_i32 s22, 0, 0x1c000
	s_add_i32 s18, s46, s28
	v_add_u32_e32 v171, s22, v148
	v_lshl_add_u64 v[168:169], v[168:169], 0, s[10:11]
	s_mov_b32 m0, s18
	ds_read_b128 v[204:207], v171
	ds_read_b128 v[208:211], v171 offset:1024
	ds_read_b128 v[212:215], v171 offset:2048
	ds_read_b128 v[216:219], v171 offset:3072
	global_load_lds_dwordx4 v[168:169], off
	v_lshl_add_u64 v[168:169], v[220:221], 0, s[10:11]
	s_add_i32 m0, s18, 0x2000
	s_nop 0
	global_load_lds_dwordx4 v[168:169], off
	s_barrier
	s_waitcnt lgkmcnt(0)
	s_setprio 1
	s_waitcnt lgkmcnt(0)
	v_mfma_f32_16x16x32_bf16 v[112:115], v[204:207], v[172:175], v[112:115]
	v_mfma_f32_16x16x32_bf16 v[104:107], v[212:215], v[172:175], v[104:107]
	v_mfma_f32_16x16x32_bf16 v[96:99], v[204:207], v[180:183], v[96:99]
	v_mfma_f32_16x16x32_bf16 v[88:91], v[212:215], v[180:183], v[88:91]
	v_mfma_f32_16x16x32_bf16 v[80:83], v[204:207], v[188:191], v[80:83]
	v_mfma_f32_16x16x32_bf16 v[72:75], v[212:215], v[188:191], v[72:75]
	v_mfma_f32_16x16x32_bf16 v[68:71], v[204:207], v[196:199], v[68:71]
	v_mfma_f32_16x16x32_bf16 v[64:67], v[212:215], v[196:199], v[64:67]
	v_mfma_f32_16x16x32_bf16 v[112:115], v[208:211], v[176:179], v[112:115]
	v_mfma_f32_16x16x32_bf16 v[104:107], v[216:219], v[176:179], v[104:107]
	v_mfma_f32_16x16x32_bf16 v[96:99], v[208:211], v[184:187], v[96:99]
	v_mfma_f32_16x16x32_bf16 v[88:91], v[216:219], v[184:187], v[88:91]
	v_mfma_f32_16x16x32_bf16 v[80:83], v[208:211], v[192:195], v[80:83]
	v_mfma_f32_16x16x32_bf16 v[72:75], v[216:219], v[192:195], v[72:75]
	v_mfma_f32_16x16x32_bf16 v[68:71], v[208:211], v[200:203], v[68:71]
	v_mfma_f32_16x16x32_bf16 v[64:67], v[216:219], v[200:203], v[64:67]
	s_setprio 0
	s_mov_b32 m0, s34
	v_lshl_add_u64 v[168:169], v[222:223], 0, s[10:11]
	s_barrier
	ds_read_b128 v[172:175], v150 offset:49152
	ds_read_b128 v[176:179], v150 offset:50176
	ds_read_b128 v[180:183], v150 offset:51200
	ds_read_b128 v[184:187], v150 offset:52224
	ds_read_b128 v[188:191], v150 offset:53248
	ds_read_b128 v[192:195], v150 offset:54272
	ds_read_b128 v[196:199], v150 offset:55296
	ds_read_b128 v[200:203], v150 offset:56320
	global_load_lds_dwordx4 v[168:169], off
	v_lshl_add_u64 v[168:169], v[224:225], 0, s[10:11]
	s_mov_b32 m0, s35
	s_nop 0
	global_load_lds_dwordx4 v[168:169], off
	s_barrier
	s_waitcnt lgkmcnt(0)
	s_setprio 1
	s_waitcnt lgkmcnt(0)
	v_mfma_f32_16x16x32_bf16 v[60:63], v[152:155], v[172:175], v[60:63]
	v_mfma_f32_16x16x32_bf16 v[56:59], v[160:163], v[172:175], v[56:59]
	v_mfma_f32_16x16x32_bf16 v[52:55], v[152:155], v[180:183], v[52:55]
	v_mfma_f32_16x16x32_bf16 v[44:47], v[160:163], v[180:183], v[44:47]
	v_mfma_f32_16x16x32_bf16 v[36:39], v[152:155], v[188:191], v[36:39]
	v_mfma_f32_16x16x32_bf16 v[28:31], v[160:163], v[188:191], v[28:31]
	v_mfma_f32_16x16x32_bf16 v[20:23], v[152:155], v[196:199], v[20:23]
	v_mfma_f32_16x16x32_bf16 v[12:15], v[160:163], v[196:199], v[12:15]
	v_mfma_f32_16x16x32_bf16 v[60:63], v[156:159], v[176:179], v[60:63]
	v_mfma_f32_16x16x32_bf16 v[56:59], v[164:167], v[176:179], v[56:59]
	v_mfma_f32_16x16x32_bf16 v[52:55], v[156:159], v[184:187], v[52:55]
	v_mfma_f32_16x16x32_bf16 v[44:47], v[164:167], v[184:187], v[44:47]
	v_mfma_f32_16x16x32_bf16 v[36:39], v[156:159], v[192:195], v[36:39]
	v_mfma_f32_16x16x32_bf16 v[28:31], v[164:167], v[192:195], v[28:31]
	v_mfma_f32_16x16x32_bf16 v[20:23], v[156:159], v[200:203], v[20:23]
	v_mfma_f32_16x16x32_bf16 v[12:15], v[164:167], v[200:203], v[12:15]
	s_setprio 0
	s_barrier
	s_add_u32 s18, s20, 0x40080
	s_addc_u32 s19, s21, 0
	s_add_i32 s20, s22, s28
	v_lshl_add_u64 v[152:153], s[18:19], 0, v[132:133]
	s_mov_b32 m0, s20
	s_nop 0
	global_load_lds_dwordx4 v[152:153], off
	v_lshl_add_u64 v[152:153], s[18:19], 0, v[128:129]
	s_add_i32 m0, s20, 0x2000
	s_nop 0
	global_load_lds_dwordx4 v[152:153], off
	s_waitcnt vmcnt(6)
	s_barrier
	s_setprio 1
	v_mfma_f32_16x16x32_bf16 v[48:51], v[204:207], v[172:175], v[48:51]
	v_mfma_f32_16x16x32_bf16 v[40:43], v[212:215], v[172:175], v[40:43]
	v_mfma_f32_16x16x32_bf16 v[32:35], v[204:207], v[180:183], v[32:35]
	v_mfma_f32_16x16x32_bf16 v[24:27], v[212:215], v[180:183], v[24:27]
	v_mfma_f32_16x16x32_bf16 v[16:19], v[204:207], v[188:191], v[16:19]
	v_mfma_f32_16x16x32_bf16 v[8:11], v[212:215], v[188:191], v[8:11]
	v_mfma_f32_16x16x32_bf16 v[4:7], v[204:207], v[196:199], v[4:7]
	v_mfma_f32_16x16x32_bf16 v[0:3], v[212:215], v[196:199], v[0:3]
	v_mfma_f32_16x16x32_bf16 v[48:51], v[208:211], v[176:179], v[48:51]
	v_mfma_f32_16x16x32_bf16 v[40:43], v[216:219], v[176:179], v[40:43]
	v_mfma_f32_16x16x32_bf16 v[32:35], v[208:211], v[184:187], v[32:35]
	v_mfma_f32_16x16x32_bf16 v[24:27], v[216:219], v[184:187], v[24:27]
	v_mfma_f32_16x16x32_bf16 v[16:19], v[208:211], v[192:195], v[16:19]
	v_mfma_f32_16x16x32_bf16 v[8:11], v[216:219], v[192:195], v[8:11]
	v_mfma_f32_16x16x32_bf16 v[4:7], v[208:211], v[200:203], v[4:7]
	v_mfma_f32_16x16x32_bf16 v[0:3], v[216:219], v[200:203], v[0:3]
	s_setprio 0
	s_add_i32 s45, s45, 2
	s_add_u32 s43, s43, 0x100
	s_addc_u32 s44, s44, 0
	s_cmp_gt_u32 s45, 13
	s_mov_b64 s[18:19], s[4:5]
	s_barrier
	s_cbranch_scc0 .LBB0_1051
	v_lshl_add_u32 v152, s41, 8, v147
	s_lshl_b32 s4, s40, 8
	v_ashrrev_i32_e32 v153, 31, v152
	s_ashr_i32 s5, s4, 31
	v_lshlrev_b64 v[154:155], 11, v[152:153]
	v_lshl_add_u64 v[154:155], s[6:7], 0, v[154:155]
	s_lshl_b64 s[4:5], s[4:5], 1
	v_lshl_add_u64 v[154:155], v[154:155], 0, s[4:5]
	v_lshl_add_u64 v[154:155], v[154:155], 0, s[8:9]
	v_lshl_add_u64 v[154:155], v[154:155], 0, v[136:137]
	v_mbcnt_lo_u32_b32 v237, -1, 0
	v_mbcnt_hi_u32_b32 v237, -1, v237
	v_bfe_i32 v237, v237, 4, 1
	v_and_b32_e32 v244, 24, v237
	v_add_co_u32_e32 v248, vcc, v244, v154
	s_nop 1
	v_addc_co_u32_e32 v249, vcc, 0, v155, vcc
	v_cvt_pk_bf16_f32 v124, v124, v125
	v_cvt_pk_bf16_f32 v125, v126, v127
	v_cvt_pk_bf16_f32 v120, v120, v121
	v_cvt_pk_bf16_f32 v121, v122, v123
	v_bfi_b32 v244, v237, v124, v120
	v_bfi_b32 v245, v237, v125, v121
	ds_swizzle_b32 v250, v244 offset:0x401f
	ds_swizzle_b32 v251, v245 offset:0x401f
	v_cvt_pk_bf16_f32 v112, v112, v113
	v_cvt_pk_bf16_f32 v113, v114, v115
	v_cvt_pk_bf16_f32 v104, v104, v105
	v_cvt_pk_bf16_f32 v105, v106, v107
	v_bfi_b32 v246, v237, v112, v104
	v_bfi_b32 v247, v237, v113, v105
	ds_swizzle_b32 v252, v246 offset:0x401f
	ds_swizzle_b32 v253, v247 offset:0x401f
	s_waitcnt lgkmcnt(0)
	v_bfi_b32 v240, v237, v250, v124
	v_bfi_b32 v241, v237, v251, v125
	v_bfi_b32 v242, v237, v120, v250
	v_bfi_b32 v243, v237, v121, v251
	global_store_dwordx4 v[248:249], v[240:243], off sc1
	s_nop 1
	v_bfi_b32 v240, v237, v252, v112
	v_bfi_b32 v241, v237, v253, v113
	v_bfi_b32 v242, v237, v104, v252
	v_bfi_b32 v243, v237, v105, v253
	global_store_dwordx4 v[248:249], v[240:243], off offset:256 sc1
	s_nop 1
	v_add_co_u32_e32 v238, vcc, 0x8000, v248
	s_nop 1
	v_addc_co_u32_e32 v239, vcc, 0, v249, vcc
	v_cvt_pk_bf16_f32 v116, v116, v117
	v_cvt_pk_bf16_f32 v117, v118, v119
	v_cvt_pk_bf16_f32 v108, v108, v109
	v_cvt_pk_bf16_f32 v109, v110, v111
	v_bfi_b32 v244, v237, v116, v108
	v_bfi_b32 v245, v237, v117, v109
	ds_swizzle_b32 v250, v244 offset:0x401f
	ds_swizzle_b32 v251, v245 offset:0x401f
	v_cvt_pk_bf16_f32 v96, v96, v97
	v_cvt_pk_bf16_f32 v97, v98, v99
	v_cvt_pk_bf16_f32 v88, v88, v89
	v_cvt_pk_bf16_f32 v89, v90, v91
	v_bfi_b32 v246, v237, v96, v88
	v_bfi_b32 v247, v237, v97, v89
	ds_swizzle_b32 v252, v246 offset:0x401f
	ds_swizzle_b32 v253, v247 offset:0x401f
	s_waitcnt lgkmcnt(0)
	v_bfi_b32 v240, v237, v250, v116
	v_bfi_b32 v241, v237, v251, v117
	v_bfi_b32 v242, v237, v108, v250
	v_bfi_b32 v243, v237, v109, v251
	global_store_dwordx4 v[238:239], v[240:243], off sc1
	s_nop 1
	v_bfi_b32 v240, v237, v252, v96
	v_bfi_b32 v241, v237, v253, v97
	v_bfi_b32 v242, v237, v88, v252
	v_bfi_b32 v243, v237, v89, v253
	global_store_dwordx4 v[238:239], v[240:243], off offset:256 sc1
	s_nop 1
	v_add_co_u32_e32 v238, vcc, 0x10000, v248
	s_nop 1
	v_addc_co_u32_e32 v239, vcc, 0, v249, vcc
	v_cvt_pk_bf16_f32 v100, v100, v101
	v_cvt_pk_bf16_f32 v101, v102, v103
	v_cvt_pk_bf16_f32 v92, v92, v93
	v_cvt_pk_bf16_f32 v93, v94, v95
	v_bfi_b32 v244, v237, v100, v92
	v_bfi_b32 v245, v237, v101, v93
	ds_swizzle_b32 v250, v244 offset:0x401f
	ds_swizzle_b32 v251, v245 offset:0x401f
	v_cvt_pk_bf16_f32 v80, v80, v81
	v_cvt_pk_bf16_f32 v81, v82, v83
	v_cvt_pk_bf16_f32 v72, v72, v73
	v_cvt_pk_bf16_f32 v73, v74, v75
	v_bfi_b32 v246, v237, v80, v72
	v_bfi_b32 v247, v237, v81, v73
	ds_swizzle_b32 v252, v246 offset:0x401f
	ds_swizzle_b32 v253, v247 offset:0x401f
	s_waitcnt lgkmcnt(0)
	v_bfi_b32 v240, v237, v250, v100
	v_bfi_b32 v241, v237, v251, v101
	v_bfi_b32 v242, v237, v92, v250
	v_bfi_b32 v243, v237, v93, v251
	global_store_dwordx4 v[238:239], v[240:243], off sc1
	s_nop 1
	v_bfi_b32 v240, v237, v252, v80
	v_bfi_b32 v241, v237, v253, v81
	v_bfi_b32 v242, v237, v72, v252
	v_bfi_b32 v243, v237, v73, v253
	global_store_dwordx4 v[238:239], v[240:243], off offset:256 sc1
	s_nop 1
	v_add_co_u32_e32 v238, vcc, 0x18000, v248
	s_nop 1
	v_addc_co_u32_e32 v239, vcc, 0, v249, vcc
	v_cvt_pk_bf16_f32 v84, v84, v85
	v_cvt_pk_bf16_f32 v85, v86, v87
	v_cvt_pk_bf16_f32 v76, v76, v77
	v_cvt_pk_bf16_f32 v77, v78, v79
	v_bfi_b32 v244, v237, v84, v76
	v_bfi_b32 v245, v237, v85, v77
	ds_swizzle_b32 v250, v244 offset:0x401f
	ds_swizzle_b32 v251, v245 offset:0x401f
	v_cvt_pk_bf16_f32 v68, v68, v69
	v_cvt_pk_bf16_f32 v69, v70, v71
	v_cvt_pk_bf16_f32 v64, v64, v65
	v_cvt_pk_bf16_f32 v65, v66, v67
	v_bfi_b32 v246, v237, v68, v64
	v_bfi_b32 v247, v237, v69, v65
	ds_swizzle_b32 v252, v246 offset:0x401f
	ds_swizzle_b32 v253, v247 offset:0x401f
	s_waitcnt lgkmcnt(0)
	v_bfi_b32 v240, v237, v250, v84
	v_bfi_b32 v241, v237, v251, v85
	v_bfi_b32 v242, v237, v76, v250
	v_bfi_b32 v243, v237, v77, v251
	global_store_dwordx4 v[238:239], v[240:243], off sc1
	s_nop 1
	v_bfi_b32 v240, v237, v252, v68
	v_bfi_b32 v241, v237, v253, v69
	v_bfi_b32 v242, v237, v64, v252
	v_bfi_b32 v243, v237, v65, v253
	global_store_dwordx4 v[238:239], v[240:243], off offset:256 sc1
	s_nop 1
	v_add_co_u32_e32 v238, vcc, 0x40000, v248
	s_nop 1
	v_addc_co_u32_e32 v239, vcc, 0, v249, vcc
	v_cvt_pk_bf16_f32 v60, v60, v61
	v_cvt_pk_bf16_f32 v61, v62, v63
	v_cvt_pk_bf16_f32 v56, v56, v57
	v_cvt_pk_bf16_f32 v57, v58, v59
	v_bfi_b32 v244, v237, v60, v56
	v_bfi_b32 v245, v237, v61, v57
	ds_swizzle_b32 v250, v244 offset:0x401f
	ds_swizzle_b32 v251, v245 offset:0x401f
	v_cvt_pk_bf16_f32 v48, v48, v49
	v_cvt_pk_bf16_f32 v49, v50, v51
	v_cvt_pk_bf16_f32 v40, v40, v41
	v_cvt_pk_bf16_f32 v41, v42, v43
	v_bfi_b32 v246, v237, v48, v40
	v_bfi_b32 v247, v237, v49, v41
	ds_swizzle_b32 v252, v246 offset:0x401f
	ds_swizzle_b32 v253, v247 offset:0x401f
	s_waitcnt lgkmcnt(0)
	v_bfi_b32 v240, v237, v250, v60
	v_bfi_b32 v241, v237, v251, v61
	v_bfi_b32 v242, v237, v56, v250
	v_bfi_b32 v243, v237, v57, v251
	global_store_dwordx4 v[238:239], v[240:243], off sc1
	s_nop 1
	v_bfi_b32 v240, v237, v252, v48
	v_bfi_b32 v241, v237, v253, v49
	v_bfi_b32 v242, v237, v40, v252
	v_bfi_b32 v243, v237, v41, v253
	global_store_dwordx4 v[238:239], v[240:243], off offset:256 sc1
	s_nop 1
	v_add_co_u32_e32 v238, vcc, 0x48000, v248
	s_nop 1
	v_addc_co_u32_e32 v239, vcc, 0, v249, vcc
	v_cvt_pk_bf16_f32 v52, v52, v53
	v_cvt_pk_bf16_f32 v53, v54, v55
	v_cvt_pk_bf16_f32 v44, v44, v45
	v_cvt_pk_bf16_f32 v45, v46, v47
	v_bfi_b32 v244, v237, v52, v44
	v_bfi_b32 v245, v237, v53, v45
	ds_swizzle_b32 v250, v244 offset:0x401f
	ds_swizzle_b32 v251, v245 offset:0x401f
	v_cvt_pk_bf16_f32 v32, v32, v33
	v_cvt_pk_bf16_f32 v33, v34, v35
	v_cvt_pk_bf16_f32 v24, v24, v25
	v_cvt_pk_bf16_f32 v25, v26, v27
	v_bfi_b32 v246, v237, v32, v24
	v_bfi_b32 v247, v237, v33, v25
	ds_swizzle_b32 v252, v246 offset:0x401f
	ds_swizzle_b32 v253, v247 offset:0x401f
	s_waitcnt lgkmcnt(0)
	v_bfi_b32 v240, v237, v250, v52
	v_bfi_b32 v241, v237, v251, v53
	v_bfi_b32 v242, v237, v44, v250
	v_bfi_b32 v243, v237, v45, v251
	global_store_dwordx4 v[238:239], v[240:243], off sc1
	s_nop 1
	v_bfi_b32 v240, v237, v252, v32
	v_bfi_b32 v241, v237, v253, v33
	v_bfi_b32 v242, v237, v24, v252
	v_bfi_b32 v243, v237, v25, v253
	global_store_dwordx4 v[238:239], v[240:243], off offset:256 sc1
	s_nop 1
	v_add_co_u32_e32 v238, vcc, 0x50000, v248
	s_nop 1
	v_addc_co_u32_e32 v239, vcc, 0, v249, vcc
	v_cvt_pk_bf16_f32 v36, v36, v37
	v_cvt_pk_bf16_f32 v37, v38, v39
	v_cvt_pk_bf16_f32 v28, v28, v29
	v_cvt_pk_bf16_f32 v29, v30, v31
	v_bfi_b32 v244, v237, v36, v28
	v_bfi_b32 v245, v237, v37, v29
	ds_swizzle_b32 v250, v244 offset:0x401f
	ds_swizzle_b32 v251, v245 offset:0x401f
	v_cvt_pk_bf16_f32 v16, v16, v17
	v_cvt_pk_bf16_f32 v17, v18, v19
	v_cvt_pk_bf16_f32 v8, v8, v9
	v_cvt_pk_bf16_f32 v9, v10, v11
	v_bfi_b32 v246, v237, v16, v8
	v_bfi_b32 v247, v237, v17, v9
	ds_swizzle_b32 v252, v246 offset:0x401f
	ds_swizzle_b32 v253, v247 offset:0x401f
	s_waitcnt lgkmcnt(0)
	v_bfi_b32 v240, v237, v250, v36
	v_bfi_b32 v241, v237, v251, v37
	v_bfi_b32 v242, v237, v28, v250
	v_bfi_b32 v243, v237, v29, v251
	global_store_dwordx4 v[238:239], v[240:243], off sc1
	s_nop 1
	v_bfi_b32 v240, v237, v252, v16
	v_bfi_b32 v241, v237, v253, v17
	v_bfi_b32 v242, v237, v8, v252
	v_bfi_b32 v243, v237, v9, v253
	global_store_dwordx4 v[238:239], v[240:243], off offset:256 sc1
	s_nop 1
	v_add_co_u32_e32 v238, vcc, 0x58000, v248
	s_nop 1
	v_addc_co_u32_e32 v239, vcc, 0, v249, vcc
	v_cvt_pk_bf16_f32 v20, v20, v21
	v_cvt_pk_bf16_f32 v21, v22, v23
	v_cvt_pk_bf16_f32 v12, v12, v13
	v_cvt_pk_bf16_f32 v13, v14, v15
	v_bfi_b32 v244, v237, v20, v12
	v_bfi_b32 v245, v237, v21, v13
	ds_swizzle_b32 v250, v244 offset:0x401f
	ds_swizzle_b32 v251, v245 offset:0x401f
	v_cvt_pk_bf16_f32 v4, v4, v5
	v_cvt_pk_bf16_f32 v5, v6, v7
	v_cvt_pk_bf16_f32 v0, v0, v1
	v_cvt_pk_bf16_f32 v1, v2, v3
	v_bfi_b32 v246, v237, v4, v0
	v_bfi_b32 v247, v237, v5, v1
	ds_swizzle_b32 v252, v246 offset:0x401f
	ds_swizzle_b32 v253, v247 offset:0x401f
	s_waitcnt lgkmcnt(0)
	v_bfi_b32 v240, v237, v250, v20
	v_bfi_b32 v241, v237, v251, v21
	v_bfi_b32 v242, v237, v12, v250
	v_bfi_b32 v243, v237, v13, v251
	global_store_dwordx4 v[238:239], v[240:243], off sc1
	s_nop 1
	v_bfi_b32 v240, v237, v252, v4
	v_bfi_b32 v241, v237, v253, v5
	v_bfi_b32 v242, v237, v0, v252
	v_bfi_b32 v243, v237, v1, v253
	global_store_dwordx4 v[238:239], v[240:243], off offset:256 sc1
	s_nop 1
	s_and_b64 vcc, exec, s[0:1]
	s_mov_b32 s40, s12
	s_mov_b32 s41, s39
	s_mov_b64 s[20:21], s[16:17]
	s_mov_b64 s[18:19], s[14:15]
	s_cbranch_vccz .LBB0_1046
	s_waitcnt vmcnt(0)
	s_cmpk_gt_u32 s3, 0xff
	s_cbranch_scc1 .LBB0_1055
	s_barrier

.Lupf_u0_entry:
	v_mbcnt_lo_u32_b32 v253, -1, 0
	v_mbcnt_hi_u32_b32 v253, -1, v253
	v_and_b32_e32 v254, 15, v253
	v_lshrrev_b32_e32 v255, 4, v253
	s_lshr_b32 s100, s3, 6
	s_lshr_b32 s101, s100, 2
	s_and_b32 s100, s100, 3
	s_lshl_b32 vcc_lo, s101, 6
	v_add_u32_e32 v251, vcc_lo, v254
	s_add_i32 vcc_hi, s98, -1
	v_add_u32_e32 v250, vcc_hi, v251
	v_mul_u32_u24_e32 v250, 0x1600, v250
	s_lshl_b32 vcc_lo, s28, 7
	s_lshl_b32 vcc_hi, s100, 5
	s_add_i32 vcc_lo, vcc_lo, vcc_hi
	v_lshl_add_u32 v253, v255, 2, vcc_lo
	v_and_b32_e32 v252, 1, v255
	v_lshlrev_b32_e32 v252, 1, v252
	v_lshrrev_b32_e32 v245, 1, v255
	v_or_b32_e32 v252, v252, v245
	v_lshl_add_u32 v252, v252, 3, vcc_lo
	v_lshl_add_u32 v250, v252, 1, v250
	v_lshlrev_b32_e32 v146, 2, v253
	v_add_u32_e32 v147, 0x5800, v146
	v_add_u32_e32 v168, 0xb000, v146
	v_add_u32_e32 v169, 0x2c00, v146
	v_add_u32_e32 v245, 0x8400, v146
	v_add_u32_e32 v252, 0xdc00, v146
	global_load_dwordx4 v[172:175], v146, s[62:63] offset:0
	global_load_dwordx4 v[176:179], v147, s[62:63] offset:0
	global_load_dwordx4 v[180:183], v168, s[62:63] offset:0
	global_load_dwordx4 v[188:191], v169, s[62:63] offset:0
	global_load_dwordx4 v[192:195], v245, s[62:63] offset:0
	global_load_dwordx4 v[196:199], v252, s[62:63] offset:0
	global_load_dwordx4 v[184:187], v146, s[64:65] offset:0
	global_load_dwordx4 v[200:203], v169, s[64:65] offset:0
	s_lshl_b32 s101, s101, 11
	s_lshl_b32 s100, s100, 7
	s_add_i32 s101, s101, s100
	s_add_i32 s101, s101, 0x20000
	v_lshl_add_u32 v249, v255, 4, s101
	v_add_u32_e32 v253, 0x400, v249
	v_cmp_eq_u32_e64 s[98:99], 0, v254
	v_cmp_eq_u32_e32 vcc, 15, v254
	s_nop 4
	s_mov_b64 exec, s[98:99]
	ds_write_b128 v253, v[124:127] offset:0
	ds_write_b128 v253, v[108:111] offset:64
	ds_write_b128 v253, v[112:115] offset:512
	ds_write_b128 v253, v[84:87] offset:576
	ds_write_b128 v253, v[72:75] offset:4096
	ds_write_b128 v253, v[44:47] offset:4160
	ds_write_b128 v253, v[48:51] offset:4608
	ds_write_b128 v253, v[20:23] offset:4672
	s_mov_b64 exec, vcc
	ds_write_b128 v253, v[104:107] offset:1024
	ds_write_b128 v253, v[76:79] offset:1088
	ds_write_b128 v253, v[80:83] offset:1536
	ds_write_b128 v253, v[52:55] offset:1600
	ds_write_b128 v253, v[40:43] offset:5120
	ds_write_b128 v253, v[12:15] offset:5184
	ds_write_b128 v253, v[16:19] offset:5632
	ds_write_b128 v253, v[0:3] offset:5696
	s_mov_b64 exec, -1
	s_waitcnt lgkmcnt(0)
	s_barrier
	ds_read_b128 v[204:207], v249 offset:0
	ds_read_b128 v[208:211], v249 offset:512
	ds_read_b128 v[160:163], v249 offset:3072
	ds_read_b128 v[164:167], v249 offset:3584
	s_waitcnt vmcnt(0) lgkmcnt(0)
	v_cndmask_b32_e32 v148, v124, v204, vcc
	v_cndmask_b32_e32 v149, v125, v205, vcc
	v_cndmask_b32_e32 v150, v126, v206, vcc
	v_cndmask_b32_e32 v151, v127, v207, vcc
	v_cndmask_b32_e64 v152, v124, v120, s[98:99]
	v_cndmask_b32_e64 v153, v125, v121, s[98:99]
	v_cndmask_b32_e64 v154, v126, v122, s[98:99]
	v_cndmask_b32_e64 v155, v127, v123, s[98:99]
	v_fma_f32 v156, v176, v124, v184
	v_fma_f32 v157, v177, v125, v185
	v_fma_f32 v158, v178, v126, v186
	v_fma_f32 v159, v179, v127, v187
	v_fmac_f32_dpp v156, v148, v172 row_ror:1 row_mask:0xf bank_mask:0xf
	v_fmac_f32_dpp v157, v149, v173 row_ror:1 row_mask:0xf bank_mask:0xf
	v_fmac_f32_dpp v158, v150, v174 row_ror:1 row_mask:0xf bank_mask:0xf
	v_fmac_f32_dpp v159, v151, v175 row_ror:1 row_mask:0xf bank_mask:0xf
	v_fmac_f32_dpp v156, v152, v180 row_ror:15 row_mask:0xf bank_mask:0xf
	v_fmac_f32_dpp v157, v153, v181 row_ror:15 row_mask:0xf bank_mask:0xf
	v_fmac_f32_dpp v158, v154, v182 row_ror:15 row_mask:0xf bank_mask:0xf
	v_fmac_f32_dpp v159, v155, v183 row_ror:15 row_mask:0xf bank_mask:0xf
	v_cndmask_b32_e32 v148, v112, v208, vcc
	v_cndmask_b32_e32 v149, v113, v209, vcc
	v_cndmask_b32_e32 v150, v114, v210, vcc
	v_cndmask_b32_e32 v151, v115, v211, vcc
	v_cndmask_b32_e64 v152, v112, v100, s[98:99]
	v_cndmask_b32_e64 v153, v113, v101, s[98:99]
	v_cndmask_b32_e64 v154, v114, v102, s[98:99]
	v_cndmask_b32_e64 v155, v115, v103, s[98:99]
	v_fma_f32 v237, v192, v112, v200
	v_fma_f32 v238, v193, v113, v201
	v_fma_f32 v239, v194, v114, v202
	v_fma_f32 v240, v195, v115, v203
	v_fmac_f32_dpp v237, v148, v188 row_ror:1 row_mask:0xf bank_mask:0xf
	v_fmac_f32_dpp v238, v149, v189 row_ror:1 row_mask:0xf bank_mask:0xf
	v_fmac_f32_dpp v239, v150, v190 row_ror:1 row_mask:0xf bank_mask:0xf
	v_fmac_f32_dpp v240, v151, v191 row_ror:1 row_mask:0xf bank_mask:0xf
	v_fmac_f32_dpp v237, v152, v196 row_ror:15 row_mask:0xf bank_mask:0xf
	v_fmac_f32_dpp v238, v153, v197 row_ror:15 row_mask:0xf bank_mask:0xf
	v_fmac_f32_dpp v239, v154, v198 row_ror:15 row_mask:0xf bank_mask:0xf
	v_fmac_f32_dpp v240, v155, v199 row_ror:15 row_mask:0xf bank_mask:0xf
	v_mul_f32_e32 v148, 0xbfb8aa3b, v156
	v_mul_f32_e32 v149, 0xbfb8aa3b, v157
	v_mul_f32_e32 v150, 0xbfb8aa3b, v158
	v_mul_f32_e32 v151, 0xbfb8aa3b, v159
	v_exp_f32_e32 v148, v148
	v_exp_f32_e32 v149, v149
	v_exp_f32_e32 v150, v150
	v_exp_f32_e32 v151, v151
	v_add_f32_e32 v148, 1.0, v148
	v_add_f32_e32 v149, 1.0, v149
	v_add_f32_e32 v150, 1.0, v150
	v_add_f32_e32 v151, 1.0, v151
	v_rcp_f32_e32 v148, v148
	v_rcp_f32_e32 v149, v149
	v_rcp_f32_e32 v150, v150
	v_rcp_f32_e32 v151, v151
	v_mul_f32_e32 v156, v156, v148
	v_mul_f32_e32 v157, v157, v149
	v_mul_f32_e32 v158, v158, v150
	v_mul_f32_e32 v159, v159, v151
	v_mul_f32_e32 v156, v156, v237
	v_mul_f32_e32 v157, v157, v238
	v_mul_f32_e32 v158, v158, v239
	v_mul_f32_e32 v159, v159, v240
	v_cvt_pk_bf16_f32 v241, v156, v157
	v_cvt_pk_bf16_f32 v242, v158, v159
	ds_read_b128 v[204:207], v249 offset:4096
	ds_read_b128 v[208:211], v249 offset:4608
	v_cndmask_b32_e32 v148, v120, v124, vcc
	v_cndmask_b32_e32 v149, v121, v125, vcc
	v_cndmask_b32_e32 v150, v122, v126, vcc
	v_cndmask_b32_e32 v151, v123, v127, vcc
	v_cndmask_b32_e64 v152, v120, v116, s[98:99]
	v_cndmask_b32_e64 v153, v121, v117, s[98:99]
	v_cndmask_b32_e64 v154, v122, v118, s[98:99]
	v_cndmask_b32_e64 v155, v123, v119, s[98:99]
	v_fma_f32 v156, v176, v120, v184
	v_fma_f32 v157, v177, v121, v185
	v_fma_f32 v158, v178, v122, v186
	v_fma_f32 v159, v179, v123, v187
	v_fmac_f32_dpp v156, v148, v172 row_ror:1 row_mask:0xf bank_mask:0xf
	v_fmac_f32_dpp v157, v149, v173 row_ror:1 row_mask:0xf bank_mask:0xf
	v_fmac_f32_dpp v158, v150, v174 row_ror:1 row_mask:0xf bank_mask:0xf
	v_fmac_f32_dpp v159, v151, v175 row_ror:1 row_mask:0xf bank_mask:0xf
	v_fmac_f32_dpp v156, v152, v180 row_ror:15 row_mask:0xf bank_mask:0xf
	v_fmac_f32_dpp v157, v153, v181 row_ror:15 row_mask:0xf bank_mask:0xf
	v_fmac_f32_dpp v158, v154, v182 row_ror:15 row_mask:0xf bank_mask:0xf
	v_fmac_f32_dpp v159, v155, v183 row_ror:15 row_mask:0xf bank_mask:0xf
	v_cndmask_b32_e32 v148, v100, v112, vcc
	v_cndmask_b32_e32 v149, v101, v113, vcc
	v_cndmask_b32_e32 v150, v102, v114, vcc
	v_cndmask_b32_e32 v151, v103, v115, vcc
	v_cndmask_b32_e64 v152, v100, v92, s[98:99]
	v_cndmask_b32_e64 v153, v101, v93, s[98:99]
	v_cndmask_b32_e64 v154, v102, v94, s[98:99]
	v_cndmask_b32_e64 v155, v103, v95, s[98:99]
	v_fma_f32 v237, v192, v100, v200
	v_fma_f32 v238, v193, v101, v201
	v_fma_f32 v239, v194, v102, v202
	v_fma_f32 v240, v195, v103, v203
	v_fmac_f32_dpp v237, v148, v188 row_ror:1 row_mask:0xf bank_mask:0xf
	v_fmac_f32_dpp v238, v149, v189 row_ror:1 row_mask:0xf bank_mask:0xf
	v_fmac_f32_dpp v239, v150, v190 row_ror:1 row_mask:0xf bank_mask:0xf
	v_fmac_f32_dpp v240, v151, v191 row_ror:1 row_mask:0xf bank_mask:0xf
	v_fmac_f32_dpp v237, v152, v196 row_ror:15 row_mask:0xf bank_mask:0xf
	v_fmac_f32_dpp v238, v153, v197 row_ror:15 row_mask:0xf bank_mask:0xf
	v_fmac_f32_dpp v239, v154, v198 row_ror:15 row_mask:0xf bank_mask:0xf
	v_fmac_f32_dpp v240, v155, v199 row_ror:15 row_mask:0xf bank_mask:0xf
	v_mul_f32_e32 v148, 0xbfb8aa3b, v156
	v_mul_f32_e32 v149, 0xbfb8aa3b, v157
	v_mul_f32_e32 v150, 0xbfb8aa3b, v158
	v_mul_f32_e32 v151, 0xbfb8aa3b, v159
	v_exp_f32_e32 v148, v148
	v_exp_f32_e32 v149, v149
	v_exp_f32_e32 v150, v150
	v_exp_f32_e32 v151, v151
	v_add_f32_e32 v148, 1.0, v148
	v_add_f32_e32 v149, 1.0, v149
	v_add_f32_e32 v150, 1.0, v150
	v_add_f32_e32 v151, 1.0, v151
	v_rcp_f32_e32 v148, v148
	v_rcp_f32_e32 v149, v149
	v_rcp_f32_e32 v150, v150
	v_rcp_f32_e32 v151, v151
	v_mul_f32_e32 v156, v156, v148
	v_mul_f32_e32 v157, v157, v149
	v_mul_f32_e32 v158, v158, v150
	v_mul_f32_e32 v159, v159, v151
	v_mul_f32_e32 v156, v156, v237
	v_mul_f32_e32 v157, v157, v238
	v_mul_f32_e32 v158, v158, v239
	v_mul_f32_e32 v159, v159, v240
	v_cvt_pk_bf16_f32 v243, v156, v157
	v_cvt_pk_bf16_f32 v244, v158, v159
	v_cndmask_b32_e32 v148, v116, v120, vcc
	v_cndmask_b32_e32 v149, v117, v121, vcc
	v_cndmask_b32_e32 v150, v118, v122, vcc
	v_cndmask_b32_e32 v151, v119, v123, vcc
	v_cndmask_b32_e64 v152, v116, v104, s[98:99]
	v_cndmask_b32_e64 v153, v117, v105, s[98:99]
	v_cndmask_b32_e64 v154, v118, v106, s[98:99]
	v_cndmask_b32_e64 v155, v119, v107, s[98:99]
	v_fma_f32 v156, v176, v116, v184
	v_fma_f32 v157, v177, v117, v185
	v_fma_f32 v158, v178, v118, v186
	v_fma_f32 v159, v179, v119, v187
	v_fmac_f32_dpp v156, v148, v172 row_ror:1 row_mask:0xf bank_mask:0xf
	v_fmac_f32_dpp v157, v149, v173 row_ror:1 row_mask:0xf bank_mask:0xf
	v_fmac_f32_dpp v158, v150, v174 row_ror:1 row_mask:0xf bank_mask:0xf
	v_fmac_f32_dpp v159, v151, v175 row_ror:1 row_mask:0xf bank_mask:0xf
	v_fmac_f32_dpp v156, v152, v180 row_ror:15 row_mask:0xf bank_mask:0xf
	v_fmac_f32_dpp v157, v153, v181 row_ror:15 row_mask:0xf bank_mask:0xf
	v_fmac_f32_dpp v158, v154, v182 row_ror:15 row_mask:0xf bank_mask:0xf
	v_fmac_f32_dpp v159, v155, v183 row_ror:15 row_mask:0xf bank_mask:0xf
	v_cndmask_b32_e32 v148, v92, v100, vcc
	v_cndmask_b32_e32 v149, v93, v101, vcc
	v_cndmask_b32_e32 v150, v94, v102, vcc
	v_cndmask_b32_e32 v151, v95, v103, vcc
	v_cndmask_b32_e64 v152, v92, v80, s[98:99]
	v_cndmask_b32_e64 v153, v93, v81, s[98:99]
	v_cndmask_b32_e64 v154, v94, v82, s[98:99]
	v_cndmask_b32_e64 v155, v95, v83, s[98:99]
	v_fma_f32 v237, v192, v92, v200
	v_fma_f32 v238, v193, v93, v201
	v_fma_f32 v239, v194, v94, v202
	v_fma_f32 v240, v195, v95, v203
	v_fmac_f32_dpp v237, v148, v188 row_ror:1 row_mask:0xf bank_mask:0xf
	v_fmac_f32_dpp v238, v149, v189 row_ror:1 row_mask:0xf bank_mask:0xf
	v_fmac_f32_dpp v239, v150, v190 row_ror:1 row_mask:0xf bank_mask:0xf
	v_fmac_f32_dpp v240, v151, v191 row_ror:1 row_mask:0xf bank_mask:0xf
	v_fmac_f32_dpp v237, v152, v196 row_ror:15 row_mask:0xf bank_mask:0xf
	v_fmac_f32_dpp v238, v153, v197 row_ror:15 row_mask:0xf bank_mask:0xf
	v_fmac_f32_dpp v239, v154, v198 row_ror:15 row_mask:0xf bank_mask:0xf
	v_fmac_f32_dpp v240, v155, v199 row_ror:15 row_mask:0xf bank_mask:0xf
	v_mul_f32_e32 v148, 0xbfb8aa3b, v156
	v_mul_f32_e32 v149, 0xbfb8aa3b, v157
	v_mul_f32_e32 v150, 0xbfb8aa3b, v158
	v_mul_f32_e32 v151, 0xbfb8aa3b, v159
	v_exp_f32_e32 v148, v148
	v_exp_f32_e32 v149, v149
	v_exp_f32_e32 v150, v150
	v_exp_f32_e32 v151, v151
	v_add_f32_e32 v148, 1.0, v148
	v_add_f32_e32 v149, 1.0, v149
	v_add_f32_e32 v150, 1.0, v150
	v_add_f32_e32 v151, 1.0, v151
	v_rcp_f32_e32 v148, v148
	v_rcp_f32_e32 v149, v149
	v_rcp_f32_e32 v150, v150
	v_rcp_f32_e32 v151, v151
	v_mul_f32_e32 v156, v156, v148
	v_mul_f32_e32 v157, v157, v149
	v_mul_f32_e32 v158, v158, v150
	v_mul_f32_e32 v159, v159, v151
	v_mul_f32_e32 v156, v156, v237
	v_mul_f32_e32 v157, v157, v238
	v_mul_f32_e32 v158, v158, v239
	v_mul_f32_e32 v159, v159, v240
	v_cvt_pk_bf16_f32 v253, v156, v157
	v_cvt_pk_bf16_f32 v254, v158, v159
	v_cndmask_b32_e32 v148, v104, v116, vcc
	v_cndmask_b32_e32 v149, v105, v117, vcc
	v_cndmask_b32_e32 v150, v106, v118, vcc
	v_cndmask_b32_e32 v151, v107, v119, vcc
	v_cndmask_b32_e64 v152, v104, v160, s[98:99]
	v_cndmask_b32_e64 v153, v105, v161, s[98:99]
	v_cndmask_b32_e64 v154, v106, v162, s[98:99]
	v_cndmask_b32_e64 v155, v107, v163, s[98:99]
	v_fma_f32 v156, v176, v104, v184
	v_fma_f32 v157, v177, v105, v185
	v_fma_f32 v158, v178, v106, v186
	v_fma_f32 v159, v179, v107, v187
	v_fmac_f32_dpp v156, v148, v172 row_ror:1 row_mask:0xf bank_mask:0xf
	v_fmac_f32_dpp v157, v149, v173 row_ror:1 row_mask:0xf bank_mask:0xf
	v_fmac_f32_dpp v158, v150, v174 row_ror:1 row_mask:0xf bank_mask:0xf
	v_fmac_f32_dpp v159, v151, v175 row_ror:1 row_mask:0xf bank_mask:0xf
	v_fmac_f32_dpp v156, v152, v180 row_ror:15 row_mask:0xf bank_mask:0xf
	v_fmac_f32_dpp v157, v153, v181 row_ror:15 row_mask:0xf bank_mask:0xf
	v_fmac_f32_dpp v158, v154, v182 row_ror:15 row_mask:0xf bank_mask:0xf
	v_fmac_f32_dpp v159, v155, v183 row_ror:15 row_mask:0xf bank_mask:0xf
	v_cndmask_b32_e32 v148, v80, v92, vcc
	v_cndmask_b32_e32 v149, v81, v93, vcc
	v_cndmask_b32_e32 v150, v82, v94, vcc
	v_cndmask_b32_e32 v151, v83, v95, vcc
	v_cndmask_b32_e64 v152, v80, v164, s[98:99]
	v_cndmask_b32_e64 v153, v81, v165, s[98:99]
	v_cndmask_b32_e64 v154, v82, v166, s[98:99]
	v_cndmask_b32_e64 v155, v83, v167, s[98:99]
	v_fma_f32 v237, v192, v80, v200
	v_fma_f32 v238, v193, v81, v201
	v_fma_f32 v239, v194, v82, v202
	v_fma_f32 v240, v195, v83, v203
	v_fmac_f32_dpp v237, v148, v188 row_ror:1 row_mask:0xf bank_mask:0xf
	v_fmac_f32_dpp v238, v149, v189 row_ror:1 row_mask:0xf bank_mask:0xf
	v_fmac_f32_dpp v239, v150, v190 row_ror:1 row_mask:0xf bank_mask:0xf
	v_fmac_f32_dpp v240, v151, v191 row_ror:1 row_mask:0xf bank_mask:0xf
	v_fmac_f32_dpp v237, v152, v196 row_ror:15 row_mask:0xf bank_mask:0xf
	v_fmac_f32_dpp v238, v153, v197 row_ror:15 row_mask:0xf bank_mask:0xf
	v_fmac_f32_dpp v239, v154, v198 row_ror:15 row_mask:0xf bank_mask:0xf
	v_fmac_f32_dpp v240, v155, v199 row_ror:15 row_mask:0xf bank_mask:0xf
	v_mul_f32_e32 v148, 0xbfb8aa3b, v156
	v_mul_f32_e32 v149, 0xbfb8aa3b, v157
	v_mul_f32_e32 v150, 0xbfb8aa3b, v158
	v_mul_f32_e32 v151, 0xbfb8aa3b, v159
	v_exp_f32_e32 v148, v148
	v_exp_f32_e32 v149, v149
	v_exp_f32_e32 v150, v150
	v_exp_f32_e32 v151, v151
	v_add_f32_e32 v148, 1.0, v148
	v_add_f32_e32 v149, 1.0, v149
	v_add_f32_e32 v150, 1.0, v150
	v_add_f32_e32 v151, 1.0, v151
	v_rcp_f32_e32 v148, v148
	v_rcp_f32_e32 v149, v149
	v_rcp_f32_e32 v150, v150
	v_rcp_f32_e32 v151, v151
	v_mul_f32_e32 v156, v156, v148
	v_mul_f32_e32 v157, v157, v149
	v_mul_f32_e32 v158, v158, v150
	v_mul_f32_e32 v159, v159, v151
	v_mul_f32_e32 v156, v156, v237
	v_mul_f32_e32 v157, v157, v238
	v_mul_f32_e32 v158, v158, v239
	v_mul_f32_e32 v159, v159, v240
	v_cvt_pk_bf16_f32 v255, v156, v157
	v_cvt_pk_bf16_f32 v246, v158, v159
	global_load_dwordx4 v[124:127], v146, s[62:63] offset:64
	global_load_dwordx4 v[120:123], v147, s[62:63] offset:64
	global_load_dwordx4 v[116:119], v168, s[62:63] offset:64
	global_load_dwordx4 v[112:115], v169, s[62:63] offset:64
	global_load_dwordx4 v[100:103], v245, s[62:63] offset:64
	global_load_dwordx4 v[92:95], v252, s[62:63] offset:64
	global_load_dwordx4 v[104:107], v146, s[64:65] offset:64
	global_load_dwordx4 v[80:83], v169, s[64:65] offset:64
	ds_read_b128 v[160:163], v249 offset:7168
	ds_read_b128 v[164:167], v249 offset:7680
	s_waitcnt lgkmcnt(2)
	v_cndmask_b32_e32 v148, v72, v204, vcc
	v_cndmask_b32_e32 v149, v73, v205, vcc
	v_cndmask_b32_e32 v150, v74, v206, vcc
	v_cndmask_b32_e32 v151, v75, v207, vcc
	v_cndmask_b32_e64 v152, v72, v64, s[98:99]
	v_cndmask_b32_e64 v153, v73, v65, s[98:99]
	v_cndmask_b32_e64 v154, v74, v66, s[98:99]
	v_cndmask_b32_e64 v155, v75, v67, s[98:99]
	v_fma_f32 v156, v176, v72, v184
	v_fma_f32 v157, v177, v73, v185
	v_fma_f32 v158, v178, v74, v186
	v_fma_f32 v159, v179, v75, v187
	v_fmac_f32_dpp v156, v148, v172 row_ror:1 row_mask:0xf bank_mask:0xf
	v_fmac_f32_dpp v157, v149, v173 row_ror:1 row_mask:0xf bank_mask:0xf
	v_fmac_f32_dpp v158, v150, v174 row_ror:1 row_mask:0xf bank_mask:0xf
	v_fmac_f32_dpp v159, v151, v175 row_ror:1 row_mask:0xf bank_mask:0xf
	v_fmac_f32_dpp v156, v152, v180 row_ror:15 row_mask:0xf bank_mask:0xf
	v_fmac_f32_dpp v157, v153, v181 row_ror:15 row_mask:0xf bank_mask:0xf
	v_fmac_f32_dpp v158, v154, v182 row_ror:15 row_mask:0xf bank_mask:0xf
	v_fmac_f32_dpp v159, v155, v183 row_ror:15 row_mask:0xf bank_mask:0xf
	v_cndmask_b32_e32 v148, v48, v208, vcc
	v_cndmask_b32_e32 v149, v49, v209, vcc
	v_cndmask_b32_e32 v150, v50, v210, vcc
	v_cndmask_b32_e32 v151, v51, v211, vcc
	v_cndmask_b32_e64 v152, v48, v36, s[98:99]
	v_cndmask_b32_e64 v153, v49, v37, s[98:99]
	v_cndmask_b32_e64 v154, v50, v38, s[98:99]
	v_cndmask_b32_e64 v155, v51, v39, s[98:99]
	v_fma_f32 v237, v192, v48, v200
	v_fma_f32 v238, v193, v49, v201
	v_fma_f32 v239, v194, v50, v202
	v_fma_f32 v240, v195, v51, v203
	v_fmac_f32_dpp v237, v148, v188 row_ror:1 row_mask:0xf bank_mask:0xf
	v_fmac_f32_dpp v238, v149, v189 row_ror:1 row_mask:0xf bank_mask:0xf
	v_fmac_f32_dpp v239, v150, v190 row_ror:1 row_mask:0xf bank_mask:0xf
	v_fmac_f32_dpp v240, v151, v191 row_ror:1 row_mask:0xf bank_mask:0xf
	v_fmac_f32_dpp v237, v152, v196 row_ror:15 row_mask:0xf bank_mask:0xf
	v_fmac_f32_dpp v238, v153, v197 row_ror:15 row_mask:0xf bank_mask:0xf
	v_fmac_f32_dpp v239, v154, v198 row_ror:15 row_mask:0xf bank_mask:0xf
	v_fmac_f32_dpp v240, v155, v199 row_ror:15 row_mask:0xf bank_mask:0xf
	v_mul_f32_e32 v148, 0xbfb8aa3b, v156
	v_mul_f32_e32 v149, 0xbfb8aa3b, v157
	v_mul_f32_e32 v150, 0xbfb8aa3b, v158
	v_mul_f32_e32 v151, 0xbfb8aa3b, v159
	v_exp_f32_e32 v148, v148
	v_exp_f32_e32 v149, v149
	v_exp_f32_e32 v150, v150
	v_exp_f32_e32 v151, v151
	v_add_f32_e32 v148, 1.0, v148
	v_add_f32_e32 v149, 1.0, v149
	v_add_f32_e32 v150, 1.0, v150
	v_add_f32_e32 v151, 1.0, v151
	v_rcp_f32_e32 v148, v148
	v_rcp_f32_e32 v149, v149
	v_rcp_f32_e32 v150, v150
	v_rcp_f32_e32 v151, v151
	v_mul_f32_e32 v156, v156, v148
	v_mul_f32_e32 v157, v157, v149
	v_mul_f32_e32 v158, v158, v150
	v_mul_f32_e32 v159, v159, v151
	v_mul_f32_e32 v156, v156, v237
	v_mul_f32_e32 v157, v157, v238
	v_mul_f32_e32 v158, v158, v239
	v_mul_f32_e32 v159, v159, v240
	v_cvt_pk_bf16_f32 v247, v156, v157
	v_cvt_pk_bf16_f32 v248, v158, v159
	ds_read_b128 v[204:207], v249 offset:64
	ds_read_b128 v[208:211], v249 offset:576
	v_cndmask_b32_e32 v148, v64, v72, vcc
	v_cndmask_b32_e32 v149, v65, v73, vcc
	v_cndmask_b32_e32 v150, v66, v74, vcc
	v_cndmask_b32_e32 v151, v67, v75, vcc
	v_cndmask_b32_e64 v152, v64, v56, s[98:99]
	v_cndmask_b32_e64 v153, v65, v57, s[98:99]
	v_cndmask_b32_e64 v154, v66, v58, s[98:99]
	v_cndmask_b32_e64 v155, v67, v59, s[98:99]
	v_fma_f32 v156, v176, v64, v184
	v_fma_f32 v157, v177, v65, v185
	v_fma_f32 v158, v178, v66, v186
	v_fma_f32 v159, v179, v67, v187
	v_fmac_f32_dpp v156, v148, v172 row_ror:1 row_mask:0xf bank_mask:0xf
	v_fmac_f32_dpp v157, v149, v173 row_ror:1 row_mask:0xf bank_mask:0xf
	v_fmac_f32_dpp v158, v150, v174 row_ror:1 row_mask:0xf bank_mask:0xf
	v_fmac_f32_dpp v159, v151, v175 row_ror:1 row_mask:0xf bank_mask:0xf
	v_fmac_f32_dpp v156, v152, v180 row_ror:15 row_mask:0xf bank_mask:0xf
	v_fmac_f32_dpp v157, v153, v181 row_ror:15 row_mask:0xf bank_mask:0xf
	v_fmac_f32_dpp v158, v154, v182 row_ror:15 row_mask:0xf bank_mask:0xf
	v_fmac_f32_dpp v159, v155, v183 row_ror:15 row_mask:0xf bank_mask:0xf
	v_cndmask_b32_e32 v148, v36, v48, vcc
	v_cndmask_b32_e32 v149, v37, v49, vcc
	v_cndmask_b32_e32 v150, v38, v50, vcc
	v_cndmask_b32_e32 v151, v39, v51, vcc
	v_cndmask_b32_e64 v152, v36, v28, s[98:99]
	v_cndmask_b32_e64 v153, v37, v29, s[98:99]
	v_cndmask_b32_e64 v154, v38, v30, s[98:99]
	v_cndmask_b32_e64 v155, v39, v31, s[98:99]
	v_fma_f32 v237, v192, v36, v200
	v_fma_f32 v238, v193, v37, v201
	v_fma_f32 v239, v194, v38, v202
	v_fma_f32 v240, v195, v39, v203
	v_fmac_f32_dpp v237, v148, v188 row_ror:1 row_mask:0xf bank_mask:0xf
	v_fmac_f32_dpp v238, v149, v189 row_ror:1 row_mask:0xf bank_mask:0xf
	v_fmac_f32_dpp v239, v150, v190 row_ror:1 row_mask:0xf bank_mask:0xf
	v_fmac_f32_dpp v240, v151, v191 row_ror:1 row_mask:0xf bank_mask:0xf
	v_fmac_f32_dpp v237, v152, v196 row_ror:15 row_mask:0xf bank_mask:0xf
	v_fmac_f32_dpp v238, v153, v197 row_ror:15 row_mask:0xf bank_mask:0xf
	v_fmac_f32_dpp v239, v154, v198 row_ror:15 row_mask:0xf bank_mask:0xf
	v_fmac_f32_dpp v240, v155, v199 row_ror:15 row_mask:0xf bank_mask:0xf
	v_mul_f32_e32 v148, 0xbfb8aa3b, v156
	v_mul_f32_e32 v149, 0xbfb8aa3b, v157
	v_mul_f32_e32 v150, 0xbfb8aa3b, v158
	v_mul_f32_e32 v151, 0xbfb8aa3b, v159
	v_exp_f32_e32 v148, v148
	v_exp_f32_e32 v149, v149
	v_exp_f32_e32 v150, v150
	v_exp_f32_e32 v151, v151
	v_add_f32_e32 v148, 1.0, v148
	v_add_f32_e32 v149, 1.0, v149
	v_add_f32_e32 v150, 1.0, v150
	v_add_f32_e32 v151, 1.0, v151
	v_rcp_f32_e32 v148, v148
	v_rcp_f32_e32 v149, v149
	v_rcp_f32_e32 v150, v150
	v_rcp_f32_e32 v151, v151
	v_mul_f32_e32 v156, v156, v148
	v_mul_f32_e32 v157, v157, v149
	v_mul_f32_e32 v158, v158, v150
	v_mul_f32_e32 v159, v159, v151
	v_mul_f32_e32 v156, v156, v237
	v_mul_f32_e32 v157, v157, v238
	v_mul_f32_e32 v158, v158, v239
	v_mul_f32_e32 v159, v159, v240
	v_cvt_pk_bf16_f32 v72, v156, v157
	v_cvt_pk_bf16_f32 v73, v158, v159
	v_cndmask_b32_e32 v148, v56, v64, vcc
	v_cndmask_b32_e32 v149, v57, v65, vcc
	v_cndmask_b32_e32 v150, v58, v66, vcc
	v_cndmask_b32_e32 v151, v59, v67, vcc
	v_cndmask_b32_e64 v152, v56, v40, s[98:99]
	v_cndmask_b32_e64 v153, v57, v41, s[98:99]
	v_cndmask_b32_e64 v154, v58, v42, s[98:99]
	v_cndmask_b32_e64 v155, v59, v43, s[98:99]
	v_fma_f32 v156, v176, v56, v184
	v_fma_f32 v157, v177, v57, v185
	v_fma_f32 v158, v178, v58, v186
	v_fma_f32 v159, v179, v59, v187
	v_fmac_f32_dpp v156, v148, v172 row_ror:1 row_mask:0xf bank_mask:0xf
	v_fmac_f32_dpp v157, v149, v173 row_ror:1 row_mask:0xf bank_mask:0xf
	v_fmac_f32_dpp v158, v150, v174 row_ror:1 row_mask:0xf bank_mask:0xf
	v_fmac_f32_dpp v159, v151, v175 row_ror:1 row_mask:0xf bank_mask:0xf
	v_fmac_f32_dpp v156, v152, v180 row_ror:15 row_mask:0xf bank_mask:0xf
	v_fmac_f32_dpp v157, v153, v181 row_ror:15 row_mask:0xf bank_mask:0xf
	v_fmac_f32_dpp v158, v154, v182 row_ror:15 row_mask:0xf bank_mask:0xf
	v_fmac_f32_dpp v159, v155, v183 row_ror:15 row_mask:0xf bank_mask:0xf
	v_cndmask_b32_e32 v148, v28, v36, vcc
	v_cndmask_b32_e32 v149, v29, v37, vcc
	v_cndmask_b32_e32 v150, v30, v38, vcc
	v_cndmask_b32_e32 v151, v31, v39, vcc
	v_cndmask_b32_e64 v152, v28, v16, s[98:99]
	v_cndmask_b32_e64 v153, v29, v17, s[98:99]
	v_cndmask_b32_e64 v154, v30, v18, s[98:99]
	v_cndmask_b32_e64 v155, v31, v19, s[98:99]
	v_fma_f32 v237, v192, v28, v200
	v_fma_f32 v238, v193, v29, v201
	v_fma_f32 v239, v194, v30, v202
	v_fma_f32 v240, v195, v31, v203
	v_fmac_f32_dpp v237, v148, v188 row_ror:1 row_mask:0xf bank_mask:0xf
	v_fmac_f32_dpp v238, v149, v189 row_ror:1 row_mask:0xf bank_mask:0xf
	v_fmac_f32_dpp v239, v150, v190 row_ror:1 row_mask:0xf bank_mask:0xf
	v_fmac_f32_dpp v240, v151, v191 row_ror:1 row_mask:0xf bank_mask:0xf
	v_fmac_f32_dpp v237, v152, v196 row_ror:15 row_mask:0xf bank_mask:0xf
	v_fmac_f32_dpp v238, v153, v197 row_ror:15 row_mask:0xf bank_mask:0xf
	v_fmac_f32_dpp v239, v154, v198 row_ror:15 row_mask:0xf bank_mask:0xf
	v_fmac_f32_dpp v240, v155, v199 row_ror:15 row_mask:0xf bank_mask:0xf
	v_mul_f32_e32 v148, 0xbfb8aa3b, v156
	v_mul_f32_e32 v149, 0xbfb8aa3b, v157
	v_mul_f32_e32 v150, 0xbfb8aa3b, v158
	v_mul_f32_e32 v151, 0xbfb8aa3b, v159
	v_exp_f32_e32 v148, v148
	v_exp_f32_e32 v149, v149
	v_exp_f32_e32 v150, v150
	v_exp_f32_e32 v151, v151
	v_add_f32_e32 v148, 1.0, v148
	v_add_f32_e32 v149, 1.0, v149
	v_add_f32_e32 v150, 1.0, v150
	v_add_f32_e32 v151, 1.0, v151
	v_rcp_f32_e32 v148, v148
	v_rcp_f32_e32 v149, v149
	v_rcp_f32_e32 v150, v150
	v_rcp_f32_e32 v151, v151
	v_mul_f32_e32 v156, v156, v148
	v_mul_f32_e32 v157, v157, v149
	v_mul_f32_e32 v158, v158, v150
	v_mul_f32_e32 v159, v159, v151
	v_mul_f32_e32 v156, v156, v237
	v_mul_f32_e32 v157, v157, v238
	v_mul_f32_e32 v158, v158, v239
	v_mul_f32_e32 v159, v159, v240
	v_cvt_pk_bf16_f32 v74, v156, v157
	v_cvt_pk_bf16_f32 v75, v158, v159
	s_waitcnt lgkmcnt(2)
	v_cndmask_b32_e32 v148, v40, v56, vcc
	v_cndmask_b32_e32 v149, v41, v57, vcc
	v_cndmask_b32_e32 v150, v42, v58, vcc
	v_cndmask_b32_e32 v151, v43, v59, vcc
	v_cndmask_b32_e64 v152, v40, v160, s[98:99]
	v_cndmask_b32_e64 v153, v41, v161, s[98:99]
	v_cndmask_b32_e64 v154, v42, v162, s[98:99]
	v_cndmask_b32_e64 v155, v43, v163, s[98:99]
	v_fma_f32 v156, v176, v40, v184
	v_fma_f32 v157, v177, v41, v185
	v_fma_f32 v158, v178, v42, v186
	v_fma_f32 v159, v179, v43, v187
	v_fmac_f32_dpp v156, v148, v172 row_ror:1 row_mask:0xf bank_mask:0xf
	v_fmac_f32_dpp v157, v149, v173 row_ror:1 row_mask:0xf bank_mask:0xf
	v_fmac_f32_dpp v158, v150, v174 row_ror:1 row_mask:0xf bank_mask:0xf
	v_fmac_f32_dpp v159, v151, v175 row_ror:1 row_mask:0xf bank_mask:0xf
	v_fmac_f32_dpp v156, v152, v180 row_ror:15 row_mask:0xf bank_mask:0xf
	v_fmac_f32_dpp v157, v153, v181 row_ror:15 row_mask:0xf bank_mask:0xf
	v_fmac_f32_dpp v158, v154, v182 row_ror:15 row_mask:0xf bank_mask:0xf
	v_fmac_f32_dpp v159, v155, v183 row_ror:15 row_mask:0xf bank_mask:0xf
	v_cndmask_b32_e32 v148, v16, v28, vcc
	v_cndmask_b32_e32 v149, v17, v29, vcc
	v_cndmask_b32_e32 v150, v18, v30, vcc
	v_cndmask_b32_e32 v151, v19, v31, vcc
	v_cndmask_b32_e64 v152, v16, v164, s[98:99]
	v_cndmask_b32_e64 v153, v17, v165, s[98:99]
	v_cndmask_b32_e64 v154, v18, v166, s[98:99]
	v_cndmask_b32_e64 v155, v19, v167, s[98:99]
	v_fma_f32 v237, v192, v16, v200
	v_fma_f32 v238, v193, v17, v201
	v_fma_f32 v239, v194, v18, v202
	v_fma_f32 v240, v195, v19, v203
	v_fmac_f32_dpp v237, v148, v188 row_ror:1 row_mask:0xf bank_mask:0xf
	v_fmac_f32_dpp v238, v149, v189 row_ror:1 row_mask:0xf bank_mask:0xf
	v_fmac_f32_dpp v239, v150, v190 row_ror:1 row_mask:0xf bank_mask:0xf
	v_fmac_f32_dpp v240, v151, v191 row_ror:1 row_mask:0xf bank_mask:0xf
	v_fmac_f32_dpp v237, v152, v196 row_ror:15 row_mask:0xf bank_mask:0xf
	v_fmac_f32_dpp v238, v153, v197 row_ror:15 row_mask:0xf bank_mask:0xf
	v_fmac_f32_dpp v239, v154, v198 row_ror:15 row_mask:0xf bank_mask:0xf
	v_fmac_f32_dpp v240, v155, v199 row_ror:15 row_mask:0xf bank_mask:0xf
	v_mul_f32_e32 v148, 0xbfb8aa3b, v156
	v_mul_f32_e32 v149, 0xbfb8aa3b, v157
	v_mul_f32_e32 v150, 0xbfb8aa3b, v158
	v_mul_f32_e32 v151, 0xbfb8aa3b, v159
	v_exp_f32_e32 v148, v148
	v_exp_f32_e32 v149, v149
	v_exp_f32_e32 v150, v150
	v_exp_f32_e32 v151, v151
	v_add_f32_e32 v148, 1.0, v148
	v_add_f32_e32 v149, 1.0, v149
	v_add_f32_e32 v150, 1.0, v150
	v_add_f32_e32 v151, 1.0, v151
	v_rcp_f32_e32 v148, v148
	v_rcp_f32_e32 v149, v149
	v_rcp_f32_e32 v150, v150
	v_rcp_f32_e32 v151, v151
	v_mul_f32_e32 v156, v156, v148
	v_mul_f32_e32 v157, v157, v149
	v_mul_f32_e32 v158, v158, v150
	v_mul_f32_e32 v159, v159, v151
	v_mul_f32_e32 v156, v156, v237
	v_mul_f32_e32 v157, v157, v238
	v_mul_f32_e32 v158, v158, v239
	v_mul_f32_e32 v159, v159, v240
	v_cvt_pk_bf16_f32 v48, v156, v157
	v_cvt_pk_bf16_f32 v49, v158, v159
	ds_read_b128 v[160:163], v249 offset:3136
	ds_read_b128 v[164:167], v249 offset:3648
	s_waitcnt vmcnt(0) lgkmcnt(0)
	v_mbcnt_lo_u32_b32 v146, -1, 0
	v_mbcnt_hi_u32_b32 v146, -1, v146
	v_bfe_i32 v146, v146, 4, 1
	v_cndmask_b32_e32 v148, v108, v204, vcc
	v_cndmask_b32_e32 v149, v109, v205, vcc
	v_cndmask_b32_e32 v150, v110, v206, vcc
	v_cndmask_b32_e32 v151, v111, v207, vcc
	v_cndmask_b32_e64 v152, v108, v96, s[98:99]
	v_cndmask_b32_e64 v153, v109, v97, s[98:99]
	v_cndmask_b32_e64 v154, v110, v98, s[98:99]
	v_cndmask_b32_e64 v155, v111, v99, s[98:99]
	v_fma_f32 v156, v120, v108, v104
	v_fma_f32 v157, v121, v109, v105
	v_fma_f32 v158, v122, v110, v106
	v_fma_f32 v159, v123, v111, v107
	v_fmac_f32_dpp v156, v148, v124 row_ror:1 row_mask:0xf bank_mask:0xf
	v_fmac_f32_dpp v157, v149, v125 row_ror:1 row_mask:0xf bank_mask:0xf
	v_fmac_f32_dpp v158, v150, v126 row_ror:1 row_mask:0xf bank_mask:0xf
	v_fmac_f32_dpp v159, v151, v127 row_ror:1 row_mask:0xf bank_mask:0xf
	v_fmac_f32_dpp v156, v152, v116 row_ror:15 row_mask:0xf bank_mask:0xf
	v_fmac_f32_dpp v157, v153, v117 row_ror:15 row_mask:0xf bank_mask:0xf
	v_fmac_f32_dpp v158, v154, v118 row_ror:15 row_mask:0xf bank_mask:0xf
	v_fmac_f32_dpp v159, v155, v119 row_ror:15 row_mask:0xf bank_mask:0xf
	v_cndmask_b32_e32 v148, v84, v208, vcc
	v_cndmask_b32_e32 v149, v85, v209, vcc
	v_cndmask_b32_e32 v150, v86, v210, vcc
	v_cndmask_b32_e32 v151, v87, v211, vcc
	v_cndmask_b32_e64 v152, v84, v68, s[98:99]
	v_cndmask_b32_e64 v153, v85, v69, s[98:99]
	v_cndmask_b32_e64 v154, v86, v70, s[98:99]
	v_cndmask_b32_e64 v155, v87, v71, s[98:99]
	v_fma_f32 v237, v100, v84, v80
	v_fma_f32 v238, v101, v85, v81
	v_fma_f32 v239, v102, v86, v82
	v_fma_f32 v240, v103, v87, v83
	v_fmac_f32_dpp v237, v148, v112 row_ror:1 row_mask:0xf bank_mask:0xf
	v_fmac_f32_dpp v238, v149, v113 row_ror:1 row_mask:0xf bank_mask:0xf
	v_fmac_f32_dpp v239, v150, v114 row_ror:1 row_mask:0xf bank_mask:0xf
	v_fmac_f32_dpp v240, v151, v115 row_ror:1 row_mask:0xf bank_mask:0xf
	v_fmac_f32_dpp v237, v152, v92 row_ror:15 row_mask:0xf bank_mask:0xf
	v_fmac_f32_dpp v238, v153, v93 row_ror:15 row_mask:0xf bank_mask:0xf
	v_fmac_f32_dpp v239, v154, v94 row_ror:15 row_mask:0xf bank_mask:0xf
	v_fmac_f32_dpp v240, v155, v95 row_ror:15 row_mask:0xf bank_mask:0xf
	v_mul_f32_e32 v148, 0xbfb8aa3b, v156
	v_mul_f32_e32 v149, 0xbfb8aa3b, v157
	v_mul_f32_e32 v150, 0xbfb8aa3b, v158
	v_mul_f32_e32 v151, 0xbfb8aa3b, v159
	v_exp_f32_e32 v148, v148
	v_exp_f32_e32 v149, v149
	v_exp_f32_e32 v150, v150
	v_exp_f32_e32 v151, v151
	v_add_f32_e32 v148, 1.0, v148
	v_add_f32_e32 v149, 1.0, v149
	v_add_f32_e32 v150, 1.0, v150
	v_add_f32_e32 v151, 1.0, v151
	v_rcp_f32_e32 v148, v148
	v_rcp_f32_e32 v149, v149
	v_rcp_f32_e32 v150, v150
	v_rcp_f32_e32 v151, v151
	v_mul_f32_e32 v156, v156, v148
	v_mul_f32_e32 v157, v157, v149
	v_mul_f32_e32 v158, v158, v150
	v_mul_f32_e32 v159, v159, v151
	v_mul_f32_e32 v156, v156, v237
	v_mul_f32_e32 v157, v157, v238
	v_mul_f32_e32 v158, v158, v239
	v_mul_f32_e32 v159, v159, v240
	v_cvt_pk_bf16_f32 v40, v156, v157
	v_cvt_pk_bf16_f32 v41, v158, v159
	v_bfi_b32 v18, v146, v241, v40
	v_bfi_b32 v19, v146, v242, v41
	ds_swizzle_b32 v16, v18 offset:0x401f
	ds_swizzle_b32 v17, v19 offset:0x401f
	v_mov_b32_e32 v42, v250
	v_lshrrev_b32_e32 v152, 6, v251
	s_nop 1
	v_readfirstlane_b32 s100, v152
	s_waitcnt lgkmcnt(0)
	v_bfi_b32 v148, v146, v16, v241
	v_bfi_b32 v149, v146, v17, v242
	v_bfi_b32 v150, v146, v40, v16
	v_bfi_b32 v151, v146, v41, v17
	s_cmp_eq_u32 s100, 0
	s_cselect_b64 s[100:101], s[98:99], 0
	s_andn2_b64 exec, exec, s[100:101]
	global_store_dwordx4 v42, v[148:151], s[14:15] sc1
	s_mov_b64 exec, -1
	s_nop 1
	ds_read_b128 v[204:207], v249 offset:4160
	ds_read_b128 v[208:211], v249 offset:4672
	v_cndmask_b32_e32 v148, v96, v108, vcc
	v_cndmask_b32_e32 v149, v97, v109, vcc
	v_cndmask_b32_e32 v150, v98, v110, vcc
	v_cndmask_b32_e32 v151, v99, v111, vcc
	v_cndmask_b32_e64 v152, v96, v88, s[98:99]
	v_cndmask_b32_e64 v153, v97, v89, s[98:99]
	v_cndmask_b32_e64 v154, v98, v90, s[98:99]
	v_cndmask_b32_e64 v155, v99, v91, s[98:99]
	v_fma_f32 v156, v120, v96, v104
	v_fma_f32 v157, v121, v97, v105
	v_fma_f32 v158, v122, v98, v106
	v_fma_f32 v159, v123, v99, v107
	v_fmac_f32_dpp v156, v148, v124 row_ror:1 row_mask:0xf bank_mask:0xf
	v_fmac_f32_dpp v157, v149, v125 row_ror:1 row_mask:0xf bank_mask:0xf
	v_fmac_f32_dpp v158, v150, v126 row_ror:1 row_mask:0xf bank_mask:0xf
	v_fmac_f32_dpp v159, v151, v127 row_ror:1 row_mask:0xf bank_mask:0xf
	v_fmac_f32_dpp v156, v152, v116 row_ror:15 row_mask:0xf bank_mask:0xf
	v_fmac_f32_dpp v157, v153, v117 row_ror:15 row_mask:0xf bank_mask:0xf
	v_fmac_f32_dpp v158, v154, v118 row_ror:15 row_mask:0xf bank_mask:0xf
	v_fmac_f32_dpp v159, v155, v119 row_ror:15 row_mask:0xf bank_mask:0xf
	v_cndmask_b32_e32 v148, v68, v84, vcc
	v_cndmask_b32_e32 v149, v69, v85, vcc
	v_cndmask_b32_e32 v150, v70, v86, vcc
	v_cndmask_b32_e32 v151, v71, v87, vcc
	v_cndmask_b32_e64 v152, v68, v60, s[98:99]
	v_cndmask_b32_e64 v153, v69, v61, s[98:99]
	v_cndmask_b32_e64 v154, v70, v62, s[98:99]
	v_cndmask_b32_e64 v155, v71, v63, s[98:99]
	v_fma_f32 v237, v100, v68, v80
	v_fma_f32 v238, v101, v69, v81
	v_fma_f32 v239, v102, v70, v82
	v_fma_f32 v240, v103, v71, v83
	v_fmac_f32_dpp v237, v148, v112 row_ror:1 row_mask:0xf bank_mask:0xf
	v_fmac_f32_dpp v238, v149, v113 row_ror:1 row_mask:0xf bank_mask:0xf
	v_fmac_f32_dpp v239, v150, v114 row_ror:1 row_mask:0xf bank_mask:0xf
	v_fmac_f32_dpp v240, v151, v115 row_ror:1 row_mask:0xf bank_mask:0xf
	v_fmac_f32_dpp v237, v152, v92 row_ror:15 row_mask:0xf bank_mask:0xf
	v_fmac_f32_dpp v238, v153, v93 row_ror:15 row_mask:0xf bank_mask:0xf
	v_fmac_f32_dpp v239, v154, v94 row_ror:15 row_mask:0xf bank_mask:0xf
	v_fmac_f32_dpp v240, v155, v95 row_ror:15 row_mask:0xf bank_mask:0xf
	v_mul_f32_e32 v148, 0xbfb8aa3b, v156
	v_mul_f32_e32 v149, 0xbfb8aa3b, v157
	v_mul_f32_e32 v150, 0xbfb8aa3b, v158
	v_mul_f32_e32 v151, 0xbfb8aa3b, v159
	v_exp_f32_e32 v148, v148
	v_exp_f32_e32 v149, v149
	v_exp_f32_e32 v150, v150
	v_exp_f32_e32 v151, v151
	v_add_f32_e32 v148, 1.0, v148
	v_add_f32_e32 v149, 1.0, v149
	v_add_f32_e32 v150, 1.0, v150
	v_add_f32_e32 v151, 1.0, v151
	v_rcp_f32_e32 v148, v148
	v_rcp_f32_e32 v149, v149
	v_rcp_f32_e32 v150, v150
	v_rcp_f32_e32 v151, v151
	v_mul_f32_e32 v156, v156, v148
	v_mul_f32_e32 v157, v157, v149
	v_mul_f32_e32 v158, v158, v150
	v_mul_f32_e32 v159, v159, v151
	v_mul_f32_e32 v156, v156, v237
	v_mul_f32_e32 v157, v157, v238
	v_mul_f32_e32 v158, v158, v239
	v_mul_f32_e32 v159, v159, v240
	v_cvt_pk_bf16_f32 v40, v156, v157
	v_cvt_pk_bf16_f32 v41, v158, v159
	v_bfi_b32 v18, v146, v243, v40
	v_bfi_b32 v19, v146, v244, v41
	ds_swizzle_b32 v16, v18 offset:0x401f
	ds_swizzle_b32 v17, v19 offset:0x401f
	v_add_u32_e32 v42, 0x16000, v250
	s_waitcnt lgkmcnt(0)
	v_bfi_b32 v148, v146, v16, v243
	v_bfi_b32 v149, v146, v17, v244
	v_bfi_b32 v150, v146, v40, v16
	v_bfi_b32 v151, v146, v41, v17
	global_store_dwordx4 v42, v[148:151], s[14:15] sc1
	s_nop 1
	v_cndmask_b32_e32 v148, v88, v96, vcc
	v_cndmask_b32_e32 v149, v89, v97, vcc
	v_cndmask_b32_e32 v150, v90, v98, vcc
	v_cndmask_b32_e32 v151, v91, v99, vcc
	v_cndmask_b32_e64 v152, v88, v76, s[98:99]
	v_cndmask_b32_e64 v153, v89, v77, s[98:99]
	v_cndmask_b32_e64 v154, v90, v78, s[98:99]
	v_cndmask_b32_e64 v155, v91, v79, s[98:99]
	v_fma_f32 v156, v120, v88, v104
	v_fma_f32 v157, v121, v89, v105
	v_fma_f32 v158, v122, v90, v106
	v_fma_f32 v159, v123, v91, v107
	v_fmac_f32_dpp v156, v148, v124 row_ror:1 row_mask:0xf bank_mask:0xf
	v_fmac_f32_dpp v157, v149, v125 row_ror:1 row_mask:0xf bank_mask:0xf
	v_fmac_f32_dpp v158, v150, v126 row_ror:1 row_mask:0xf bank_mask:0xf
	v_fmac_f32_dpp v159, v151, v127 row_ror:1 row_mask:0xf bank_mask:0xf
	v_fmac_f32_dpp v156, v152, v116 row_ror:15 row_mask:0xf bank_mask:0xf
	v_fmac_f32_dpp v157, v153, v117 row_ror:15 row_mask:0xf bank_mask:0xf
	v_fmac_f32_dpp v158, v154, v118 row_ror:15 row_mask:0xf bank_mask:0xf
	v_fmac_f32_dpp v159, v155, v119 row_ror:15 row_mask:0xf bank_mask:0xf
	v_cndmask_b32_e32 v148, v60, v68, vcc
	v_cndmask_b32_e32 v149, v61, v69, vcc
	v_cndmask_b32_e32 v150, v62, v70, vcc
	v_cndmask_b32_e32 v151, v63, v71, vcc
	v_cndmask_b32_e64 v152, v60, v52, s[98:99]
	v_cndmask_b32_e64 v153, v61, v53, s[98:99]
	v_cndmask_b32_e64 v154, v62, v54, s[98:99]
	v_cndmask_b32_e64 v155, v63, v55, s[98:99]
	v_fma_f32 v237, v100, v60, v80
	v_fma_f32 v238, v101, v61, v81
	v_fma_f32 v239, v102, v62, v82
	v_fma_f32 v240, v103, v63, v83
	v_fmac_f32_dpp v237, v148, v112 row_ror:1 row_mask:0xf bank_mask:0xf
	v_fmac_f32_dpp v238, v149, v113 row_ror:1 row_mask:0xf bank_mask:0xf
	v_fmac_f32_dpp v239, v150, v114 row_ror:1 row_mask:0xf bank_mask:0xf
	v_fmac_f32_dpp v240, v151, v115 row_ror:1 row_mask:0xf bank_mask:0xf
	v_fmac_f32_dpp v237, v152, v92 row_ror:15 row_mask:0xf bank_mask:0xf
	v_fmac_f32_dpp v238, v153, v93 row_ror:15 row_mask:0xf bank_mask:0xf
	v_fmac_f32_dpp v239, v154, v94 row_ror:15 row_mask:0xf bank_mask:0xf
	v_fmac_f32_dpp v240, v155, v95 row_ror:15 row_mask:0xf bank_mask:0xf
	v_mul_f32_e32 v148, 0xbfb8aa3b, v156
	v_mul_f32_e32 v149, 0xbfb8aa3b, v157
	v_mul_f32_e32 v150, 0xbfb8aa3b, v158
	v_mul_f32_e32 v151, 0xbfb8aa3b, v159
	v_exp_f32_e32 v148, v148
	v_exp_f32_e32 v149, v149
	v_exp_f32_e32 v150, v150
	v_exp_f32_e32 v151, v151
	v_add_f32_e32 v148, 1.0, v148
	v_add_f32_e32 v149, 1.0, v149
	v_add_f32_e32 v150, 1.0, v150
	v_add_f32_e32 v151, 1.0, v151
	v_rcp_f32_e32 v148, v148
	v_rcp_f32_e32 v149, v149
	v_rcp_f32_e32 v150, v150
	v_rcp_f32_e32 v151, v151
	v_mul_f32_e32 v156, v156, v148
	v_mul_f32_e32 v157, v157, v149
	v_mul_f32_e32 v158, v158, v150
	v_mul_f32_e32 v159, v159, v151
	v_mul_f32_e32 v156, v156, v237
	v_mul_f32_e32 v157, v157, v238
	v_mul_f32_e32 v158, v158, v239
	v_mul_f32_e32 v159, v159, v240
	v_cvt_pk_bf16_f32 v40, v156, v157
	v_cvt_pk_bf16_f32 v41, v158, v159
	v_bfi_b32 v18, v146, v253, v40
	v_bfi_b32 v19, v146, v254, v41
	ds_swizzle_b32 v16, v18 offset:0x401f
	ds_swizzle_b32 v17, v19 offset:0x401f
	v_add_u32_e32 v42, 0x2c000, v250
	s_waitcnt lgkmcnt(0)
	v_bfi_b32 v148, v146, v16, v253
	v_bfi_b32 v149, v146, v17, v254
	v_bfi_b32 v150, v146, v40, v16
	v_bfi_b32 v151, v146, v41, v17
	global_store_dwordx4 v42, v[148:151], s[14:15] sc1
	s_nop 1
	v_cndmask_b32_e32 v148, v76, v88, vcc
	v_cndmask_b32_e32 v149, v77, v89, vcc
	v_cndmask_b32_e32 v150, v78, v90, vcc
	v_cndmask_b32_e32 v151, v79, v91, vcc
	v_cndmask_b32_e64 v152, v76, v160, s[98:99]
	v_cndmask_b32_e64 v153, v77, v161, s[98:99]
	v_cndmask_b32_e64 v154, v78, v162, s[98:99]
	v_cndmask_b32_e64 v155, v79, v163, s[98:99]
	v_fma_f32 v156, v120, v76, v104
	v_fma_f32 v157, v121, v77, v105
	v_fma_f32 v158, v122, v78, v106
	v_fma_f32 v159, v123, v79, v107
	v_fmac_f32_dpp v156, v148, v124 row_ror:1 row_mask:0xf bank_mask:0xf
	v_fmac_f32_dpp v157, v149, v125 row_ror:1 row_mask:0xf bank_mask:0xf
	v_fmac_f32_dpp v158, v150, v126 row_ror:1 row_mask:0xf bank_mask:0xf
	v_fmac_f32_dpp v159, v151, v127 row_ror:1 row_mask:0xf bank_mask:0xf
	v_fmac_f32_dpp v156, v152, v116 row_ror:15 row_mask:0xf bank_mask:0xf
	v_fmac_f32_dpp v157, v153, v117 row_ror:15 row_mask:0xf bank_mask:0xf
	v_fmac_f32_dpp v158, v154, v118 row_ror:15 row_mask:0xf bank_mask:0xf
	v_fmac_f32_dpp v159, v155, v119 row_ror:15 row_mask:0xf bank_mask:0xf
	v_cndmask_b32_e32 v148, v52, v60, vcc
	v_cndmask_b32_e32 v149, v53, v61, vcc
	v_cndmask_b32_e32 v150, v54, v62, vcc
	v_cndmask_b32_e32 v151, v55, v63, vcc
	v_cndmask_b32_e64 v152, v52, v164, s[98:99]
	v_cndmask_b32_e64 v153, v53, v165, s[98:99]
	v_cndmask_b32_e64 v154, v54, v166, s[98:99]
	v_cndmask_b32_e64 v155, v55, v167, s[98:99]
	v_fma_f32 v237, v100, v52, v80
	v_fma_f32 v238, v101, v53, v81
	v_fma_f32 v239, v102, v54, v82
	v_fma_f32 v240, v103, v55, v83
	v_fmac_f32_dpp v237, v148, v112 row_ror:1 row_mask:0xf bank_mask:0xf
	v_fmac_f32_dpp v238, v149, v113 row_ror:1 row_mask:0xf bank_mask:0xf
	v_fmac_f32_dpp v239, v150, v114 row_ror:1 row_mask:0xf bank_mask:0xf
	v_fmac_f32_dpp v240, v151, v115 row_ror:1 row_mask:0xf bank_mask:0xf
	v_fmac_f32_dpp v237, v152, v92 row_ror:15 row_mask:0xf bank_mask:0xf
	v_fmac_f32_dpp v238, v153, v93 row_ror:15 row_mask:0xf bank_mask:0xf
	v_fmac_f32_dpp v239, v154, v94 row_ror:15 row_mask:0xf bank_mask:0xf
	v_fmac_f32_dpp v240, v155, v95 row_ror:15 row_mask:0xf bank_mask:0xf
	v_mul_f32_e32 v148, 0xbfb8aa3b, v156
	v_mul_f32_e32 v149, 0xbfb8aa3b, v157
	v_mul_f32_e32 v150, 0xbfb8aa3b, v158
	v_mul_f32_e32 v151, 0xbfb8aa3b, v159
	v_exp_f32_e32 v148, v148
	v_exp_f32_e32 v149, v149
	v_exp_f32_e32 v150, v150
	v_exp_f32_e32 v151, v151
	v_add_f32_e32 v148, 1.0, v148
	v_add_f32_e32 v149, 1.0, v149
	v_add_f32_e32 v150, 1.0, v150
	v_add_f32_e32 v151, 1.0, v151
	v_rcp_f32_e32 v148, v148
	v_rcp_f32_e32 v149, v149
	v_rcp_f32_e32 v150, v150
	v_rcp_f32_e32 v151, v151
	v_mul_f32_e32 v156, v156, v148
	v_mul_f32_e32 v157, v157, v149
	v_mul_f32_e32 v158, v158, v150
	v_mul_f32_e32 v159, v159, v151
	v_mul_f32_e32 v156, v156, v237
	v_mul_f32_e32 v157, v157, v238
	v_mul_f32_e32 v158, v158, v239
	v_mul_f32_e32 v159, v159, v240
	v_cvt_pk_bf16_f32 v40, v156, v157
	v_cvt_pk_bf16_f32 v41, v158, v159
	v_bfi_b32 v18, v146, v255, v40
	v_bfi_b32 v19, v146, v246, v41
	ds_swizzle_b32 v16, v18 offset:0x401f
	ds_swizzle_b32 v17, v19 offset:0x401f
	v_add_u32_e32 v42, 0x42000, v250
	s_waitcnt lgkmcnt(0)
	v_bfi_b32 v148, v146, v16, v255
	v_bfi_b32 v149, v146, v17, v246
	v_bfi_b32 v150, v146, v40, v16
	v_bfi_b32 v151, v146, v41, v17
	global_store_dwordx4 v42, v[148:151], s[14:15] sc1
	s_nop 1
	ds_read_b128 v[160:163], v249 offset:7232
	ds_read_b128 v[164:167], v249 offset:7744
	s_waitcnt lgkmcnt(2)
	v_cndmask_b32_e32 v148, v44, v204, vcc
	v_cndmask_b32_e32 v149, v45, v205, vcc
	v_cndmask_b32_e32 v150, v46, v206, vcc
	v_cndmask_b32_e32 v151, v47, v207, vcc
	v_cndmask_b32_e64 v152, v44, v32, s[98:99]
	v_cndmask_b32_e64 v153, v45, v33, s[98:99]
	v_cndmask_b32_e64 v154, v46, v34, s[98:99]
	v_cndmask_b32_e64 v155, v47, v35, s[98:99]
	v_fma_f32 v156, v120, v44, v104
	v_fma_f32 v157, v121, v45, v105
	v_fma_f32 v158, v122, v46, v106
	v_fma_f32 v159, v123, v47, v107
	v_fmac_f32_dpp v156, v148, v124 row_ror:1 row_mask:0xf bank_mask:0xf
	v_fmac_f32_dpp v157, v149, v125 row_ror:1 row_mask:0xf bank_mask:0xf
	v_fmac_f32_dpp v158, v150, v126 row_ror:1 row_mask:0xf bank_mask:0xf
	v_fmac_f32_dpp v159, v151, v127 row_ror:1 row_mask:0xf bank_mask:0xf
	v_fmac_f32_dpp v156, v152, v116 row_ror:15 row_mask:0xf bank_mask:0xf
	v_fmac_f32_dpp v157, v153, v117 row_ror:15 row_mask:0xf bank_mask:0xf
	v_fmac_f32_dpp v158, v154, v118 row_ror:15 row_mask:0xf bank_mask:0xf
	v_fmac_f32_dpp v159, v155, v119 row_ror:15 row_mask:0xf bank_mask:0xf
	v_cndmask_b32_e32 v148, v20, v208, vcc
	v_cndmask_b32_e32 v149, v21, v209, vcc
	v_cndmask_b32_e32 v150, v22, v210, vcc
	v_cndmask_b32_e32 v151, v23, v211, vcc
	v_cndmask_b32_e64 v152, v20, v8, s[98:99]
	v_cndmask_b32_e64 v153, v21, v9, s[98:99]
	v_cndmask_b32_e64 v154, v22, v10, s[98:99]
	v_cndmask_b32_e64 v155, v23, v11, s[98:99]
	v_fma_f32 v237, v100, v20, v80
	v_fma_f32 v238, v101, v21, v81
	v_fma_f32 v239, v102, v22, v82
	v_fma_f32 v240, v103, v23, v83
	v_fmac_f32_dpp v237, v148, v112 row_ror:1 row_mask:0xf bank_mask:0xf
	v_fmac_f32_dpp v238, v149, v113 row_ror:1 row_mask:0xf bank_mask:0xf
	v_fmac_f32_dpp v239, v150, v114 row_ror:1 row_mask:0xf bank_mask:0xf
	v_fmac_f32_dpp v240, v151, v115 row_ror:1 row_mask:0xf bank_mask:0xf
	v_fmac_f32_dpp v237, v152, v92 row_ror:15 row_mask:0xf bank_mask:0xf
	v_fmac_f32_dpp v238, v153, v93 row_ror:15 row_mask:0xf bank_mask:0xf
	v_fmac_f32_dpp v239, v154, v94 row_ror:15 row_mask:0xf bank_mask:0xf
	v_fmac_f32_dpp v240, v155, v95 row_ror:15 row_mask:0xf bank_mask:0xf
	v_mul_f32_e32 v148, 0xbfb8aa3b, v156
	v_mul_f32_e32 v149, 0xbfb8aa3b, v157
	v_mul_f32_e32 v150, 0xbfb8aa3b, v158
	v_mul_f32_e32 v151, 0xbfb8aa3b, v159
	v_exp_f32_e32 v148, v148
	v_exp_f32_e32 v149, v149
	v_exp_f32_e32 v150, v150
	v_exp_f32_e32 v151, v151
	v_add_f32_e32 v148, 1.0, v148
	v_add_f32_e32 v149, 1.0, v149
	v_add_f32_e32 v150, 1.0, v150
	v_add_f32_e32 v151, 1.0, v151
	v_rcp_f32_e32 v148, v148
	v_rcp_f32_e32 v149, v149
	v_rcp_f32_e32 v150, v150
	v_rcp_f32_e32 v151, v151
	v_mul_f32_e32 v156, v156, v148
	v_mul_f32_e32 v157, v157, v149
	v_mul_f32_e32 v158, v158, v150
	v_mul_f32_e32 v159, v159, v151
	v_mul_f32_e32 v156, v156, v237
	v_mul_f32_e32 v157, v157, v238
	v_mul_f32_e32 v158, v158, v239
	v_mul_f32_e32 v159, v159, v240
	v_cvt_pk_bf16_f32 v40, v156, v157
	v_cvt_pk_bf16_f32 v41, v158, v159
	v_bfi_b32 v18, v146, v247, v40
	v_bfi_b32 v19, v146, v248, v41
	ds_swizzle_b32 v16, v18 offset:0x401f
	ds_swizzle_b32 v17, v19 offset:0x401f
	v_add_u32_e32 v42, 0xb0000, v250
	s_waitcnt lgkmcnt(0)
	v_bfi_b32 v148, v146, v16, v247
	v_bfi_b32 v149, v146, v17, v248
	v_bfi_b32 v150, v146, v40, v16
	v_bfi_b32 v151, v146, v41, v17
	global_store_dwordx4 v42, v[148:151], s[14:15] sc1
	s_nop 1
	v_cndmask_b32_e32 v148, v32, v44, vcc
	v_cndmask_b32_e32 v149, v33, v45, vcc
	v_cndmask_b32_e32 v150, v34, v46, vcc
	v_cndmask_b32_e32 v151, v35, v47, vcc
	v_cndmask_b32_e64 v152, v32, v24, s[98:99]
	v_cndmask_b32_e64 v153, v33, v25, s[98:99]
	v_cndmask_b32_e64 v154, v34, v26, s[98:99]
	v_cndmask_b32_e64 v155, v35, v27, s[98:99]
	v_fma_f32 v156, v120, v32, v104
	v_fma_f32 v157, v121, v33, v105
	v_fma_f32 v158, v122, v34, v106
	v_fma_f32 v159, v123, v35, v107
	v_fmac_f32_dpp v156, v148, v124 row_ror:1 row_mask:0xf bank_mask:0xf
	v_fmac_f32_dpp v157, v149, v125 row_ror:1 row_mask:0xf bank_mask:0xf
	v_fmac_f32_dpp v158, v150, v126 row_ror:1 row_mask:0xf bank_mask:0xf
	v_fmac_f32_dpp v159, v151, v127 row_ror:1 row_mask:0xf bank_mask:0xf
	v_fmac_f32_dpp v156, v152, v116 row_ror:15 row_mask:0xf bank_mask:0xf
	v_fmac_f32_dpp v157, v153, v117 row_ror:15 row_mask:0xf bank_mask:0xf
	v_fmac_f32_dpp v158, v154, v118 row_ror:15 row_mask:0xf bank_mask:0xf
	v_fmac_f32_dpp v159, v155, v119 row_ror:15 row_mask:0xf bank_mask:0xf
	v_cndmask_b32_e32 v148, v8, v20, vcc
	v_cndmask_b32_e32 v149, v9, v21, vcc
	v_cndmask_b32_e32 v150, v10, v22, vcc
	v_cndmask_b32_e32 v151, v11, v23, vcc
	v_cndmask_b32_e64 v152, v8, v4, s[98:99]
	v_cndmask_b32_e64 v153, v9, v5, s[98:99]
	v_cndmask_b32_e64 v154, v10, v6, s[98:99]
	v_cndmask_b32_e64 v155, v11, v7, s[98:99]
	v_fma_f32 v237, v100, v8, v80
	v_fma_f32 v238, v101, v9, v81
	v_fma_f32 v239, v102, v10, v82
	v_fma_f32 v240, v103, v11, v83
	v_fmac_f32_dpp v237, v148, v112 row_ror:1 row_mask:0xf bank_mask:0xf
	v_fmac_f32_dpp v238, v149, v113 row_ror:1 row_mask:0xf bank_mask:0xf
	v_fmac_f32_dpp v239, v150, v114 row_ror:1 row_mask:0xf bank_mask:0xf
	v_fmac_f32_dpp v240, v151, v115 row_ror:1 row_mask:0xf bank_mask:0xf
	v_fmac_f32_dpp v237, v152, v92 row_ror:15 row_mask:0xf bank_mask:0xf
	v_fmac_f32_dpp v238, v153, v93 row_ror:15 row_mask:0xf bank_mask:0xf
	v_fmac_f32_dpp v239, v154, v94 row_ror:15 row_mask:0xf bank_mask:0xf
	v_fmac_f32_dpp v240, v155, v95 row_ror:15 row_mask:0xf bank_mask:0xf
	v_mul_f32_e32 v148, 0xbfb8aa3b, v156
	v_mul_f32_e32 v149, 0xbfb8aa3b, v157
	v_mul_f32_e32 v150, 0xbfb8aa3b, v158
	v_mul_f32_e32 v151, 0xbfb8aa3b, v159
	v_exp_f32_e32 v148, v148
	v_exp_f32_e32 v149, v149
	v_exp_f32_e32 v150, v150
	v_exp_f32_e32 v151, v151
	v_add_f32_e32 v148, 1.0, v148
	v_add_f32_e32 v149, 1.0, v149
	v_add_f32_e32 v150, 1.0, v150
	v_add_f32_e32 v151, 1.0, v151
	v_rcp_f32_e32 v148, v148
	v_rcp_f32_e32 v149, v149
	v_rcp_f32_e32 v150, v150
	v_rcp_f32_e32 v151, v151
	v_mul_f32_e32 v156, v156, v148
	v_mul_f32_e32 v157, v157, v149
	v_mul_f32_e32 v158, v158, v150
	v_mul_f32_e32 v159, v159, v151
	v_mul_f32_e32 v156, v156, v237
	v_mul_f32_e32 v157, v157, v238
	v_mul_f32_e32 v158, v158, v239
	v_mul_f32_e32 v159, v159, v240
	v_cvt_pk_bf16_f32 v40, v156, v157
	v_cvt_pk_bf16_f32 v41, v158, v159
	v_bfi_b32 v18, v146, v72, v40
	v_bfi_b32 v19, v146, v73, v41
	ds_swizzle_b32 v16, v18 offset:0x401f
	ds_swizzle_b32 v17, v19 offset:0x401f
	v_add_u32_e32 v42, 0xc6000, v250
	s_waitcnt lgkmcnt(0)
	v_bfi_b32 v148, v146, v16, v72
	v_bfi_b32 v149, v146, v17, v73
	v_bfi_b32 v150, v146, v40, v16
	v_bfi_b32 v151, v146, v41, v17
	global_store_dwordx4 v42, v[148:151], s[14:15] sc1
	s_nop 1
	v_cndmask_b32_e32 v148, v24, v32, vcc
	v_cndmask_b32_e32 v149, v25, v33, vcc
	v_cndmask_b32_e32 v150, v26, v34, vcc
	v_cndmask_b32_e32 v151, v27, v35, vcc
	v_cndmask_b32_e64 v152, v24, v12, s[98:99]
	v_cndmask_b32_e64 v153, v25, v13, s[98:99]
	v_cndmask_b32_e64 v154, v26, v14, s[98:99]
	v_cndmask_b32_e64 v155, v27, v15, s[98:99]
	v_fma_f32 v156, v120, v24, v104
	v_fma_f32 v157, v121, v25, v105
	v_fma_f32 v158, v122, v26, v106
	v_fma_f32 v159, v123, v27, v107
	v_fmac_f32_dpp v156, v148, v124 row_ror:1 row_mask:0xf bank_mask:0xf
	v_fmac_f32_dpp v157, v149, v125 row_ror:1 row_mask:0xf bank_mask:0xf
	v_fmac_f32_dpp v158, v150, v126 row_ror:1 row_mask:0xf bank_mask:0xf
	v_fmac_f32_dpp v159, v151, v127 row_ror:1 row_mask:0xf bank_mask:0xf
	v_fmac_f32_dpp v156, v152, v116 row_ror:15 row_mask:0xf bank_mask:0xf
	v_fmac_f32_dpp v157, v153, v117 row_ror:15 row_mask:0xf bank_mask:0xf
	v_fmac_f32_dpp v158, v154, v118 row_ror:15 row_mask:0xf bank_mask:0xf
	v_fmac_f32_dpp v159, v155, v119 row_ror:15 row_mask:0xf bank_mask:0xf
	v_cndmask_b32_e32 v148, v4, v8, vcc
	v_cndmask_b32_e32 v149, v5, v9, vcc
	v_cndmask_b32_e32 v150, v6, v10, vcc
	v_cndmask_b32_e32 v151, v7, v11, vcc
	v_cndmask_b32_e64 v152, v4, v0, s[98:99]
	v_cndmask_b32_e64 v153, v5, v1, s[98:99]
	v_cndmask_b32_e64 v154, v6, v2, s[98:99]
	v_cndmask_b32_e64 v155, v7, v3, s[98:99]
	v_fma_f32 v237, v100, v4, v80
	v_fma_f32 v238, v101, v5, v81
	v_fma_f32 v239, v102, v6, v82
	v_fma_f32 v240, v103, v7, v83
	v_fmac_f32_dpp v237, v148, v112 row_ror:1 row_mask:0xf bank_mask:0xf
	v_fmac_f32_dpp v238, v149, v113 row_ror:1 row_mask:0xf bank_mask:0xf
	v_fmac_f32_dpp v239, v150, v114 row_ror:1 row_mask:0xf bank_mask:0xf
	v_fmac_f32_dpp v240, v151, v115 row_ror:1 row_mask:0xf bank_mask:0xf
	v_fmac_f32_dpp v237, v152, v92 row_ror:15 row_mask:0xf bank_mask:0xf
	v_fmac_f32_dpp v238, v153, v93 row_ror:15 row_mask:0xf bank_mask:0xf
	v_fmac_f32_dpp v239, v154, v94 row_ror:15 row_mask:0xf bank_mask:0xf
	v_fmac_f32_dpp v240, v155, v95 row_ror:15 row_mask:0xf bank_mask:0xf
	v_mul_f32_e32 v148, 0xbfb8aa3b, v156
	v_mul_f32_e32 v149, 0xbfb8aa3b, v157
	v_mul_f32_e32 v150, 0xbfb8aa3b, v158
	v_mul_f32_e32 v151, 0xbfb8aa3b, v159
	v_exp_f32_e32 v148, v148
	v_exp_f32_e32 v149, v149
	v_exp_f32_e32 v150, v150
	v_exp_f32_e32 v151, v151
	v_add_f32_e32 v148, 1.0, v148
	v_add_f32_e32 v149, 1.0, v149
	v_add_f32_e32 v150, 1.0, v150
	v_add_f32_e32 v151, 1.0, v151
	v_rcp_f32_e32 v148, v148
	v_rcp_f32_e32 v149, v149
	v_rcp_f32_e32 v150, v150
	v_rcp_f32_e32 v151, v151
	v_mul_f32_e32 v156, v156, v148
	v_mul_f32_e32 v157, v157, v149
	v_mul_f32_e32 v158, v158, v150
	v_mul_f32_e32 v159, v159, v151
	v_mul_f32_e32 v156, v156, v237
	v_mul_f32_e32 v157, v157, v238
	v_mul_f32_e32 v158, v158, v239
	v_mul_f32_e32 v159, v159, v240
	v_cvt_pk_bf16_f32 v40, v156, v157
	v_cvt_pk_bf16_f32 v41, v158, v159
	v_bfi_b32 v18, v146, v74, v40
	v_bfi_b32 v19, v146, v75, v41
	ds_swizzle_b32 v16, v18 offset:0x401f
	ds_swizzle_b32 v17, v19 offset:0x401f
	v_add_u32_e32 v42, 0xdc000, v250
	s_waitcnt lgkmcnt(0)
	v_bfi_b32 v148, v146, v16, v74
	v_bfi_b32 v149, v146, v17, v75
	v_bfi_b32 v150, v146, v40, v16
	v_bfi_b32 v151, v146, v41, v17
	global_store_dwordx4 v42, v[148:151], s[14:15] sc1
	s_nop 1
	s_waitcnt lgkmcnt(0)
	v_cndmask_b32_e32 v148, v12, v24, vcc
	v_cndmask_b32_e32 v149, v13, v25, vcc
	v_cndmask_b32_e32 v150, v14, v26, vcc
	v_cndmask_b32_e32 v151, v15, v27, vcc
	v_cndmask_b32_e64 v152, v12, v160, s[98:99]
	v_cndmask_b32_e64 v153, v13, v161, s[98:99]
	v_cndmask_b32_e64 v154, v14, v162, s[98:99]
	v_cndmask_b32_e64 v155, v15, v163, s[98:99]
	v_fma_f32 v156, v120, v12, v104
	v_fma_f32 v157, v121, v13, v105
	v_fma_f32 v158, v122, v14, v106
	v_fma_f32 v159, v123, v15, v107
	v_fmac_f32_dpp v156, v148, v124 row_ror:1 row_mask:0xf bank_mask:0xf
	v_fmac_f32_dpp v157, v149, v125 row_ror:1 row_mask:0xf bank_mask:0xf
	v_fmac_f32_dpp v158, v150, v126 row_ror:1 row_mask:0xf bank_mask:0xf
	v_fmac_f32_dpp v159, v151, v127 row_ror:1 row_mask:0xf bank_mask:0xf
	v_fmac_f32_dpp v156, v152, v116 row_ror:15 row_mask:0xf bank_mask:0xf
	v_fmac_f32_dpp v157, v153, v117 row_ror:15 row_mask:0xf bank_mask:0xf
	v_fmac_f32_dpp v158, v154, v118 row_ror:15 row_mask:0xf bank_mask:0xf
	v_fmac_f32_dpp v159, v155, v119 row_ror:15 row_mask:0xf bank_mask:0xf
	v_cndmask_b32_e32 v148, v0, v4, vcc
	v_cndmask_b32_e32 v149, v1, v5, vcc
	v_cndmask_b32_e32 v150, v2, v6, vcc
	v_cndmask_b32_e32 v151, v3, v7, vcc
	v_cndmask_b32_e64 v152, v0, v164, s[98:99]
	v_cndmask_b32_e64 v153, v1, v165, s[98:99]
	v_cndmask_b32_e64 v154, v2, v166, s[98:99]
	v_cndmask_b32_e64 v155, v3, v167, s[98:99]
	v_fma_f32 v237, v100, v0, v80
	v_fma_f32 v238, v101, v1, v81
	v_fma_f32 v239, v102, v2, v82
	v_fma_f32 v240, v103, v3, v83
	v_fmac_f32_dpp v237, v148, v112 row_ror:1 row_mask:0xf bank_mask:0xf
	v_fmac_f32_dpp v238, v149, v113 row_ror:1 row_mask:0xf bank_mask:0xf
	v_fmac_f32_dpp v239, v150, v114 row_ror:1 row_mask:0xf bank_mask:0xf
	v_fmac_f32_dpp v240, v151, v115 row_ror:1 row_mask:0xf bank_mask:0xf
	v_fmac_f32_dpp v237, v152, v92 row_ror:15 row_mask:0xf bank_mask:0xf
	v_fmac_f32_dpp v238, v153, v93 row_ror:15 row_mask:0xf bank_mask:0xf
	v_fmac_f32_dpp v239, v154, v94 row_ror:15 row_mask:0xf bank_mask:0xf
	v_fmac_f32_dpp v240, v155, v95 row_ror:15 row_mask:0xf bank_mask:0xf
	v_mul_f32_e32 v148, 0xbfb8aa3b, v156
	v_mul_f32_e32 v149, 0xbfb8aa3b, v157
	v_mul_f32_e32 v150, 0xbfb8aa3b, v158
	v_mul_f32_e32 v151, 0xbfb8aa3b, v159
	v_exp_f32_e32 v148, v148
	v_exp_f32_e32 v149, v149
	v_exp_f32_e32 v150, v150
	v_exp_f32_e32 v151, v151
	v_add_f32_e32 v148, 1.0, v148
	v_add_f32_e32 v149, 1.0, v149
	v_add_f32_e32 v150, 1.0, v150
	v_add_f32_e32 v151, 1.0, v151
	v_rcp_f32_e32 v148, v148
	v_rcp_f32_e32 v149, v149
	v_rcp_f32_e32 v150, v150
	v_rcp_f32_e32 v151, v151
	v_mul_f32_e32 v156, v156, v148
	v_mul_f32_e32 v157, v157, v149
	v_mul_f32_e32 v158, v158, v150
	v_mul_f32_e32 v159, v159, v151
	v_mul_f32_e32 v156, v156, v237
	v_mul_f32_e32 v157, v157, v238
	v_mul_f32_e32 v158, v158, v239
	v_mul_f32_e32 v159, v159, v240
	v_cvt_pk_bf16_f32 v40, v156, v157
	v_cvt_pk_bf16_f32 v41, v158, v159
	v_bfi_b32 v18, v146, v48, v40
	v_bfi_b32 v19, v146, v49, v41
	ds_swizzle_b32 v16, v18 offset:0x401f
	ds_swizzle_b32 v17, v19 offset:0x401f
	v_add_u32_e32 v42, 0xf2000, v250
	v_lshrrev_b32_e32 v152, 6, v251
	s_nop 1
	v_readfirstlane_b32 s100, v152
	s_waitcnt lgkmcnt(0)
	v_bfi_b32 v148, v146, v16, v48
	v_bfi_b32 v149, v146, v17, v49
	v_bfi_b32 v150, v146, v40, v16
	v_bfi_b32 v151, v146, v41, v17
	s_cmp_eq_u32 s100, 1
	s_cselect_b64 s[100:101], vcc, 0
	s_andn2_b64 exec, exec, s[100:101]
	global_store_dwordx4 v42, v[148:151], s[14:15] sc1
	s_mov_b64 exec, -1
	s_nop 1
	s_branch .LBB0_1215

.LBB0_1284:
	ds_read_b128 v[148:151], v145
	ds_read_b128 v[152:155], v145 offset:1024
	ds_read_b128 v[156:159], v145 offset:2048
	ds_read_b128 v[160:163], v145 offset:3072
	s_add_u32 s14, s12, 0x100
	s_addc_u32 s15, s13, 0
	s_cmp_eq_u32 s44, 40
	s_cselect_b32 s19, s9, s15
	s_cselect_b32 s18, s8, s14
	s_cselect_b32 s17, s1, s43
	s_cselect_b32 s16, s0, s42
	s_mov_b32 m0, s35
	v_lshl_add_u64 v[168:169], s[12:13], 0, v[136:137]
	ds_read_b128 v[164:167], v146
	ds_read_b128 v[172:175], v146 offset:1024
	ds_read_b128 v[176:179], v146 offset:2048
	ds_read_b128 v[180:183], v146 offset:3072
	ds_read_b128 v[184:187], v146 offset:4096
	ds_read_b128 v[188:191], v146 offset:5120
	ds_read_b128 v[192:195], v146 offset:6144
	ds_read_b128 v[196:199], v146 offset:7168
	global_load_lds_dwordx4 v[168:169], off
	v_lshl_add_u64 v[168:169], s[12:13], 0, v[134:135]
	s_mov_b32 m0, s36
	s_nop 0
	global_load_lds_dwordx4 v[168:169], off
	s_waitcnt lgkmcnt(8)
	s_barrier
	s_waitcnt lgkmcnt(0)
	s_setprio 1
	s_waitcnt lgkmcnt(0)
	v_mfma_f32_16x16x32_bf16 v[124:127], v[148:151], v[164:167], v[124:127]
	v_mfma_f32_16x16x32_bf16 v[120:123], v[156:159], v[164:167], v[120:123]
	v_mfma_f32_16x16x32_bf16 v[116:119], v[148:151], v[176:179], v[116:119]
	v_mfma_f32_16x16x32_bf16 v[108:111], v[156:159], v[176:179], v[108:111]
	v_mfma_f32_16x16x32_bf16 v[100:103], v[148:151], v[184:187], v[100:103]
	v_mfma_f32_16x16x32_bf16 v[92:95], v[156:159], v[184:187], v[92:95]
	v_mfma_f32_16x16x32_bf16 v[84:87], v[148:151], v[192:195], v[84:87]
	v_mfma_f32_16x16x32_bf16 v[76:79], v[156:159], v[192:195], v[76:79]
	v_mfma_f32_16x16x32_bf16 v[124:127], v[152:155], v[172:175], v[124:127]
	v_mfma_f32_16x16x32_bf16 v[120:123], v[160:163], v[172:175], v[120:123]
	v_mfma_f32_16x16x32_bf16 v[116:119], v[152:155], v[180:183], v[116:119]
	v_mfma_f32_16x16x32_bf16 v[108:111], v[160:163], v[180:183], v[108:111]
	v_mfma_f32_16x16x32_bf16 v[100:103], v[152:155], v[188:191], v[100:103]
	v_mfma_f32_16x16x32_bf16 v[92:95], v[160:163], v[188:191], v[92:95]
	v_mfma_f32_16x16x32_bf16 v[84:87], v[152:155], v[196:199], v[84:87]
	v_mfma_f32_16x16x32_bf16 v[76:79], v[160:163], v[196:199], v[76:79]
	s_setprio 0
	s_barrier
	s_add_i32 s12, s33, s25
	v_lshl_add_u64 v[168:169], s[16:17], 0, v[130:131]
	s_mov_b32 m0, s12
	ds_read_b128 v[200:203], v147
	ds_read_b128 v[204:207], v147 offset:1024
	ds_read_b128 v[208:211], v147 offset:2048
	ds_read_b128 v[212:215], v147 offset:3072
	global_load_lds_dwordx4 v[168:169], off
	v_lshl_add_u64 v[216:217], s[16:17], 0, v[128:129]
	s_add_i32 m0, s12, 0x2000
	s_nop 0
	global_load_lds_dwordx4 v[216:217], off
	s_barrier
	s_waitcnt lgkmcnt(0)
	s_setprio 1
	s_waitcnt lgkmcnt(0)
	v_mfma_f32_16x16x32_bf16 v[112:115], v[200:203], v[164:167], v[112:115]
	v_mfma_f32_16x16x32_bf16 v[104:107], v[208:211], v[164:167], v[104:107]
	v_mfma_f32_16x16x32_bf16 v[96:99], v[200:203], v[176:179], v[96:99]
	v_mfma_f32_16x16x32_bf16 v[88:91], v[208:211], v[176:179], v[88:91]
	v_mfma_f32_16x16x32_bf16 v[80:83], v[200:203], v[184:187], v[80:83]
	v_mfma_f32_16x16x32_bf16 v[72:75], v[208:211], v[184:187], v[72:75]
	v_mfma_f32_16x16x32_bf16 v[68:71], v[200:203], v[192:195], v[68:71]
	v_mfma_f32_16x16x32_bf16 v[64:67], v[208:211], v[192:195], v[64:67]
	v_mfma_f32_16x16x32_bf16 v[112:115], v[204:207], v[172:175], v[112:115]
	v_mfma_f32_16x16x32_bf16 v[104:107], v[212:215], v[172:175], v[104:107]
	v_mfma_f32_16x16x32_bf16 v[96:99], v[204:207], v[180:183], v[96:99]
	v_mfma_f32_16x16x32_bf16 v[88:91], v[212:215], v[180:183], v[88:91]
	v_mfma_f32_16x16x32_bf16 v[80:83], v[204:207], v[188:191], v[80:83]
	v_mfma_f32_16x16x32_bf16 v[72:75], v[212:215], v[188:191], v[72:75]
	v_mfma_f32_16x16x32_bf16 v[68:71], v[204:207], v[196:199], v[68:71]
	v_mfma_f32_16x16x32_bf16 v[64:67], v[212:215], v[196:199], v[64:67]
	s_setprio 0
	s_mov_b32 m0, s26
	v_lshl_add_u64 v[218:219], s[18:19], 0, v[130:131]
	s_barrier
	ds_read_b128 v[164:167], v146 offset:16384
	ds_read_b128 v[172:175], v146 offset:17408
	ds_read_b128 v[176:179], v146 offset:18432
	ds_read_b128 v[180:183], v146 offset:19456
	ds_read_b128 v[184:187], v146 offset:20480
	ds_read_b128 v[188:191], v146 offset:21504
	ds_read_b128 v[192:195], v146 offset:22528
	ds_read_b128 v[196:199], v146 offset:23552
	global_load_lds_dwordx4 v[218:219], off
	v_lshl_add_u64 v[220:221], s[18:19], 0, v[128:129]
	s_mov_b32 m0, s27
	s_nop 0
	global_load_lds_dwordx4 v[220:221], off
	s_barrier
	s_waitcnt lgkmcnt(0)
	s_setprio 1
	s_waitcnt lgkmcnt(0)
	v_mfma_f32_16x16x32_bf16 v[60:63], v[148:151], v[164:167], v[60:63]
	v_mfma_f32_16x16x32_bf16 v[56:59], v[156:159], v[164:167], v[56:59]
	v_mfma_f32_16x16x32_bf16 v[52:55], v[148:151], v[176:179], v[52:55]
	v_mfma_f32_16x16x32_bf16 v[44:47], v[156:159], v[176:179], v[44:47]
	v_mfma_f32_16x16x32_bf16 v[36:39], v[148:151], v[184:187], v[36:39]
	v_mfma_f32_16x16x32_bf16 v[28:31], v[156:159], v[184:187], v[28:31]
	v_mfma_f32_16x16x32_bf16 v[20:23], v[148:151], v[192:195], v[20:23]
	v_mfma_f32_16x16x32_bf16 v[12:15], v[156:159], v[192:195], v[12:15]
	v_mfma_f32_16x16x32_bf16 v[60:63], v[152:155], v[172:175], v[60:63]
	v_mfma_f32_16x16x32_bf16 v[56:59], v[160:163], v[172:175], v[56:59]
	v_mfma_f32_16x16x32_bf16 v[52:55], v[152:155], v[180:183], v[52:55]
	v_mfma_f32_16x16x32_bf16 v[44:47], v[160:163], v[180:183], v[44:47]
	v_mfma_f32_16x16x32_bf16 v[36:39], v[152:155], v[188:191], v[36:39]
	v_mfma_f32_16x16x32_bf16 v[28:31], v[160:163], v[188:191], v[28:31]
	v_mfma_f32_16x16x32_bf16 v[20:23], v[152:155], v[196:199], v[20:23]
	v_mfma_f32_16x16x32_bf16 v[12:15], v[160:163], v[196:199], v[12:15]
	s_setprio 0
	s_barrier
	s_add_u32 s12, s16, 0xb0000
	s_addc_u32 s13, s17, 0
	s_add_i32 s45, s34, s25
	v_lshl_add_u64 v[148:149], s[12:13], 0, v[130:131]
	s_mov_b32 m0, s45
	s_nop 0
	global_load_lds_dwordx4 v[148:149], off
	v_lshl_add_u64 v[148:149], s[12:13], 0, v[128:129]
	s_add_i32 m0, s45, 0x2000
	s_nop 0
	global_load_lds_dwordx4 v[148:149], off
	s_waitcnt vmcnt(6)
	s_barrier
	s_setprio 1
	v_mfma_f32_16x16x32_bf16 v[48:51], v[200:203], v[164:167], v[48:51]
	v_mfma_f32_16x16x32_bf16 v[40:43], v[208:211], v[164:167], v[40:43]
	v_mfma_f32_16x16x32_bf16 v[32:35], v[200:203], v[176:179], v[32:35]
	v_mfma_f32_16x16x32_bf16 v[24:27], v[208:211], v[176:179], v[24:27]
	v_mfma_f32_16x16x32_bf16 v[16:19], v[200:203], v[184:187], v[16:19]
	v_mfma_f32_16x16x32_bf16 v[8:11], v[208:211], v[184:187], v[8:11]
	v_mfma_f32_16x16x32_bf16 v[4:7], v[200:203], v[192:195], v[4:7]
	v_mfma_f32_16x16x32_bf16 v[0:3], v[208:211], v[192:195], v[0:3]
	v_mfma_f32_16x16x32_bf16 v[48:51], v[204:207], v[172:175], v[48:51]
	v_mfma_f32_16x16x32_bf16 v[40:43], v[212:215], v[172:175], v[40:43]
	v_mfma_f32_16x16x32_bf16 v[32:35], v[204:207], v[180:183], v[32:35]
	v_mfma_f32_16x16x32_bf16 v[24:27], v[212:215], v[180:183], v[24:27]
	v_mfma_f32_16x16x32_bf16 v[16:19], v[204:207], v[188:191], v[16:19]
	v_mfma_f32_16x16x32_bf16 v[8:11], v[212:215], v[188:191], v[8:11]
	v_mfma_f32_16x16x32_bf16 v[4:7], v[204:207], v[196:199], v[4:7]
	v_mfma_f32_16x16x32_bf16 v[0:3], v[212:215], v[196:199], v[0:3]
	s_setprio 0
	s_add_i32 s45, 0, 0x18000
	v_add_u32_e32 v160, s45, v144
	s_barrier
	ds_read_b128 v[148:151], v160
	ds_read_b128 v[152:155], v160 offset:1024
	ds_read_b128 v[156:159], v160 offset:2048
	ds_read_b128 v[160:163], v160 offset:3072
	s_add_u32 s12, s18, 0xb0000
	s_addc_u32 s13, s19, 0
	s_mov_b32 m0, s28
	v_lshl_add_u64 v[200:201], s[12:13], 0, v[130:131]
	ds_read_b128 v[164:167], v146 offset:32768
	ds_read_b128 v[172:175], v146 offset:33792
	ds_read_b128 v[176:179], v146 offset:34816
	ds_read_b128 v[180:183], v146 offset:35840
	ds_read_b128 v[184:187], v146 offset:36864
	ds_read_b128 v[188:191], v146 offset:37888
	ds_read_b128 v[192:195], v146 offset:38912
	ds_read_b128 v[196:199], v146 offset:39936
	global_load_lds_dwordx4 v[200:201], off
	v_lshl_add_u64 v[200:201], s[12:13], 0, v[128:129]
	s_mov_b32 m0, s29
	s_nop 0
	global_load_lds_dwordx4 v[200:201], off
	s_waitcnt lgkmcnt(8)
	s_barrier
	s_waitcnt lgkmcnt(0)
	s_setprio 1
	s_waitcnt lgkmcnt(0)
	v_mfma_f32_16x16x32_bf16 v[124:127], v[148:151], v[164:167], v[124:127]
	v_mfma_f32_16x16x32_bf16 v[120:123], v[156:159], v[164:167], v[120:123]
	v_mfma_f32_16x16x32_bf16 v[116:119], v[148:151], v[176:179], v[116:119]
	v_mfma_f32_16x16x32_bf16 v[108:111], v[156:159], v[176:179], v[108:111]
	v_mfma_f32_16x16x32_bf16 v[100:103], v[148:151], v[184:187], v[100:103]
	v_mfma_f32_16x16x32_bf16 v[92:95], v[156:159], v[184:187], v[92:95]
	v_mfma_f32_16x16x32_bf16 v[84:87], v[148:151], v[192:195], v[84:87]
	v_mfma_f32_16x16x32_bf16 v[76:79], v[156:159], v[192:195], v[76:79]
	v_mfma_f32_16x16x32_bf16 v[124:127], v[152:155], v[172:175], v[124:127]
	v_mfma_f32_16x16x32_bf16 v[120:123], v[160:163], v[172:175], v[120:123]
	v_mfma_f32_16x16x32_bf16 v[116:119], v[152:155], v[180:183], v[116:119]
	v_mfma_f32_16x16x32_bf16 v[108:111], v[160:163], v[180:183], v[108:111]
	v_mfma_f32_16x16x32_bf16 v[100:103], v[152:155], v[188:191], v[100:103]
	v_mfma_f32_16x16x32_bf16 v[92:95], v[160:163], v[188:191], v[92:95]
	v_mfma_f32_16x16x32_bf16 v[84:87], v[152:155], v[196:199], v[84:87]
	v_mfma_f32_16x16x32_bf16 v[76:79], v[160:163], v[196:199], v[76:79]
	s_setprio 0
	s_barrier
	s_add_i32 s18, 0, 0x1c000
	s_add_i32 s12, s45, s25
	v_add_u32_e32 v171, s18, v144
	v_lshl_add_u64 v[168:169], v[168:169], 0, s[10:11]
	s_mov_b32 m0, s12
	ds_read_b128 v[200:203], v171
	ds_read_b128 v[204:207], v171 offset:1024
	ds_read_b128 v[208:211], v171 offset:2048
	ds_read_b128 v[212:215], v171 offset:3072
	global_load_lds_dwordx4 v[168:169], off
	v_lshl_add_u64 v[168:169], v[216:217], 0, s[10:11]
	s_add_i32 m0, s12, 0x2000
	s_nop 0
	global_load_lds_dwordx4 v[168:169], off
	s_barrier
	s_waitcnt lgkmcnt(0)
	s_setprio 1
	s_waitcnt lgkmcnt(0)
	v_mfma_f32_16x16x32_bf16 v[112:115], v[200:203], v[164:167], v[112:115]
	v_mfma_f32_16x16x32_bf16 v[104:107], v[208:211], v[164:167], v[104:107]
	v_mfma_f32_16x16x32_bf16 v[96:99], v[200:203], v[176:179], v[96:99]
	v_mfma_f32_16x16x32_bf16 v[88:91], v[208:211], v[176:179], v[88:91]
	v_mfma_f32_16x16x32_bf16 v[80:83], v[200:203], v[184:187], v[80:83]
	v_mfma_f32_16x16x32_bf16 v[72:75], v[208:211], v[184:187], v[72:75]
	v_mfma_f32_16x16x32_bf16 v[68:71], v[200:203], v[192:195], v[68:71]
	v_mfma_f32_16x16x32_bf16 v[64:67], v[208:211], v[192:195], v[64:67]
	v_mfma_f32_16x16x32_bf16 v[112:115], v[204:207], v[172:175], v[112:115]
	v_mfma_f32_16x16x32_bf16 v[104:107], v[212:215], v[172:175], v[104:107]
	v_mfma_f32_16x16x32_bf16 v[96:99], v[204:207], v[180:183], v[96:99]
	v_mfma_f32_16x16x32_bf16 v[88:91], v[212:215], v[180:183], v[88:91]
	v_mfma_f32_16x16x32_bf16 v[80:83], v[204:207], v[188:191], v[80:83]
	v_mfma_f32_16x16x32_bf16 v[72:75], v[212:215], v[188:191], v[72:75]
	v_mfma_f32_16x16x32_bf16 v[68:71], v[204:207], v[196:199], v[68:71]
	v_mfma_f32_16x16x32_bf16 v[64:67], v[212:215], v[196:199], v[64:67]
	s_setprio 0
	s_mov_b32 m0, s30
	v_lshl_add_u64 v[168:169], v[218:219], 0, s[10:11]
	s_barrier
	ds_read_b128 v[164:167], v146 offset:49152
	ds_read_b128 v[172:175], v146 offset:50176
	ds_read_b128 v[176:179], v146 offset:51200
	ds_read_b128 v[180:183], v146 offset:52224
	ds_read_b128 v[184:187], v146 offset:53248
	ds_read_b128 v[188:191], v146 offset:54272
	ds_read_b128 v[192:195], v146 offset:55296
	ds_read_b128 v[196:199], v146 offset:56320
	global_load_lds_dwordx4 v[168:169], off
	v_lshl_add_u64 v[168:169], v[220:221], 0, s[10:11]
	s_mov_b32 m0, s31
	s_nop 0
	global_load_lds_dwordx4 v[168:169], off
	s_barrier
	s_waitcnt lgkmcnt(0)
	s_setprio 1
	s_waitcnt lgkmcnt(0)
	v_mfma_f32_16x16x32_bf16 v[60:63], v[148:151], v[164:167], v[60:63]
	v_mfma_f32_16x16x32_bf16 v[56:59], v[156:159], v[164:167], v[56:59]
	v_mfma_f32_16x16x32_bf16 v[52:55], v[148:151], v[176:179], v[52:55]
	v_mfma_f32_16x16x32_bf16 v[44:47], v[156:159], v[176:179], v[44:47]
	v_mfma_f32_16x16x32_bf16 v[36:39], v[148:151], v[184:187], v[36:39]
	v_mfma_f32_16x16x32_bf16 v[28:31], v[156:159], v[184:187], v[28:31]
	v_mfma_f32_16x16x32_bf16 v[20:23], v[148:151], v[192:195], v[20:23]
	v_mfma_f32_16x16x32_bf16 v[12:15], v[156:159], v[192:195], v[12:15]
	v_mfma_f32_16x16x32_bf16 v[60:63], v[152:155], v[172:175], v[60:63]
	v_mfma_f32_16x16x32_bf16 v[56:59], v[160:163], v[172:175], v[56:59]
	v_mfma_f32_16x16x32_bf16 v[52:55], v[152:155], v[180:183], v[52:55]
	v_mfma_f32_16x16x32_bf16 v[44:47], v[160:163], v[180:183], v[44:47]
	v_mfma_f32_16x16x32_bf16 v[36:39], v[152:155], v[188:191], v[36:39]
	v_mfma_f32_16x16x32_bf16 v[28:31], v[160:163], v[188:191], v[28:31]
	v_mfma_f32_16x16x32_bf16 v[20:23], v[152:155], v[196:199], v[20:23]
	v_mfma_f32_16x16x32_bf16 v[12:15], v[160:163], v[196:199], v[12:15]
	s_setprio 0
	s_barrier
	s_add_u32 s12, s16, 0xb0080
	s_addc_u32 s13, s17, 0
	s_add_i32 s16, s18, s25
	v_lshl_add_u64 v[148:149], s[12:13], 0, v[130:131]
	s_mov_b32 m0, s16
	s_nop 0
	global_load_lds_dwordx4 v[148:149], off
	v_lshl_add_u64 v[148:149], s[12:13], 0, v[128:129]
	s_add_i32 m0, s16, 0x2000
	s_nop 0
	global_load_lds_dwordx4 v[148:149], off
	s_waitcnt vmcnt(6)
	s_barrier
	s_setprio 1
	v_mfma_f32_16x16x32_bf16 v[48:51], v[200:203], v[164:167], v[48:51]
	v_mfma_f32_16x16x32_bf16 v[40:43], v[208:211], v[164:167], v[40:43]
	v_mfma_f32_16x16x32_bf16 v[32:35], v[200:203], v[176:179], v[32:35]
	v_mfma_f32_16x16x32_bf16 v[24:27], v[208:211], v[176:179], v[24:27]
	v_mfma_f32_16x16x32_bf16 v[16:19], v[200:203], v[184:187], v[16:19]
	v_mfma_f32_16x16x32_bf16 v[8:11], v[208:211], v[184:187], v[8:11]
	v_mfma_f32_16x16x32_bf16 v[4:7], v[200:203], v[192:195], v[4:7]
	v_mfma_f32_16x16x32_bf16 v[0:3], v[208:211], v[192:195], v[0:3]
	v_mfma_f32_16x16x32_bf16 v[48:51], v[204:207], v[172:175], v[48:51]
	v_mfma_f32_16x16x32_bf16 v[40:43], v[212:215], v[172:175], v[40:43]
	v_mfma_f32_16x16x32_bf16 v[32:35], v[204:207], v[180:183], v[32:35]
	v_mfma_f32_16x16x32_bf16 v[24:27], v[212:215], v[180:183], v[24:27]
	v_mfma_f32_16x16x32_bf16 v[16:19], v[204:207], v[188:191], v[16:19]
	v_mfma_f32_16x16x32_bf16 v[8:11], v[212:215], v[188:191], v[8:11]
	v_mfma_f32_16x16x32_bf16 v[4:7], v[204:207], v[196:199], v[4:7]
	v_mfma_f32_16x16x32_bf16 v[0:3], v[212:215], v[196:199], v[0:3]
	s_setprio 0
	s_add_i32 s44, s44, 2
	s_add_u32 s42, s42, 0x100
	s_addc_u32 s43, s43, 0
	s_cmp_gt_u32 s44, 41
	s_mov_b64 s[12:13], s[14:15]
	s_barrier
	s_cbranch_scc0 .LBB0_1284
	v_lshl_add_u32 v148, s41, 8, v143
	s_lshl_b32 s12, s40, 8
	v_ashrrev_i32_e32 v149, 31, v148
	s_ashr_i32 s13, s12, 31
	v_lshlrev_b64 v[150:151], 11, v[148:149]
	v_lshl_add_u64 v[150:151], s[4:5], 0, v[150:151]
	s_lshl_b64 s[12:13], s[12:13], 1
	v_lshl_add_u64 v[150:151], v[150:151], 0, s[12:13]
	v_lshl_add_u64 v[150:151], v[150:151], 0, s[2:3]
	v_lshl_add_u64 v[150:151], v[150:151], 0, v[132:133]
	v_mbcnt_lo_u32_b32 v237, -1, 0
	v_mbcnt_hi_u32_b32 v237, -1, v237
	v_bfe_i32 v237, v237, 4, 1
	v_and_b32_e32 v244, 24, v237
	v_add_co_u32_e32 v248, vcc, v244, v150
	s_nop 1
	v_addc_co_u32_e32 v249, vcc, 0, v151, vcc
	v_cvt_pk_bf16_f32 v124, v124, v125
	v_cvt_pk_bf16_f32 v125, v126, v127
	v_cvt_pk_bf16_f32 v120, v120, v121
	v_cvt_pk_bf16_f32 v121, v122, v123
	v_bfi_b32 v244, v237, v124, v120
	v_bfi_b32 v245, v237, v125, v121
	ds_swizzle_b32 v250, v244 offset:0x401f
	ds_swizzle_b32 v251, v245 offset:0x401f
	v_cvt_pk_bf16_f32 v112, v112, v113
	v_cvt_pk_bf16_f32 v113, v114, v115
	v_cvt_pk_bf16_f32 v104, v104, v105
	v_cvt_pk_bf16_f32 v105, v106, v107
	v_bfi_b32 v246, v237, v112, v104
	v_bfi_b32 v247, v237, v113, v105
	ds_swizzle_b32 v252, v246 offset:0x401f
	ds_swizzle_b32 v253, v247 offset:0x401f
	s_waitcnt lgkmcnt(0)
	v_bfi_b32 v240, v237, v250, v124
	v_bfi_b32 v241, v237, v251, v125
	v_bfi_b32 v242, v237, v120, v250
	v_bfi_b32 v243, v237, v121, v251
	global_store_dwordx4 v[248:249], v[240:243], off sc1
	s_nop 1
	v_bfi_b32 v240, v237, v252, v112
	v_bfi_b32 v241, v237, v253, v113
	v_bfi_b32 v242, v237, v104, v252
	v_bfi_b32 v243, v237, v105, v253
	global_store_dwordx4 v[248:249], v[240:243], off offset:256 sc1
	s_nop 1
	v_add_co_u32_e32 v238, vcc, 0x8000, v248
	s_nop 1
	v_addc_co_u32_e32 v239, vcc, 0, v249, vcc
	v_cvt_pk_bf16_f32 v116, v116, v117
	v_cvt_pk_bf16_f32 v117, v118, v119
	v_cvt_pk_bf16_f32 v108, v108, v109
	v_cvt_pk_bf16_f32 v109, v110, v111
	v_bfi_b32 v244, v237, v116, v108
	v_bfi_b32 v245, v237, v117, v109
	ds_swizzle_b32 v250, v244 offset:0x401f
	ds_swizzle_b32 v251, v245 offset:0x401f
	v_cvt_pk_bf16_f32 v96, v96, v97
	v_cvt_pk_bf16_f32 v97, v98, v99
	v_cvt_pk_bf16_f32 v88, v88, v89
	v_cvt_pk_bf16_f32 v89, v90, v91
	v_bfi_b32 v246, v237, v96, v88
	v_bfi_b32 v247, v237, v97, v89
	ds_swizzle_b32 v252, v246 offset:0x401f
	ds_swizzle_b32 v253, v247 offset:0x401f
	s_waitcnt lgkmcnt(0)
	v_bfi_b32 v240, v237, v250, v116
	v_bfi_b32 v241, v237, v251, v117
	v_bfi_b32 v242, v237, v108, v250
	v_bfi_b32 v243, v237, v109, v251
	global_store_dwordx4 v[238:239], v[240:243], off sc1
	s_nop 1
	v_bfi_b32 v240, v237, v252, v96
	v_bfi_b32 v241, v237, v253, v97
	v_bfi_b32 v242, v237, v88, v252
	v_bfi_b32 v243, v237, v89, v253
	global_store_dwordx4 v[238:239], v[240:243], off offset:256 sc1
	s_nop 1
	v_add_co_u32_e32 v238, vcc, 0x10000, v248
	s_nop 1
	v_addc_co_u32_e32 v239, vcc, 0, v249, vcc
	v_cvt_pk_bf16_f32 v100, v100, v101
	v_cvt_pk_bf16_f32 v101, v102, v103
	v_cvt_pk_bf16_f32 v92, v92, v93
	v_cvt_pk_bf16_f32 v93, v94, v95
	v_bfi_b32 v244, v237, v100, v92
	v_bfi_b32 v245, v237, v101, v93
	ds_swizzle_b32 v250, v244 offset:0x401f
	ds_swizzle_b32 v251, v245 offset:0x401f
	v_cvt_pk_bf16_f32 v80, v80, v81
	v_cvt_pk_bf16_f32 v81, v82, v83
	v_cvt_pk_bf16_f32 v72, v72, v73
	v_cvt_pk_bf16_f32 v73, v74, v75
	v_bfi_b32 v246, v237, v80, v72
	v_bfi_b32 v247, v237, v81, v73
	ds_swizzle_b32 v252, v246 offset:0x401f
	ds_swizzle_b32 v253, v247 offset:0x401f
	s_waitcnt lgkmcnt(0)
	v_bfi_b32 v240, v237, v250, v100
	v_bfi_b32 v241, v237, v251, v101
	v_bfi_b32 v242, v237, v92, v250
	v_bfi_b32 v243, v237, v93, v251
	global_store_dwordx4 v[238:239], v[240:243], off sc1
	s_nop 1
	v_bfi_b32 v240, v237, v252, v80
	v_bfi_b32 v241, v237, v253, v81
	v_bfi_b32 v242, v237, v72, v252
	v_bfi_b32 v243, v237, v73, v253
	global_store_dwordx4 v[238:239], v[240:243], off offset:256 sc1
	s_nop 1
	v_add_co_u32_e32 v238, vcc, 0x18000, v248
	s_nop 1
	v_addc_co_u32_e32 v239, vcc, 0, v249, vcc
	v_cvt_pk_bf16_f32 v84, v84, v85
	v_cvt_pk_bf16_f32 v85, v86, v87
	v_cvt_pk_bf16_f32 v76, v76, v77
	v_cvt_pk_bf16_f32 v77, v78, v79
	v_bfi_b32 v244, v237, v84, v76
	v_bfi_b32 v245, v237, v85, v77
	ds_swizzle_b32 v250, v244 offset:0x401f
	ds_swizzle_b32 v251, v245 offset:0x401f
	v_cvt_pk_bf16_f32 v68, v68, v69
	v_cvt_pk_bf16_f32 v69, v70, v71
	v_cvt_pk_bf16_f32 v64, v64, v65
	v_cvt_pk_bf16_f32 v65, v66, v67
	v_bfi_b32 v246, v237, v68, v64
	v_bfi_b32 v247, v237, v69, v65
	ds_swizzle_b32 v252, v246 offset:0x401f
	ds_swizzle_b32 v253, v247 offset:0x401f
	s_waitcnt lgkmcnt(0)
	v_bfi_b32 v240, v237, v250, v84
	v_bfi_b32 v241, v237, v251, v85
	v_bfi_b32 v242, v237, v76, v250
	v_bfi_b32 v243, v237, v77, v251
	global_store_dwordx4 v[238:239], v[240:243], off sc1
	s_nop 1
	v_bfi_b32 v240, v237, v252, v68
	v_bfi_b32 v241, v237, v253, v69
	v_bfi_b32 v242, v237, v64, v252
	v_bfi_b32 v243, v237, v65, v253
	global_store_dwordx4 v[238:239], v[240:243], off offset:256 sc1
	s_nop 1
	v_add_co_u32_e32 v238, vcc, 0x40000, v248
	s_nop 1
	v_addc_co_u32_e32 v239, vcc, 0, v249, vcc
	v_cvt_pk_bf16_f32 v60, v60, v61
	v_cvt_pk_bf16_f32 v61, v62, v63
	v_cvt_pk_bf16_f32 v56, v56, v57
	v_cvt_pk_bf16_f32 v57, v58, v59
	v_bfi_b32 v244, v237, v60, v56
	v_bfi_b32 v245, v237, v61, v57
	ds_swizzle_b32 v250, v244 offset:0x401f
	ds_swizzle_b32 v251, v245 offset:0x401f
	v_cvt_pk_bf16_f32 v48, v48, v49
	v_cvt_pk_bf16_f32 v49, v50, v51
	v_cvt_pk_bf16_f32 v40, v40, v41
	v_cvt_pk_bf16_f32 v41, v42, v43
	v_bfi_b32 v246, v237, v48, v40
	v_bfi_b32 v247, v237, v49, v41
	ds_swizzle_b32 v252, v246 offset:0x401f
	ds_swizzle_b32 v253, v247 offset:0x401f
	s_waitcnt lgkmcnt(0)
	v_bfi_b32 v240, v237, v250, v60
	v_bfi_b32 v241, v237, v251, v61
	v_bfi_b32 v242, v237, v56, v250
	v_bfi_b32 v243, v237, v57, v251
	global_store_dwordx4 v[238:239], v[240:243], off sc1
	s_nop 1
	v_bfi_b32 v240, v237, v252, v48
	v_bfi_b32 v241, v237, v253, v49
	v_bfi_b32 v242, v237, v40, v252
	v_bfi_b32 v243, v237, v41, v253
	global_store_dwordx4 v[238:239], v[240:243], off offset:256 sc1
	s_nop 1
	v_add_co_u32_e32 v238, vcc, 0x48000, v248
	s_nop 1
	v_addc_co_u32_e32 v239, vcc, 0, v249, vcc
	v_cvt_pk_bf16_f32 v52, v52, v53
	v_cvt_pk_bf16_f32 v53, v54, v55
	v_cvt_pk_bf16_f32 v44, v44, v45
	v_cvt_pk_bf16_f32 v45, v46, v47
	v_bfi_b32 v244, v237, v52, v44
	v_bfi_b32 v245, v237, v53, v45
	ds_swizzle_b32 v250, v244 offset:0x401f
	ds_swizzle_b32 v251, v245 offset:0x401f
	v_cvt_pk_bf16_f32 v32, v32, v33
	v_cvt_pk_bf16_f32 v33, v34, v35
	v_cvt_pk_bf16_f32 v24, v24, v25
	v_cvt_pk_bf16_f32 v25, v26, v27
	v_bfi_b32 v246, v237, v32, v24
	v_bfi_b32 v247, v237, v33, v25
	ds_swizzle_b32 v252, v246 offset:0x401f
	ds_swizzle_b32 v253, v247 offset:0x401f
	s_waitcnt lgkmcnt(0)
	v_bfi_b32 v240, v237, v250, v52
	v_bfi_b32 v241, v237, v251, v53
	v_bfi_b32 v242, v237, v44, v250
	v_bfi_b32 v243, v237, v45, v251
	global_store_dwordx4 v[238:239], v[240:243], off sc1
	s_nop 1
	v_bfi_b32 v240, v237, v252, v32
	v_bfi_b32 v241, v237, v253, v33
	v_bfi_b32 v242, v237, v24, v252
	v_bfi_b32 v243, v237, v25, v253
	global_store_dwordx4 v[238:239], v[240:243], off offset:256 sc1
	s_nop 1
	v_add_co_u32_e32 v238, vcc, 0x50000, v248
	s_nop 1
	v_addc_co_u32_e32 v239, vcc, 0, v249, vcc
	v_cvt_pk_bf16_f32 v36, v36, v37
	v_cvt_pk_bf16_f32 v37, v38, v39
	v_cvt_pk_bf16_f32 v28, v28, v29
	v_cvt_pk_bf16_f32 v29, v30, v31
	v_bfi_b32 v244, v237, v36, v28
	v_bfi_b32 v245, v237, v37, v29
	ds_swizzle_b32 v250, v244 offset:0x401f
	ds_swizzle_b32 v251, v245 offset:0x401f
	v_cvt_pk_bf16_f32 v16, v16, v17
	v_cvt_pk_bf16_f32 v17, v18, v19
	v_cvt_pk_bf16_f32 v8, v8, v9
	v_cvt_pk_bf16_f32 v9, v10, v11
	v_bfi_b32 v246, v237, v16, v8
	v_bfi_b32 v247, v237, v17, v9
	ds_swizzle_b32 v252, v246 offset:0x401f
	ds_swizzle_b32 v253, v247 offset:0x401f
	s_waitcnt lgkmcnt(0)
	v_bfi_b32 v240, v237, v250, v36
	v_bfi_b32 v241, v237, v251, v37
	v_bfi_b32 v242, v237, v28, v250
	v_bfi_b32 v243, v237, v29, v251
	global_store_dwordx4 v[238:239], v[240:243], off sc1
	s_nop 1
	v_bfi_b32 v240, v237, v252, v16
	v_bfi_b32 v241, v237, v253, v17
	v_bfi_b32 v242, v237, v8, v252
	v_bfi_b32 v243, v237, v9, v253
	global_store_dwordx4 v[238:239], v[240:243], off offset:256 sc1
	s_nop 1
	v_add_co_u32_e32 v238, vcc, 0x58000, v248
	s_nop 1
	v_addc_co_u32_e32 v239, vcc, 0, v249, vcc
	v_cvt_pk_bf16_f32 v20, v20, v21
	v_cvt_pk_bf16_f32 v21, v22, v23
	v_cvt_pk_bf16_f32 v12, v12, v13
	v_cvt_pk_bf16_f32 v13, v14, v15
	v_bfi_b32 v244, v237, v20, v12
	v_bfi_b32 v245, v237, v21, v13
	ds_swizzle_b32 v250, v244 offset:0x401f
	ds_swizzle_b32 v251, v245 offset:0x401f
	v_cvt_pk_bf16_f32 v4, v4, v5
	v_cvt_pk_bf16_f32 v5, v6, v7
	v_cvt_pk_bf16_f32 v0, v0, v1
	v_cvt_pk_bf16_f32 v1, v2, v3
	v_bfi_b32 v246, v237, v4, v0
	v_bfi_b32 v247, v237, v5, v1
	ds_swizzle_b32 v252, v246 offset:0x401f
	ds_swizzle_b32 v253, v247 offset:0x401f
	s_waitcnt lgkmcnt(0)
	v_bfi_b32 v240, v237, v250, v20
	v_bfi_b32 v241, v237, v251, v21
	v_bfi_b32 v242, v237, v12, v250
	v_bfi_b32 v243, v237, v13, v251
	global_store_dwordx4 v[238:239], v[240:243], off sc1
	s_nop 1
	v_bfi_b32 v240, v237, v252, v4
	v_bfi_b32 v241, v237, v253, v5
	v_bfi_b32 v242, v237, v0, v252
	v_bfi_b32 v243, v237, v1, v253
	global_store_dwordx4 v[238:239], v[240:243], off offset:256 sc1
	s_nop 1
	s_and_b64 vcc, exec, s[6:7]
	s_mov_b32 s40, s38
	s_mov_b32 s41, s39
	s_mov_b64 s[14:15], s[0:1]
	s_mov_b64 s[12:13], s[8:9]
	s_cbranch_vccz .LBB0_1277
	s_waitcnt vmcnt(0)
	s_cmpk_gt_u32 s20, 0xff
	s_cbranch_scc1 .LBB0_1288
	s_barrier

.LBB0_2046:
	ds_read_b128 v[152:155], v149
	ds_read_b128 v[156:159], v149 offset:1024
	ds_read_b128 v[160:163], v149 offset:2048
	ds_read_b128 v[164:167], v149 offset:3072
	s_add_u32 s8, s16, 0x100
	s_addc_u32 s9, s17, 0
	s_cmp_eq_u32 s45, 12
	s_cselect_b32 s21, s13, s9
	s_cselect_b32 s20, s12, s8
	s_cselect_b32 s19, s11, s44
	s_cselect_b32 s18, s42, s43
	v_lshl_add_u64 v[168:169], s[16:17], 0, v[140:141]
	s_add_i32 m0, s28, 0xc000
	ds_read_b128 v[172:175], v150
	ds_read_b128 v[176:179], v150 offset:1024
	ds_read_b128 v[180:183], v150 offset:2048
	ds_read_b128 v[184:187], v150 offset:3072
	ds_read_b128 v[188:191], v150 offset:4096
	ds_read_b128 v[192:195], v150 offset:5120
	ds_read_b128 v[196:199], v150 offset:6144
	ds_read_b128 v[200:203], v150 offset:7168
	global_load_lds_dwordx4 v[168:169], off
	v_lshl_add_u64 v[168:169], s[16:17], 0, v[138:139]
	s_add_i32 m0, s28, 0xe000
	s_nop 0
	global_load_lds_dwordx4 v[168:169], off
	s_waitcnt lgkmcnt(8)
	s_barrier
	s_waitcnt lgkmcnt(0)
	s_setprio 1
	s_waitcnt lgkmcnt(0)
	v_mfma_f32_16x16x32_bf16 v[124:127], v[152:155], v[172:175], v[124:127]
	v_mfma_f32_16x16x32_bf16 v[120:123], v[160:163], v[172:175], v[120:123]
	v_mfma_f32_16x16x32_bf16 v[116:119], v[152:155], v[180:183], v[116:119]
	v_mfma_f32_16x16x32_bf16 v[108:111], v[160:163], v[180:183], v[108:111]
	v_mfma_f32_16x16x32_bf16 v[100:103], v[152:155], v[188:191], v[100:103]
	v_mfma_f32_16x16x32_bf16 v[92:95], v[160:163], v[188:191], v[92:95]
	v_mfma_f32_16x16x32_bf16 v[84:87], v[152:155], v[196:199], v[84:87]
	v_mfma_f32_16x16x32_bf16 v[76:79], v[160:163], v[196:199], v[76:79]
	v_mfma_f32_16x16x32_bf16 v[124:127], v[156:159], v[176:179], v[124:127]
	v_mfma_f32_16x16x32_bf16 v[120:123], v[164:167], v[176:179], v[120:123]
	v_mfma_f32_16x16x32_bf16 v[116:119], v[156:159], v[184:187], v[116:119]
	v_mfma_f32_16x16x32_bf16 v[108:111], v[164:167], v[184:187], v[108:111]
	v_mfma_f32_16x16x32_bf16 v[100:103], v[156:159], v[192:195], v[100:103]
	v_mfma_f32_16x16x32_bf16 v[92:95], v[164:167], v[192:195], v[92:95]
	v_mfma_f32_16x16x32_bf16 v[84:87], v[156:159], v[200:203], v[84:87]
	v_mfma_f32_16x16x32_bf16 v[76:79], v[164:167], v[200:203], v[76:79]
	s_setprio 0
	s_barrier
	s_add_i32 s16, s36, s27
	v_lshl_add_u64 v[168:169], s[18:19], 0, v[132:133]
	s_mov_b32 m0, s16
	ds_read_b128 v[204:207], v151
	ds_read_b128 v[208:211], v151 offset:1024
	ds_read_b128 v[212:215], v151 offset:2048
	ds_read_b128 v[216:219], v151 offset:3072
	global_load_lds_dwordx4 v[168:169], off
	v_lshl_add_u64 v[220:221], s[18:19], 0, v[128:129]
	s_add_i32 m0, s16, 0x2000
	s_nop 0
	global_load_lds_dwordx4 v[220:221], off
	s_barrier
	s_waitcnt lgkmcnt(0)
	s_setprio 1
	s_waitcnt lgkmcnt(0)
	v_mfma_f32_16x16x32_bf16 v[112:115], v[204:207], v[172:175], v[112:115]
	v_mfma_f32_16x16x32_bf16 v[104:107], v[212:215], v[172:175], v[104:107]
	v_mfma_f32_16x16x32_bf16 v[96:99], v[204:207], v[180:183], v[96:99]
	v_mfma_f32_16x16x32_bf16 v[88:91], v[212:215], v[180:183], v[88:91]
	v_mfma_f32_16x16x32_bf16 v[80:83], v[204:207], v[188:191], v[80:83]
	v_mfma_f32_16x16x32_bf16 v[72:75], v[212:215], v[188:191], v[72:75]
	v_mfma_f32_16x16x32_bf16 v[68:71], v[204:207], v[196:199], v[68:71]
	v_mfma_f32_16x16x32_bf16 v[64:67], v[212:215], v[196:199], v[64:67]
	v_mfma_f32_16x16x32_bf16 v[112:115], v[208:211], v[176:179], v[112:115]
	v_mfma_f32_16x16x32_bf16 v[104:107], v[216:219], v[176:179], v[104:107]
	v_mfma_f32_16x16x32_bf16 v[96:99], v[208:211], v[184:187], v[96:99]
	v_mfma_f32_16x16x32_bf16 v[88:91], v[216:219], v[184:187], v[88:91]
	v_mfma_f32_16x16x32_bf16 v[80:83], v[208:211], v[192:195], v[80:83]
	v_mfma_f32_16x16x32_bf16 v[72:75], v[216:219], v[192:195], v[72:75]
	v_mfma_f32_16x16x32_bf16 v[68:71], v[208:211], v[200:203], v[68:71]
	v_mfma_f32_16x16x32_bf16 v[64:67], v[216:219], v[200:203], v[64:67]
	s_setprio 0
	s_mov_b32 m0, s28
	v_lshl_add_u64 v[222:223], s[20:21], 0, v[134:135]
	s_barrier
	ds_read_b128 v[172:175], v150 offset:16384
	ds_read_b128 v[176:179], v150 offset:17408
	ds_read_b128 v[180:183], v150 offset:18432
	ds_read_b128 v[184:187], v150 offset:19456
	ds_read_b128 v[188:191], v150 offset:20480
	ds_read_b128 v[192:195], v150 offset:21504
	ds_read_b128 v[196:199], v150 offset:22528
	ds_read_b128 v[200:203], v150 offset:23552
	global_load_lds_dwordx4 v[222:223], off
	v_lshl_add_u64 v[224:225], s[20:21], 0, v[130:131]
	s_mov_b32 m0, s29
	s_nop 0
	global_load_lds_dwordx4 v[224:225], off
	s_barrier
	s_waitcnt lgkmcnt(0)
	s_setprio 1
	s_waitcnt lgkmcnt(0)
	v_mfma_f32_16x16x32_bf16 v[60:63], v[152:155], v[172:175], v[60:63]
	v_mfma_f32_16x16x32_bf16 v[56:59], v[160:163], v[172:175], v[56:59]
	v_mfma_f32_16x16x32_bf16 v[52:55], v[152:155], v[180:183], v[52:55]
	v_mfma_f32_16x16x32_bf16 v[44:47], v[160:163], v[180:183], v[44:47]
	v_mfma_f32_16x16x32_bf16 v[36:39], v[152:155], v[188:191], v[36:39]
	v_mfma_f32_16x16x32_bf16 v[28:31], v[160:163], v[188:191], v[28:31]
	v_mfma_f32_16x16x32_bf16 v[20:23], v[152:155], v[196:199], v[20:23]
	v_mfma_f32_16x16x32_bf16 v[12:15], v[160:163], v[196:199], v[12:15]
	v_mfma_f32_16x16x32_bf16 v[60:63], v[156:159], v[176:179], v[60:63]
	v_mfma_f32_16x16x32_bf16 v[56:59], v[164:167], v[176:179], v[56:59]
	v_mfma_f32_16x16x32_bf16 v[52:55], v[156:159], v[184:187], v[52:55]
	v_mfma_f32_16x16x32_bf16 v[44:47], v[164:167], v[184:187], v[44:47]
	v_mfma_f32_16x16x32_bf16 v[36:39], v[156:159], v[192:195], v[36:39]
	v_mfma_f32_16x16x32_bf16 v[28:31], v[164:167], v[192:195], v[28:31]
	v_mfma_f32_16x16x32_bf16 v[20:23], v[156:159], v[200:203], v[20:23]
	v_mfma_f32_16x16x32_bf16 v[12:15], v[164:167], v[200:203], v[12:15]
	s_setprio 0
	s_barrier
	s_add_u32 s16, s18, 0x40000
	s_addc_u32 s17, s19, 0
	s_add_i32 s46, s37, s27
	v_lshl_add_u64 v[152:153], s[16:17], 0, v[132:133]
	s_mov_b32 m0, s46
	s_nop 0
	global_load_lds_dwordx4 v[152:153], off
	v_lshl_add_u64 v[152:153], s[16:17], 0, v[128:129]
	s_add_i32 m0, s46, 0x2000
	s_nop 0
	global_load_lds_dwordx4 v[152:153], off
	s_waitcnt vmcnt(6)
	s_barrier
	s_setprio 1
	v_mfma_f32_16x16x32_bf16 v[48:51], v[204:207], v[172:175], v[48:51]
	v_mfma_f32_16x16x32_bf16 v[40:43], v[212:215], v[172:175], v[40:43]
	v_mfma_f32_16x16x32_bf16 v[32:35], v[204:207], v[180:183], v[32:35]
	v_mfma_f32_16x16x32_bf16 v[24:27], v[212:215], v[180:183], v[24:27]
	v_mfma_f32_16x16x32_bf16 v[16:19], v[204:207], v[188:191], v[16:19]
	v_mfma_f32_16x16x32_bf16 v[8:11], v[212:215], v[188:191], v[8:11]
	v_mfma_f32_16x16x32_bf16 v[4:7], v[204:207], v[196:199], v[4:7]
	v_mfma_f32_16x16x32_bf16 v[0:3], v[212:215], v[196:199], v[0:3]
	v_mfma_f32_16x16x32_bf16 v[48:51], v[208:211], v[176:179], v[48:51]
	v_mfma_f32_16x16x32_bf16 v[40:43], v[216:219], v[176:179], v[40:43]
	v_mfma_f32_16x16x32_bf16 v[32:35], v[208:211], v[184:187], v[32:35]
	v_mfma_f32_16x16x32_bf16 v[24:27], v[216:219], v[184:187], v[24:27]
	v_mfma_f32_16x16x32_bf16 v[16:19], v[208:211], v[192:195], v[16:19]
	v_mfma_f32_16x16x32_bf16 v[8:11], v[216:219], v[192:195], v[8:11]
	v_mfma_f32_16x16x32_bf16 v[4:7], v[208:211], v[200:203], v[4:7]
	v_mfma_f32_16x16x32_bf16 v[0:3], v[216:219], v[200:203], v[0:3]
	s_setprio 0
	s_add_i32 s46, 0, 0x18000
	v_add_u32_e32 v164, s46, v148
	s_barrier
	ds_read_b128 v[152:155], v164
	ds_read_b128 v[156:159], v164 offset:1024
	ds_read_b128 v[160:163], v164 offset:2048
	ds_read_b128 v[164:167], v164 offset:3072
	s_add_u32 s16, s20, 0xea000
	s_addc_u32 s17, s21, 0
	s_mov_b32 m0, s30
	v_lshl_add_u64 v[204:205], s[16:17], 0, v[134:135]
	ds_read_b128 v[172:175], v150 offset:32768
	ds_read_b128 v[176:179], v150 offset:33792
	ds_read_b128 v[180:183], v150 offset:34816
	ds_read_b128 v[184:187], v150 offset:35840
	ds_read_b128 v[188:191], v150 offset:36864
	ds_read_b128 v[192:195], v150 offset:37888
	ds_read_b128 v[196:199], v150 offset:38912
	ds_read_b128 v[200:203], v150 offset:39936
	global_load_lds_dwordx4 v[204:205], off
	v_lshl_add_u64 v[204:205], s[16:17], 0, v[130:131]
	s_mov_b32 m0, s31
	s_nop 0
	global_load_lds_dwordx4 v[204:205], off
	s_waitcnt lgkmcnt(8)
	s_barrier
	s_waitcnt lgkmcnt(0)
	s_setprio 1
	s_waitcnt lgkmcnt(0)
	v_mfma_f32_16x16x32_bf16 v[124:127], v[152:155], v[172:175], v[124:127]
	v_mfma_f32_16x16x32_bf16 v[120:123], v[160:163], v[172:175], v[120:123]
	v_mfma_f32_16x16x32_bf16 v[116:119], v[152:155], v[180:183], v[116:119]
	v_mfma_f32_16x16x32_bf16 v[108:111], v[160:163], v[180:183], v[108:111]
	v_mfma_f32_16x16x32_bf16 v[100:103], v[152:155], v[188:191], v[100:103]
	v_mfma_f32_16x16x32_bf16 v[92:95], v[160:163], v[188:191], v[92:95]
	v_mfma_f32_16x16x32_bf16 v[84:87], v[152:155], v[196:199], v[84:87]
	v_mfma_f32_16x16x32_bf16 v[76:79], v[160:163], v[196:199], v[76:79]
	v_mfma_f32_16x16x32_bf16 v[124:127], v[156:159], v[176:179], v[124:127]
	v_mfma_f32_16x16x32_bf16 v[120:123], v[164:167], v[176:179], v[120:123]
	v_mfma_f32_16x16x32_bf16 v[116:119], v[156:159], v[184:187], v[116:119]
	v_mfma_f32_16x16x32_bf16 v[108:111], v[164:167], v[184:187], v[108:111]
	v_mfma_f32_16x16x32_bf16 v[100:103], v[156:159], v[192:195], v[100:103]
	v_mfma_f32_16x16x32_bf16 v[92:95], v[164:167], v[192:195], v[92:95]
	v_mfma_f32_16x16x32_bf16 v[84:87], v[156:159], v[200:203], v[84:87]
	v_mfma_f32_16x16x32_bf16 v[76:79], v[164:167], v[200:203], v[76:79]
	s_setprio 0
	s_barrier
	s_add_i32 s20, 0, 0x1c000
	s_add_i32 s16, s46, s27
	v_add_u32_e32 v171, s20, v148
	v_lshl_add_u64 v[168:169], v[168:169], 0, s[4:5]
	s_mov_b32 m0, s16
	ds_read_b128 v[204:207], v171
	ds_read_b128 v[208:211], v171 offset:1024
	ds_read_b128 v[212:215], v171 offset:2048
	ds_read_b128 v[216:219], v171 offset:3072
	global_load_lds_dwordx4 v[168:169], off
	v_lshl_add_u64 v[168:169], v[220:221], 0, s[4:5]
	s_add_i32 m0, s16, 0x2000
	s_nop 0
	global_load_lds_dwordx4 v[168:169], off
	s_barrier
	s_waitcnt lgkmcnt(0)
	s_setprio 1
	s_waitcnt lgkmcnt(0)
	v_mfma_f32_16x16x32_bf16 v[112:115], v[204:207], v[172:175], v[112:115]
	v_mfma_f32_16x16x32_bf16 v[104:107], v[212:215], v[172:175], v[104:107]
	v_mfma_f32_16x16x32_bf16 v[96:99], v[204:207], v[180:183], v[96:99]
	v_mfma_f32_16x16x32_bf16 v[88:91], v[212:215], v[180:183], v[88:91]
	v_mfma_f32_16x16x32_bf16 v[80:83], v[204:207], v[188:191], v[80:83]
	v_mfma_f32_16x16x32_bf16 v[72:75], v[212:215], v[188:191], v[72:75]
	v_mfma_f32_16x16x32_bf16 v[68:71], v[204:207], v[196:199], v[68:71]
	v_mfma_f32_16x16x32_bf16 v[64:67], v[212:215], v[196:199], v[64:67]
	v_mfma_f32_16x16x32_bf16 v[112:115], v[208:211], v[176:179], v[112:115]
	v_mfma_f32_16x16x32_bf16 v[104:107], v[216:219], v[176:179], v[104:107]
	v_mfma_f32_16x16x32_bf16 v[96:99], v[208:211], v[184:187], v[96:99]
	v_mfma_f32_16x16x32_bf16 v[88:91], v[216:219], v[184:187], v[88:91]
	v_mfma_f32_16x16x32_bf16 v[80:83], v[208:211], v[192:195], v[80:83]
	v_mfma_f32_16x16x32_bf16 v[72:75], v[216:219], v[192:195], v[72:75]
	v_mfma_f32_16x16x32_bf16 v[68:71], v[208:211], v[200:203], v[68:71]
	v_mfma_f32_16x16x32_bf16 v[64:67], v[216:219], v[200:203], v[64:67]
	s_setprio 0
	s_mov_b32 m0, s33
	v_lshl_add_u64 v[168:169], v[222:223], 0, s[4:5]
	s_barrier
	ds_read_b128 v[172:175], v150 offset:49152
	ds_read_b128 v[176:179], v150 offset:50176
	ds_read_b128 v[180:183], v150 offset:51200
	ds_read_b128 v[184:187], v150 offset:52224
	ds_read_b128 v[188:191], v150 offset:53248
	ds_read_b128 v[192:195], v150 offset:54272
	ds_read_b128 v[196:199], v150 offset:55296
	ds_read_b128 v[200:203], v150 offset:56320
	global_load_lds_dwordx4 v[168:169], off
	v_lshl_add_u64 v[168:169], v[224:225], 0, s[4:5]
	s_mov_b32 m0, s34
	s_nop 0
	global_load_lds_dwordx4 v[168:169], off
	s_barrier
	s_waitcnt lgkmcnt(0)
	s_setprio 1
	s_waitcnt lgkmcnt(0)
	v_mfma_f32_16x16x32_bf16 v[60:63], v[152:155], v[172:175], v[60:63]
	v_mfma_f32_16x16x32_bf16 v[56:59], v[160:163], v[172:175], v[56:59]
	v_mfma_f32_16x16x32_bf16 v[52:55], v[152:155], v[180:183], v[52:55]
	v_mfma_f32_16x16x32_bf16 v[44:47], v[160:163], v[180:183], v[44:47]
	v_mfma_f32_16x16x32_bf16 v[36:39], v[152:155], v[188:191], v[36:39]
	v_mfma_f32_16x16x32_bf16 v[28:31], v[160:163], v[188:191], v[28:31]
	v_mfma_f32_16x16x32_bf16 v[20:23], v[152:155], v[196:199], v[20:23]
	v_mfma_f32_16x16x32_bf16 v[12:15], v[160:163], v[196:199], v[12:15]
	v_mfma_f32_16x16x32_bf16 v[60:63], v[156:159], v[176:179], v[60:63]
	v_mfma_f32_16x16x32_bf16 v[56:59], v[164:167], v[176:179], v[56:59]
	v_mfma_f32_16x16x32_bf16 v[52:55], v[156:159], v[184:187], v[52:55]
	v_mfma_f32_16x16x32_bf16 v[44:47], v[164:167], v[184:187], v[44:47]
	v_mfma_f32_16x16x32_bf16 v[36:39], v[156:159], v[192:195], v[36:39]
	v_mfma_f32_16x16x32_bf16 v[28:31], v[164:167], v[192:195], v[28:31]
	v_mfma_f32_16x16x32_bf16 v[20:23], v[156:159], v[200:203], v[20:23]
	v_mfma_f32_16x16x32_bf16 v[12:15], v[164:167], v[200:203], v[12:15]
	s_setprio 0
	s_barrier
	s_add_u32 s16, s18, 0x40080
	s_addc_u32 s17, s19, 0
	s_add_i32 s18, s20, s27
	v_lshl_add_u64 v[152:153], s[16:17], 0, v[132:133]
	s_mov_b32 m0, s18
	s_nop 0
	global_load_lds_dwordx4 v[152:153], off
	v_lshl_add_u64 v[152:153], s[16:17], 0, v[128:129]
	s_add_i32 m0, s18, 0x2000
	s_nop 0
	global_load_lds_dwordx4 v[152:153], off
	s_waitcnt vmcnt(6)
	s_barrier
	s_setprio 1
	v_mfma_f32_16x16x32_bf16 v[48:51], v[204:207], v[172:175], v[48:51]
	v_mfma_f32_16x16x32_bf16 v[40:43], v[212:215], v[172:175], v[40:43]
	v_mfma_f32_16x16x32_bf16 v[32:35], v[204:207], v[180:183], v[32:35]
	v_mfma_f32_16x16x32_bf16 v[24:27], v[212:215], v[180:183], v[24:27]
	v_mfma_f32_16x16x32_bf16 v[16:19], v[204:207], v[188:191], v[16:19]
	v_mfma_f32_16x16x32_bf16 v[8:11], v[212:215], v[188:191], v[8:11]
	v_mfma_f32_16x16x32_bf16 v[4:7], v[204:207], v[196:199], v[4:7]
	v_mfma_f32_16x16x32_bf16 v[0:3], v[212:215], v[196:199], v[0:3]
	v_mfma_f32_16x16x32_bf16 v[48:51], v[208:211], v[176:179], v[48:51]
	v_mfma_f32_16x16x32_bf16 v[40:43], v[216:219], v[176:179], v[40:43]
	v_mfma_f32_16x16x32_bf16 v[32:35], v[208:211], v[184:187], v[32:35]
	v_mfma_f32_16x16x32_bf16 v[24:27], v[216:219], v[184:187], v[24:27]
	v_mfma_f32_16x16x32_bf16 v[16:19], v[208:211], v[192:195], v[16:19]
	v_mfma_f32_16x16x32_bf16 v[8:11], v[216:219], v[192:195], v[8:11]
	v_mfma_f32_16x16x32_bf16 v[4:7], v[208:211], v[200:203], v[4:7]
	v_mfma_f32_16x16x32_bf16 v[0:3], v[216:219], v[200:203], v[0:3]
	s_setprio 0
	s_add_i32 s45, s45, 2
	s_add_u32 s43, s43, 0x100
	s_addc_u32 s44, s44, 0
	s_cmp_gt_u32 s45, 13
	s_mov_b64 s[16:17], s[8:9]
	s_barrier
	s_cbranch_scc0 .LBB0_2046
	v_lshl_add_u32 v152, s41, 8, v147
	s_lshl_b32 s8, s40, 8
	v_ashrrev_i32_e32 v153, 31, v152
	s_ashr_i32 s9, s8, 31
	v_lshlrev_b64 v[154:155], 11, v[152:153]
	v_lshl_add_u64 v[154:155], s[0:1], 0, v[154:155]
	s_lshl_b64 s[8:9], s[8:9], 1
	v_lshl_add_u64 v[154:155], v[154:155], 0, s[8:9]
	v_lshl_add_u64 v[154:155], v[154:155], 0, s[2:3]
	v_lshl_add_u64 v[154:155], v[154:155], 0, v[136:137]
	v_mbcnt_lo_u32_b32 v237, -1, 0
	v_mbcnt_hi_u32_b32 v237, -1, v237
	v_bfe_i32 v237, v237, 4, 1
	v_and_b32_e32 v244, 24, v237
	v_add_co_u32_e32 v248, vcc, v244, v154
	s_nop 1
	v_addc_co_u32_e32 v249, vcc, 0, v155, vcc
	v_cvt_pk_bf16_f32 v124, v124, v125
	v_cvt_pk_bf16_f32 v125, v126, v127
	v_cvt_pk_bf16_f32 v120, v120, v121
	v_cvt_pk_bf16_f32 v121, v122, v123
	v_bfi_b32 v244, v237, v124, v120
	v_bfi_b32 v245, v237, v125, v121
	ds_swizzle_b32 v250, v244 offset:0x401f
	ds_swizzle_b32 v251, v245 offset:0x401f
	v_cvt_pk_bf16_f32 v112, v112, v113
	v_cvt_pk_bf16_f32 v113, v114, v115
	v_cvt_pk_bf16_f32 v104, v104, v105
	v_cvt_pk_bf16_f32 v105, v106, v107
	v_bfi_b32 v246, v237, v112, v104
	v_bfi_b32 v247, v237, v113, v105
	ds_swizzle_b32 v252, v246 offset:0x401f
	ds_swizzle_b32 v253, v247 offset:0x401f
	s_waitcnt lgkmcnt(0)
	v_bfi_b32 v240, v237, v250, v124
	v_bfi_b32 v241, v237, v251, v125
	v_bfi_b32 v242, v237, v120, v250
	v_bfi_b32 v243, v237, v121, v251
	global_store_dwordx4 v[248:249], v[240:243], off sc1
	s_nop 1
	v_bfi_b32 v240, v237, v252, v112
	v_bfi_b32 v241, v237, v253, v113
	v_bfi_b32 v242, v237, v104, v252
	v_bfi_b32 v243, v237, v105, v253
	global_store_dwordx4 v[248:249], v[240:243], off offset:256 sc1
	s_nop 1
	v_add_co_u32_e32 v238, vcc, 0x8000, v248
	s_nop 1
	v_addc_co_u32_e32 v239, vcc, 0, v249, vcc
	v_cvt_pk_bf16_f32 v116, v116, v117
	v_cvt_pk_bf16_f32 v117, v118, v119
	v_cvt_pk_bf16_f32 v108, v108, v109
	v_cvt_pk_bf16_f32 v109, v110, v111
	v_bfi_b32 v244, v237, v116, v108
	v_bfi_b32 v245, v237, v117, v109
	ds_swizzle_b32 v250, v244 offset:0x401f
	ds_swizzle_b32 v251, v245 offset:0x401f
	v_cvt_pk_bf16_f32 v96, v96, v97
	v_cvt_pk_bf16_f32 v97, v98, v99
	v_cvt_pk_bf16_f32 v88, v88, v89
	v_cvt_pk_bf16_f32 v89, v90, v91
	v_bfi_b32 v246, v237, v96, v88
	v_bfi_b32 v247, v237, v97, v89
	ds_swizzle_b32 v252, v246 offset:0x401f
	ds_swizzle_b32 v253, v247 offset:0x401f
	s_waitcnt lgkmcnt(0)
	v_bfi_b32 v240, v237, v250, v116
	v_bfi_b32 v241, v237, v251, v117
	v_bfi_b32 v242, v237, v108, v250
	v_bfi_b32 v243, v237, v109, v251
	global_store_dwordx4 v[238:239], v[240:243], off sc1
	s_nop 1
	v_bfi_b32 v240, v237, v252, v96
	v_bfi_b32 v241, v237, v253, v97
	v_bfi_b32 v242, v237, v88, v252
	v_bfi_b32 v243, v237, v89, v253
	global_store_dwordx4 v[238:239], v[240:243], off offset:256 sc1
	s_nop 1
	v_add_co_u32_e32 v238, vcc, 0x10000, v248
	s_nop 1
	v_addc_co_u32_e32 v239, vcc, 0, v249, vcc
	v_cvt_pk_bf16_f32 v100, v100, v101
	v_cvt_pk_bf16_f32 v101, v102, v103
	v_cvt_pk_bf16_f32 v92, v92, v93
	v_cvt_pk_bf16_f32 v93, v94, v95
	v_bfi_b32 v244, v237, v100, v92
	v_bfi_b32 v245, v237, v101, v93
	ds_swizzle_b32 v250, v244 offset:0x401f
	ds_swizzle_b32 v251, v245 offset:0x401f
	v_cvt_pk_bf16_f32 v80, v80, v81
	v_cvt_pk_bf16_f32 v81, v82, v83
	v_cvt_pk_bf16_f32 v72, v72, v73
	v_cvt_pk_bf16_f32 v73, v74, v75
	v_bfi_b32 v246, v237, v80, v72
	v_bfi_b32 v247, v237, v81, v73
	ds_swizzle_b32 v252, v246 offset:0x401f
	ds_swizzle_b32 v253, v247 offset:0x401f
	s_waitcnt lgkmcnt(0)
	v_bfi_b32 v240, v237, v250, v100
	v_bfi_b32 v241, v237, v251, v101
	v_bfi_b32 v242, v237, v92, v250
	v_bfi_b32 v243, v237, v93, v251
	global_store_dwordx4 v[238:239], v[240:243], off sc1
	s_nop 1
	v_bfi_b32 v240, v237, v252, v80
	v_bfi_b32 v241, v237, v253, v81
	v_bfi_b32 v242, v237, v72, v252
	v_bfi_b32 v243, v237, v73, v253
	global_store_dwordx4 v[238:239], v[240:243], off offset:256 sc1
	s_nop 1
	v_add_co_u32_e32 v238, vcc, 0x18000, v248
	s_nop 1
	v_addc_co_u32_e32 v239, vcc, 0, v249, vcc
	v_cvt_pk_bf16_f32 v84, v84, v85
	v_cvt_pk_bf16_f32 v85, v86, v87
	v_cvt_pk_bf16_f32 v76, v76, v77
	v_cvt_pk_bf16_f32 v77, v78, v79
	v_bfi_b32 v244, v237, v84, v76
	v_bfi_b32 v245, v237, v85, v77
	ds_swizzle_b32 v250, v244 offset:0x401f
	ds_swizzle_b32 v251, v245 offset:0x401f
	v_cvt_pk_bf16_f32 v68, v68, v69
	v_cvt_pk_bf16_f32 v69, v70, v71
	v_cvt_pk_bf16_f32 v64, v64, v65
	v_cvt_pk_bf16_f32 v65, v66, v67
	v_bfi_b32 v246, v237, v68, v64
	v_bfi_b32 v247, v237, v69, v65
	ds_swizzle_b32 v252, v246 offset:0x401f
	ds_swizzle_b32 v253, v247 offset:0x401f
	s_waitcnt lgkmcnt(0)
	v_bfi_b32 v240, v237, v250, v84
	v_bfi_b32 v241, v237, v251, v85
	v_bfi_b32 v242, v237, v76, v250
	v_bfi_b32 v243, v237, v77, v251
	global_store_dwordx4 v[238:239], v[240:243], off sc1
	s_nop 1
	v_bfi_b32 v240, v237, v252, v68
	v_bfi_b32 v241, v237, v253, v69
	v_bfi_b32 v242, v237, v64, v252
	v_bfi_b32 v243, v237, v65, v253
	global_store_dwordx4 v[238:239], v[240:243], off offset:256 sc1
	s_nop 1
	v_add_co_u32_e32 v238, vcc, 0x40000, v248
	s_nop 1
	v_addc_co_u32_e32 v239, vcc, 0, v249, vcc
	v_cvt_pk_bf16_f32 v60, v60, v61
	v_cvt_pk_bf16_f32 v61, v62, v63
	v_cvt_pk_bf16_f32 v56, v56, v57
	v_cvt_pk_bf16_f32 v57, v58, v59
	v_bfi_b32 v244, v237, v60, v56
	v_bfi_b32 v245, v237, v61, v57
	ds_swizzle_b32 v250, v244 offset:0x401f
	ds_swizzle_b32 v251, v245 offset:0x401f
	v_cvt_pk_bf16_f32 v48, v48, v49
	v_cvt_pk_bf16_f32 v49, v50, v51
	v_cvt_pk_bf16_f32 v40, v40, v41
	v_cvt_pk_bf16_f32 v41, v42, v43
	v_bfi_b32 v246, v237, v48, v40
	v_bfi_b32 v247, v237, v49, v41
	ds_swizzle_b32 v252, v246 offset:0x401f
	ds_swizzle_b32 v253, v247 offset:0x401f
	s_waitcnt lgkmcnt(0)
	v_bfi_b32 v240, v237, v250, v60
	v_bfi_b32 v241, v237, v251, v61
	v_bfi_b32 v242, v237, v56, v250
	v_bfi_b32 v243, v237, v57, v251
	global_store_dwordx4 v[238:239], v[240:243], off sc1
	s_nop 1
	v_bfi_b32 v240, v237, v252, v48
	v_bfi_b32 v241, v237, v253, v49
	v_bfi_b32 v242, v237, v40, v252
	v_bfi_b32 v243, v237, v41, v253
	global_store_dwordx4 v[238:239], v[240:243], off offset:256 sc1
	s_nop 1
	v_add_co_u32_e32 v238, vcc, 0x48000, v248
	s_nop 1
	v_addc_co_u32_e32 v239, vcc, 0, v249, vcc
	v_cvt_pk_bf16_f32 v52, v52, v53
	v_cvt_pk_bf16_f32 v53, v54, v55
	v_cvt_pk_bf16_f32 v44, v44, v45
	v_cvt_pk_bf16_f32 v45, v46, v47
	v_bfi_b32 v244, v237, v52, v44
	v_bfi_b32 v245, v237, v53, v45
	ds_swizzle_b32 v250, v244 offset:0x401f
	ds_swizzle_b32 v251, v245 offset:0x401f
	v_cvt_pk_bf16_f32 v32, v32, v33
	v_cvt_pk_bf16_f32 v33, v34, v35
	v_cvt_pk_bf16_f32 v24, v24, v25
	v_cvt_pk_bf16_f32 v25, v26, v27
	v_bfi_b32 v246, v237, v32, v24
	v_bfi_b32 v247, v237, v33, v25
	ds_swizzle_b32 v252, v246 offset:0x401f
	ds_swizzle_b32 v253, v247 offset:0x401f
	s_waitcnt lgkmcnt(0)
	v_bfi_b32 v240, v237, v250, v52
	v_bfi_b32 v241, v237, v251, v53
	v_bfi_b32 v242, v237, v44, v250
	v_bfi_b32 v243, v237, v45, v251
	global_store_dwordx4 v[238:239], v[240:243], off sc1
	s_nop 1
	v_bfi_b32 v240, v237, v252, v32
	v_bfi_b32 v241, v237, v253, v33
	v_bfi_b32 v242, v237, v24, v252
	v_bfi_b32 v243, v237, v25, v253
	global_store_dwordx4 v[238:239], v[240:243], off offset:256 sc1
	s_nop 1
	v_add_co_u32_e32 v238, vcc, 0x50000, v248
	s_nop 1
	v_addc_co_u32_e32 v239, vcc, 0, v249, vcc
	v_cvt_pk_bf16_f32 v36, v36, v37
	v_cvt_pk_bf16_f32 v37, v38, v39
	v_cvt_pk_bf16_f32 v28, v28, v29
	v_cvt_pk_bf16_f32 v29, v30, v31
	v_bfi_b32 v244, v237, v36, v28
	v_bfi_b32 v245, v237, v37, v29
	ds_swizzle_b32 v250, v244 offset:0x401f
	ds_swizzle_b32 v251, v245 offset:0x401f
	v_cvt_pk_bf16_f32 v16, v16, v17
	v_cvt_pk_bf16_f32 v17, v18, v19
	v_cvt_pk_bf16_f32 v8, v8, v9
	v_cvt_pk_bf16_f32 v9, v10, v11
	v_bfi_b32 v246, v237, v16, v8
	v_bfi_b32 v247, v237, v17, v9
	ds_swizzle_b32 v252, v246 offset:0x401f
	ds_swizzle_b32 v253, v247 offset:0x401f
	s_waitcnt lgkmcnt(0)
	v_bfi_b32 v240, v237, v250, v36
	v_bfi_b32 v241, v237, v251, v37
	v_bfi_b32 v242, v237, v28, v250
	v_bfi_b32 v243, v237, v29, v251
	global_store_dwordx4 v[238:239], v[240:243], off sc1
	s_nop 1
	v_bfi_b32 v240, v237, v252, v16
	v_bfi_b32 v241, v237, v253, v17
	v_bfi_b32 v242, v237, v8, v252
	v_bfi_b32 v243, v237, v9, v253
	global_store_dwordx4 v[238:239], v[240:243], off offset:256 sc1
	s_nop 1
	v_add_co_u32_e32 v238, vcc, 0x58000, v248
	s_nop 1
	v_addc_co_u32_e32 v239, vcc, 0, v249, vcc
	v_cvt_pk_bf16_f32 v20, v20, v21
	v_cvt_pk_bf16_f32 v21, v22, v23
	v_cvt_pk_bf16_f32 v12, v12, v13
	v_cvt_pk_bf16_f32 v13, v14, v15
	v_bfi_b32 v244, v237, v20, v12
	v_bfi_b32 v245, v237, v21, v13
	ds_swizzle_b32 v250, v244 offset:0x401f
	ds_swizzle_b32 v251, v245 offset:0x401f
	v_cvt_pk_bf16_f32 v4, v4, v5
	v_cvt_pk_bf16_f32 v5, v6, v7
	v_cvt_pk_bf16_f32 v0, v0, v1
	v_cvt_pk_bf16_f32 v1, v2, v3
	v_bfi_b32 v246, v237, v4, v0
	v_bfi_b32 v247, v237, v5, v1
	ds_swizzle_b32 v252, v246 offset:0x401f
	ds_swizzle_b32 v253, v247 offset:0x401f
	s_waitcnt lgkmcnt(0)
	v_bfi_b32 v240, v237, v250, v20
	v_bfi_b32 v241, v237, v251, v21
	v_bfi_b32 v242, v237, v12, v250
	v_bfi_b32 v243, v237, v13, v251
	global_store_dwordx4 v[238:239], v[240:243], off sc1
	s_nop 1
	v_bfi_b32 v240, v237, v252, v4
	v_bfi_b32 v241, v237, v253, v5
	v_bfi_b32 v242, v237, v0, v252
	v_bfi_b32 v243, v237, v1, v253
	global_store_dwordx4 v[238:239], v[240:243], off offset:256 sc1
	s_nop 1
	s_and_b64 vcc, exec, s[6:7]
	s_mov_b32 s40, s10
	s_mov_b32 s41, s39
	s_mov_b64 s[18:19], s[14:15]
	s_mov_b64 s[16:17], s[12:13]
	s_cbranch_vccz .LBB0_2041
	s_waitcnt vmcnt(0)
	s_cmpk_gt_u32 s22, 0xff
	s_cbranch_scc1 .LBB0_2050
	s_barrier

.Lupf_u1_entry:
	v_mbcnt_lo_u32_b32 v253, -1, 0
	v_mbcnt_hi_u32_b32 v253, -1, v253
	v_and_b32_e32 v254, 15, v253
	v_lshrrev_b32_e32 v255, 4, v253
	s_lshr_b32 s100, s33, 6
	s_lshr_b32 s101, s100, 2
	s_and_b32 s100, s100, 3
	s_lshl_b32 vcc_lo, s101, 6
	v_add_u32_e32 v251, vcc_lo, v254
	s_add_i32 vcc_hi, s98, -1
	v_add_u32_e32 v250, vcc_hi, v251
	v_mul_u32_u24_e32 v250, 0x1600, v250
	s_lshl_b32 vcc_lo, s40, 7
	s_lshl_b32 vcc_hi, s100, 5
	s_add_i32 vcc_lo, vcc_lo, vcc_hi
	v_lshl_add_u32 v253, v255, 2, vcc_lo
	v_and_b32_e32 v252, 1, v255
	v_lshlrev_b32_e32 v252, 1, v252
	v_lshrrev_b32_e32 v245, 1, v255
	v_or_b32_e32 v252, v252, v245
	v_lshl_add_u32 v252, v252, 3, vcc_lo
	v_lshl_add_u32 v250, v252, 1, v250
	v_lshlrev_b32_e32 v146, 2, v253
	v_add_u32_e32 v147, 0x5800, v146
	v_add_u32_e32 v168, 0xb000, v146
	v_add_u32_e32 v169, 0x2c00, v146
	v_add_u32_e32 v245, 0x8400, v146
	v_add_u32_e32 v252, 0xdc00, v146
	global_load_dwordx4 v[172:175], v146, s[14:15] offset:0
	global_load_dwordx4 v[176:179], v147, s[14:15] offset:0
	global_load_dwordx4 v[180:183], v168, s[14:15] offset:0
	global_load_dwordx4 v[188:191], v169, s[14:15] offset:0
	global_load_dwordx4 v[192:195], v245, s[14:15] offset:0
	global_load_dwordx4 v[196:199], v252, s[14:15] offset:0
	global_load_dwordx4 v[184:187], v146, s[16:17] offset:0
	global_load_dwordx4 v[200:203], v169, s[16:17] offset:0
	s_lshl_b32 s101, s101, 11
	s_lshl_b32 s100, s100, 7
	s_add_i32 s101, s101, s100
	s_add_i32 s101, s101, 0x20000
	v_lshl_add_u32 v249, v255, 4, s101
	v_add_u32_e32 v253, 0x400, v249
	v_cmp_eq_u32_e64 s[98:99], 0, v254
	v_cmp_eq_u32_e32 vcc, 15, v254
	s_nop 4
	s_mov_b64 exec, s[98:99]
	ds_write_b128 v253, v[124:127] offset:0
	ds_write_b128 v253, v[108:111] offset:64
	ds_write_b128 v253, v[112:115] offset:512
	ds_write_b128 v253, v[84:87] offset:576
	ds_write_b128 v253, v[72:75] offset:4096
	ds_write_b128 v253, v[44:47] offset:4160
	ds_write_b128 v253, v[48:51] offset:4608
	ds_write_b128 v253, v[20:23] offset:4672
	s_mov_b64 exec, vcc
	ds_write_b128 v253, v[104:107] offset:1024
	ds_write_b128 v253, v[76:79] offset:1088
	ds_write_b128 v253, v[80:83] offset:1536
	ds_write_b128 v253, v[52:55] offset:1600
	ds_write_b128 v253, v[40:43] offset:5120
	ds_write_b128 v253, v[12:15] offset:5184
	ds_write_b128 v253, v[16:19] offset:5632
	ds_write_b128 v253, v[0:3] offset:5696
	s_mov_b64 exec, -1
	s_waitcnt lgkmcnt(0)
	s_barrier
	ds_read_b128 v[204:207], v249 offset:0
	ds_read_b128 v[208:211], v249 offset:512
	ds_read_b128 v[160:163], v249 offset:3072
	ds_read_b128 v[164:167], v249 offset:3584
	s_waitcnt vmcnt(0) lgkmcnt(0)
	v_cndmask_b32_e32 v148, v124, v204, vcc
	v_cndmask_b32_e32 v149, v125, v205, vcc
	v_cndmask_b32_e32 v150, v126, v206, vcc
	v_cndmask_b32_e32 v151, v127, v207, vcc
	v_cndmask_b32_e64 v152, v124, v120, s[98:99]
	v_cndmask_b32_e64 v153, v125, v121, s[98:99]
	v_cndmask_b32_e64 v154, v126, v122, s[98:99]
	v_cndmask_b32_e64 v155, v127, v123, s[98:99]
	v_fma_f32 v156, v176, v124, v184
	v_fma_f32 v157, v177, v125, v185
	v_fma_f32 v158, v178, v126, v186
	v_fma_f32 v159, v179, v127, v187
	v_fmac_f32_dpp v156, v148, v172 row_ror:1 row_mask:0xf bank_mask:0xf
	v_fmac_f32_dpp v157, v149, v173 row_ror:1 row_mask:0xf bank_mask:0xf
	v_fmac_f32_dpp v158, v150, v174 row_ror:1 row_mask:0xf bank_mask:0xf
	v_fmac_f32_dpp v159, v151, v175 row_ror:1 row_mask:0xf bank_mask:0xf
	v_fmac_f32_dpp v156, v152, v180 row_ror:15 row_mask:0xf bank_mask:0xf
	v_fmac_f32_dpp v157, v153, v181 row_ror:15 row_mask:0xf bank_mask:0xf
	v_fmac_f32_dpp v158, v154, v182 row_ror:15 row_mask:0xf bank_mask:0xf
	v_fmac_f32_dpp v159, v155, v183 row_ror:15 row_mask:0xf bank_mask:0xf
	v_cndmask_b32_e32 v148, v112, v208, vcc
	v_cndmask_b32_e32 v149, v113, v209, vcc
	v_cndmask_b32_e32 v150, v114, v210, vcc
	v_cndmask_b32_e32 v151, v115, v211, vcc
	v_cndmask_b32_e64 v152, v112, v100, s[98:99]
	v_cndmask_b32_e64 v153, v113, v101, s[98:99]
	v_cndmask_b32_e64 v154, v114, v102, s[98:99]
	v_cndmask_b32_e64 v155, v115, v103, s[98:99]
	v_fma_f32 v237, v192, v112, v200
	v_fma_f32 v238, v193, v113, v201
	v_fma_f32 v239, v194, v114, v202
	v_fma_f32 v240, v195, v115, v203
	v_fmac_f32_dpp v237, v148, v188 row_ror:1 row_mask:0xf bank_mask:0xf
	v_fmac_f32_dpp v238, v149, v189 row_ror:1 row_mask:0xf bank_mask:0xf
	v_fmac_f32_dpp v239, v150, v190 row_ror:1 row_mask:0xf bank_mask:0xf
	v_fmac_f32_dpp v240, v151, v191 row_ror:1 row_mask:0xf bank_mask:0xf
	v_fmac_f32_dpp v237, v152, v196 row_ror:15 row_mask:0xf bank_mask:0xf
	v_fmac_f32_dpp v238, v153, v197 row_ror:15 row_mask:0xf bank_mask:0xf
	v_fmac_f32_dpp v239, v154, v198 row_ror:15 row_mask:0xf bank_mask:0xf
	v_fmac_f32_dpp v240, v155, v199 row_ror:15 row_mask:0xf bank_mask:0xf
	v_mul_f32_e32 v148, 0xbfb8aa3b, v156
	v_mul_f32_e32 v149, 0xbfb8aa3b, v157
	v_mul_f32_e32 v150, 0xbfb8aa3b, v158
	v_mul_f32_e32 v151, 0xbfb8aa3b, v159
	v_exp_f32_e32 v148, v148
	v_exp_f32_e32 v149, v149
	v_exp_f32_e32 v150, v150
	v_exp_f32_e32 v151, v151
	v_add_f32_e32 v148, 1.0, v148
	v_add_f32_e32 v149, 1.0, v149
	v_add_f32_e32 v150, 1.0, v150
	v_add_f32_e32 v151, 1.0, v151
	v_rcp_f32_e32 v148, v148
	v_rcp_f32_e32 v149, v149
	v_rcp_f32_e32 v150, v150
	v_rcp_f32_e32 v151, v151
	v_mul_f32_e32 v156, v156, v148
	v_mul_f32_e32 v157, v157, v149
	v_mul_f32_e32 v158, v158, v150
	v_mul_f32_e32 v159, v159, v151
	v_mul_f32_e32 v156, v156, v237
	v_mul_f32_e32 v157, v157, v238
	v_mul_f32_e32 v158, v158, v239
	v_mul_f32_e32 v159, v159, v240
	v_cvt_pk_bf16_f32 v241, v156, v157
	v_cvt_pk_bf16_f32 v242, v158, v159
	ds_read_b128 v[204:207], v249 offset:4096
	ds_read_b128 v[208:211], v249 offset:4608
	v_cndmask_b32_e32 v148, v120, v124, vcc
	v_cndmask_b32_e32 v149, v121, v125, vcc
	v_cndmask_b32_e32 v150, v122, v126, vcc
	v_cndmask_b32_e32 v151, v123, v127, vcc
	v_cndmask_b32_e64 v152, v120, v116, s[98:99]
	v_cndmask_b32_e64 v153, v121, v117, s[98:99]
	v_cndmask_b32_e64 v154, v122, v118, s[98:99]
	v_cndmask_b32_e64 v155, v123, v119, s[98:99]
	v_fma_f32 v156, v176, v120, v184
	v_fma_f32 v157, v177, v121, v185
	v_fma_f32 v158, v178, v122, v186
	v_fma_f32 v159, v179, v123, v187
	v_fmac_f32_dpp v156, v148, v172 row_ror:1 row_mask:0xf bank_mask:0xf
	v_fmac_f32_dpp v157, v149, v173 row_ror:1 row_mask:0xf bank_mask:0xf
	v_fmac_f32_dpp v158, v150, v174 row_ror:1 row_mask:0xf bank_mask:0xf
	v_fmac_f32_dpp v159, v151, v175 row_ror:1 row_mask:0xf bank_mask:0xf
	v_fmac_f32_dpp v156, v152, v180 row_ror:15 row_mask:0xf bank_mask:0xf
	v_fmac_f32_dpp v157, v153, v181 row_ror:15 row_mask:0xf bank_mask:0xf
	v_fmac_f32_dpp v158, v154, v182 row_ror:15 row_mask:0xf bank_mask:0xf
	v_fmac_f32_dpp v159, v155, v183 row_ror:15 row_mask:0xf bank_mask:0xf
	v_cndmask_b32_e32 v148, v100, v112, vcc
	v_cndmask_b32_e32 v149, v101, v113, vcc
	v_cndmask_b32_e32 v150, v102, v114, vcc
	v_cndmask_b32_e32 v151, v103, v115, vcc
	v_cndmask_b32_e64 v152, v100, v92, s[98:99]
	v_cndmask_b32_e64 v153, v101, v93, s[98:99]
	v_cndmask_b32_e64 v154, v102, v94, s[98:99]
	v_cndmask_b32_e64 v155, v103, v95, s[98:99]
	v_fma_f32 v237, v192, v100, v200
	v_fma_f32 v238, v193, v101, v201
	v_fma_f32 v239, v194, v102, v202
	v_fma_f32 v240, v195, v103, v203
	v_fmac_f32_dpp v237, v148, v188 row_ror:1 row_mask:0xf bank_mask:0xf
	v_fmac_f32_dpp v238, v149, v189 row_ror:1 row_mask:0xf bank_mask:0xf
	v_fmac_f32_dpp v239, v150, v190 row_ror:1 row_mask:0xf bank_mask:0xf
	v_fmac_f32_dpp v240, v151, v191 row_ror:1 row_mask:0xf bank_mask:0xf
	v_fmac_f32_dpp v237, v152, v196 row_ror:15 row_mask:0xf bank_mask:0xf
	v_fmac_f32_dpp v238, v153, v197 row_ror:15 row_mask:0xf bank_mask:0xf
	v_fmac_f32_dpp v239, v154, v198 row_ror:15 row_mask:0xf bank_mask:0xf
	v_fmac_f32_dpp v240, v155, v199 row_ror:15 row_mask:0xf bank_mask:0xf
	v_mul_f32_e32 v148, 0xbfb8aa3b, v156
	v_mul_f32_e32 v149, 0xbfb8aa3b, v157
	v_mul_f32_e32 v150, 0xbfb8aa3b, v158
	v_mul_f32_e32 v151, 0xbfb8aa3b, v159
	v_exp_f32_e32 v148, v148
	v_exp_f32_e32 v149, v149
	v_exp_f32_e32 v150, v150
	v_exp_f32_e32 v151, v151
	v_add_f32_e32 v148, 1.0, v148
	v_add_f32_e32 v149, 1.0, v149
	v_add_f32_e32 v150, 1.0, v150
	v_add_f32_e32 v151, 1.0, v151
	v_rcp_f32_e32 v148, v148
	v_rcp_f32_e32 v149, v149
	v_rcp_f32_e32 v150, v150
	v_rcp_f32_e32 v151, v151
	v_mul_f32_e32 v156, v156, v148
	v_mul_f32_e32 v157, v157, v149
	v_mul_f32_e32 v158, v158, v150
	v_mul_f32_e32 v159, v159, v151
	v_mul_f32_e32 v156, v156, v237
	v_mul_f32_e32 v157, v157, v238
	v_mul_f32_e32 v158, v158, v239
	v_mul_f32_e32 v159, v159, v240
	v_cvt_pk_bf16_f32 v243, v156, v157
	v_cvt_pk_bf16_f32 v244, v158, v159
	v_cndmask_b32_e32 v148, v116, v120, vcc
	v_cndmask_b32_e32 v149, v117, v121, vcc
	v_cndmask_b32_e32 v150, v118, v122, vcc
	v_cndmask_b32_e32 v151, v119, v123, vcc
	v_cndmask_b32_e64 v152, v116, v104, s[98:99]
	v_cndmask_b32_e64 v153, v117, v105, s[98:99]
	v_cndmask_b32_e64 v154, v118, v106, s[98:99]
	v_cndmask_b32_e64 v155, v119, v107, s[98:99]
	v_fma_f32 v156, v176, v116, v184
	v_fma_f32 v157, v177, v117, v185
	v_fma_f32 v158, v178, v118, v186
	v_fma_f32 v159, v179, v119, v187
	v_fmac_f32_dpp v156, v148, v172 row_ror:1 row_mask:0xf bank_mask:0xf
	v_fmac_f32_dpp v157, v149, v173 row_ror:1 row_mask:0xf bank_mask:0xf
	v_fmac_f32_dpp v158, v150, v174 row_ror:1 row_mask:0xf bank_mask:0xf
	v_fmac_f32_dpp v159, v151, v175 row_ror:1 row_mask:0xf bank_mask:0xf
	v_fmac_f32_dpp v156, v152, v180 row_ror:15 row_mask:0xf bank_mask:0xf
	v_fmac_f32_dpp v157, v153, v181 row_ror:15 row_mask:0xf bank_mask:0xf
	v_fmac_f32_dpp v158, v154, v182 row_ror:15 row_mask:0xf bank_mask:0xf
	v_fmac_f32_dpp v159, v155, v183 row_ror:15 row_mask:0xf bank_mask:0xf
	v_cndmask_b32_e32 v148, v92, v100, vcc
	v_cndmask_b32_e32 v149, v93, v101, vcc
	v_cndmask_b32_e32 v150, v94, v102, vcc
	v_cndmask_b32_e32 v151, v95, v103, vcc
	v_cndmask_b32_e64 v152, v92, v80, s[98:99]
	v_cndmask_b32_e64 v153, v93, v81, s[98:99]
	v_cndmask_b32_e64 v154, v94, v82, s[98:99]
	v_cndmask_b32_e64 v155, v95, v83, s[98:99]
	v_fma_f32 v237, v192, v92, v200
	v_fma_f32 v238, v193, v93, v201
	v_fma_f32 v239, v194, v94, v202
	v_fma_f32 v240, v195, v95, v203
	v_fmac_f32_dpp v237, v148, v188 row_ror:1 row_mask:0xf bank_mask:0xf
	v_fmac_f32_dpp v238, v149, v189 row_ror:1 row_mask:0xf bank_mask:0xf
	v_fmac_f32_dpp v239, v150, v190 row_ror:1 row_mask:0xf bank_mask:0xf
	v_fmac_f32_dpp v240, v151, v191 row_ror:1 row_mask:0xf bank_mask:0xf
	v_fmac_f32_dpp v237, v152, v196 row_ror:15 row_mask:0xf bank_mask:0xf
	v_fmac_f32_dpp v238, v153, v197 row_ror:15 row_mask:0xf bank_mask:0xf
	v_fmac_f32_dpp v239, v154, v198 row_ror:15 row_mask:0xf bank_mask:0xf
	v_fmac_f32_dpp v240, v155, v199 row_ror:15 row_mask:0xf bank_mask:0xf
	v_mul_f32_e32 v148, 0xbfb8aa3b, v156
	v_mul_f32_e32 v149, 0xbfb8aa3b, v157
	v_mul_f32_e32 v150, 0xbfb8aa3b, v158
	v_mul_f32_e32 v151, 0xbfb8aa3b, v159
	v_exp_f32_e32 v148, v148
	v_exp_f32_e32 v149, v149
	v_exp_f32_e32 v150, v150
	v_exp_f32_e32 v151, v151
	v_add_f32_e32 v148, 1.0, v148
	v_add_f32_e32 v149, 1.0, v149
	v_add_f32_e32 v150, 1.0, v150
	v_add_f32_e32 v151, 1.0, v151
	v_rcp_f32_e32 v148, v148
	v_rcp_f32_e32 v149, v149
	v_rcp_f32_e32 v150, v150
	v_rcp_f32_e32 v151, v151
	v_mul_f32_e32 v156, v156, v148
	v_mul_f32_e32 v157, v157, v149
	v_mul_f32_e32 v158, v158, v150
	v_mul_f32_e32 v159, v159, v151
	v_mul_f32_e32 v156, v156, v237
	v_mul_f32_e32 v157, v157, v238
	v_mul_f32_e32 v158, v158, v239
	v_mul_f32_e32 v159, v159, v240
	v_cvt_pk_bf16_f32 v253, v156, v157
	v_cvt_pk_bf16_f32 v254, v158, v159
	v_cndmask_b32_e32 v148, v104, v116, vcc
	v_cndmask_b32_e32 v149, v105, v117, vcc
	v_cndmask_b32_e32 v150, v106, v118, vcc
	v_cndmask_b32_e32 v151, v107, v119, vcc
	v_cndmask_b32_e64 v152, v104, v160, s[98:99]
	v_cndmask_b32_e64 v153, v105, v161, s[98:99]
	v_cndmask_b32_e64 v154, v106, v162, s[98:99]
	v_cndmask_b32_e64 v155, v107, v163, s[98:99]
	v_fma_f32 v156, v176, v104, v184
	v_fma_f32 v157, v177, v105, v185
	v_fma_f32 v158, v178, v106, v186
	v_fma_f32 v159, v179, v107, v187
	v_fmac_f32_dpp v156, v148, v172 row_ror:1 row_mask:0xf bank_mask:0xf
	v_fmac_f32_dpp v157, v149, v173 row_ror:1 row_mask:0xf bank_mask:0xf
	v_fmac_f32_dpp v158, v150, v174 row_ror:1 row_mask:0xf bank_mask:0xf
	v_fmac_f32_dpp v159, v151, v175 row_ror:1 row_mask:0xf bank_mask:0xf
	v_fmac_f32_dpp v156, v152, v180 row_ror:15 row_mask:0xf bank_mask:0xf
	v_fmac_f32_dpp v157, v153, v181 row_ror:15 row_mask:0xf bank_mask:0xf
	v_fmac_f32_dpp v158, v154, v182 row_ror:15 row_mask:0xf bank_mask:0xf
	v_fmac_f32_dpp v159, v155, v183 row_ror:15 row_mask:0xf bank_mask:0xf
	v_cndmask_b32_e32 v148, v80, v92, vcc
	v_cndmask_b32_e32 v149, v81, v93, vcc
	v_cndmask_b32_e32 v150, v82, v94, vcc
	v_cndmask_b32_e32 v151, v83, v95, vcc
	v_cndmask_b32_e64 v152, v80, v164, s[98:99]
	v_cndmask_b32_e64 v153, v81, v165, s[98:99]
	v_cndmask_b32_e64 v154, v82, v166, s[98:99]
	v_cndmask_b32_e64 v155, v83, v167, s[98:99]
	v_fma_f32 v237, v192, v80, v200
	v_fma_f32 v238, v193, v81, v201
	v_fma_f32 v239, v194, v82, v202
	v_fma_f32 v240, v195, v83, v203
	v_fmac_f32_dpp v237, v148, v188 row_ror:1 row_mask:0xf bank_mask:0xf
	v_fmac_f32_dpp v238, v149, v189 row_ror:1 row_mask:0xf bank_mask:0xf
	v_fmac_f32_dpp v239, v150, v190 row_ror:1 row_mask:0xf bank_mask:0xf
	v_fmac_f32_dpp v240, v151, v191 row_ror:1 row_mask:0xf bank_mask:0xf
	v_fmac_f32_dpp v237, v152, v196 row_ror:15 row_mask:0xf bank_mask:0xf
	v_fmac_f32_dpp v238, v153, v197 row_ror:15 row_mask:0xf bank_mask:0xf
	v_fmac_f32_dpp v239, v154, v198 row_ror:15 row_mask:0xf bank_mask:0xf
	v_fmac_f32_dpp v240, v155, v199 row_ror:15 row_mask:0xf bank_mask:0xf
	v_mul_f32_e32 v148, 0xbfb8aa3b, v156
	v_mul_f32_e32 v149, 0xbfb8aa3b, v157
	v_mul_f32_e32 v150, 0xbfb8aa3b, v158
	v_mul_f32_e32 v151, 0xbfb8aa3b, v159
	v_exp_f32_e32 v148, v148
	v_exp_f32_e32 v149, v149
	v_exp_f32_e32 v150, v150
	v_exp_f32_e32 v151, v151
	v_add_f32_e32 v148, 1.0, v148
	v_add_f32_e32 v149, 1.0, v149
	v_add_f32_e32 v150, 1.0, v150
	v_add_f32_e32 v151, 1.0, v151
	v_rcp_f32_e32 v148, v148
	v_rcp_f32_e32 v149, v149
	v_rcp_f32_e32 v150, v150
	v_rcp_f32_e32 v151, v151
	v_mul_f32_e32 v156, v156, v148
	v_mul_f32_e32 v157, v157, v149
	v_mul_f32_e32 v158, v158, v150
	v_mul_f32_e32 v159, v159, v151
	v_mul_f32_e32 v156, v156, v237
	v_mul_f32_e32 v157, v157, v238
	v_mul_f32_e32 v158, v158, v239
	v_mul_f32_e32 v159, v159, v240
	v_cvt_pk_bf16_f32 v255, v156, v157
	v_cvt_pk_bf16_f32 v246, v158, v159
	global_load_dwordx4 v[124:127], v146, s[14:15] offset:64
	global_load_dwordx4 v[120:123], v147, s[14:15] offset:64
	global_load_dwordx4 v[116:119], v168, s[14:15] offset:64
	global_load_dwordx4 v[112:115], v169, s[14:15] offset:64
	global_load_dwordx4 v[100:103], v245, s[14:15] offset:64
	global_load_dwordx4 v[92:95], v252, s[14:15] offset:64
	global_load_dwordx4 v[104:107], v146, s[16:17] offset:64
	global_load_dwordx4 v[80:83], v169, s[16:17] offset:64
	ds_read_b128 v[160:163], v249 offset:7168
	ds_read_b128 v[164:167], v249 offset:7680
	s_waitcnt lgkmcnt(2)
	v_cndmask_b32_e32 v148, v72, v204, vcc
	v_cndmask_b32_e32 v149, v73, v205, vcc
	v_cndmask_b32_e32 v150, v74, v206, vcc
	v_cndmask_b32_e32 v151, v75, v207, vcc
	v_cndmask_b32_e64 v152, v72, v64, s[98:99]
	v_cndmask_b32_e64 v153, v73, v65, s[98:99]
	v_cndmask_b32_e64 v154, v74, v66, s[98:99]
	v_cndmask_b32_e64 v155, v75, v67, s[98:99]
	v_fma_f32 v156, v176, v72, v184
	v_fma_f32 v157, v177, v73, v185
	v_fma_f32 v158, v178, v74, v186
	v_fma_f32 v159, v179, v75, v187
	v_fmac_f32_dpp v156, v148, v172 row_ror:1 row_mask:0xf bank_mask:0xf
	v_fmac_f32_dpp v157, v149, v173 row_ror:1 row_mask:0xf bank_mask:0xf
	v_fmac_f32_dpp v158, v150, v174 row_ror:1 row_mask:0xf bank_mask:0xf
	v_fmac_f32_dpp v159, v151, v175 row_ror:1 row_mask:0xf bank_mask:0xf
	v_fmac_f32_dpp v156, v152, v180 row_ror:15 row_mask:0xf bank_mask:0xf
	v_fmac_f32_dpp v157, v153, v181 row_ror:15 row_mask:0xf bank_mask:0xf
	v_fmac_f32_dpp v158, v154, v182 row_ror:15 row_mask:0xf bank_mask:0xf
	v_fmac_f32_dpp v159, v155, v183 row_ror:15 row_mask:0xf bank_mask:0xf
	v_cndmask_b32_e32 v148, v48, v208, vcc
	v_cndmask_b32_e32 v149, v49, v209, vcc
	v_cndmask_b32_e32 v150, v50, v210, vcc
	v_cndmask_b32_e32 v151, v51, v211, vcc
	v_cndmask_b32_e64 v152, v48, v36, s[98:99]
	v_cndmask_b32_e64 v153, v49, v37, s[98:99]
	v_cndmask_b32_e64 v154, v50, v38, s[98:99]
	v_cndmask_b32_e64 v155, v51, v39, s[98:99]
	v_fma_f32 v237, v192, v48, v200
	v_fma_f32 v238, v193, v49, v201
	v_fma_f32 v239, v194, v50, v202
	v_fma_f32 v240, v195, v51, v203
	v_fmac_f32_dpp v237, v148, v188 row_ror:1 row_mask:0xf bank_mask:0xf
	v_fmac_f32_dpp v238, v149, v189 row_ror:1 row_mask:0xf bank_mask:0xf
	v_fmac_f32_dpp v239, v150, v190 row_ror:1 row_mask:0xf bank_mask:0xf
	v_fmac_f32_dpp v240, v151, v191 row_ror:1 row_mask:0xf bank_mask:0xf
	v_fmac_f32_dpp v237, v152, v196 row_ror:15 row_mask:0xf bank_mask:0xf
	v_fmac_f32_dpp v238, v153, v197 row_ror:15 row_mask:0xf bank_mask:0xf
	v_fmac_f32_dpp v239, v154, v198 row_ror:15 row_mask:0xf bank_mask:0xf
	v_fmac_f32_dpp v240, v155, v199 row_ror:15 row_mask:0xf bank_mask:0xf
	v_mul_f32_e32 v148, 0xbfb8aa3b, v156
	v_mul_f32_e32 v149, 0xbfb8aa3b, v157
	v_mul_f32_e32 v150, 0xbfb8aa3b, v158
	v_mul_f32_e32 v151, 0xbfb8aa3b, v159
	v_exp_f32_e32 v148, v148
	v_exp_f32_e32 v149, v149
	v_exp_f32_e32 v150, v150
	v_exp_f32_e32 v151, v151
	v_add_f32_e32 v148, 1.0, v148
	v_add_f32_e32 v149, 1.0, v149
	v_add_f32_e32 v150, 1.0, v150
	v_add_f32_e32 v151, 1.0, v151
	v_rcp_f32_e32 v148, v148
	v_rcp_f32_e32 v149, v149
	v_rcp_f32_e32 v150, v150
	v_rcp_f32_e32 v151, v151
	v_mul_f32_e32 v156, v156, v148
	v_mul_f32_e32 v157, v157, v149
	v_mul_f32_e32 v158, v158, v150
	v_mul_f32_e32 v159, v159, v151
	v_mul_f32_e32 v156, v156, v237
	v_mul_f32_e32 v157, v157, v238
	v_mul_f32_e32 v158, v158, v239
	v_mul_f32_e32 v159, v159, v240
	v_cvt_pk_bf16_f32 v247, v156, v157
	v_cvt_pk_bf16_f32 v248, v158, v159
	ds_read_b128 v[204:207], v249 offset:64
	ds_read_b128 v[208:211], v249 offset:576
	v_cndmask_b32_e32 v148, v64, v72, vcc
	v_cndmask_b32_e32 v149, v65, v73, vcc
	v_cndmask_b32_e32 v150, v66, v74, vcc
	v_cndmask_b32_e32 v151, v67, v75, vcc
	v_cndmask_b32_e64 v152, v64, v56, s[98:99]
	v_cndmask_b32_e64 v153, v65, v57, s[98:99]
	v_cndmask_b32_e64 v154, v66, v58, s[98:99]
	v_cndmask_b32_e64 v155, v67, v59, s[98:99]
	v_fma_f32 v156, v176, v64, v184
	v_fma_f32 v157, v177, v65, v185
	v_fma_f32 v158, v178, v66, v186
	v_fma_f32 v159, v179, v67, v187
	v_fmac_f32_dpp v156, v148, v172 row_ror:1 row_mask:0xf bank_mask:0xf
	v_fmac_f32_dpp v157, v149, v173 row_ror:1 row_mask:0xf bank_mask:0xf
	v_fmac_f32_dpp v158, v150, v174 row_ror:1 row_mask:0xf bank_mask:0xf
	v_fmac_f32_dpp v159, v151, v175 row_ror:1 row_mask:0xf bank_mask:0xf
	v_fmac_f32_dpp v156, v152, v180 row_ror:15 row_mask:0xf bank_mask:0xf
	v_fmac_f32_dpp v157, v153, v181 row_ror:15 row_mask:0xf bank_mask:0xf
	v_fmac_f32_dpp v158, v154, v182 row_ror:15 row_mask:0xf bank_mask:0xf
	v_fmac_f32_dpp v159, v155, v183 row_ror:15 row_mask:0xf bank_mask:0xf
	v_cndmask_b32_e32 v148, v36, v48, vcc
	v_cndmask_b32_e32 v149, v37, v49, vcc
	v_cndmask_b32_e32 v150, v38, v50, vcc
	v_cndmask_b32_e32 v151, v39, v51, vcc
	v_cndmask_b32_e64 v152, v36, v28, s[98:99]
	v_cndmask_b32_e64 v153, v37, v29, s[98:99]
	v_cndmask_b32_e64 v154, v38, v30, s[98:99]
	v_cndmask_b32_e64 v155, v39, v31, s[98:99]
	v_fma_f32 v237, v192, v36, v200
	v_fma_f32 v238, v193, v37, v201
	v_fma_f32 v239, v194, v38, v202
	v_fma_f32 v240, v195, v39, v203
	v_fmac_f32_dpp v237, v148, v188 row_ror:1 row_mask:0xf bank_mask:0xf
	v_fmac_f32_dpp v238, v149, v189 row_ror:1 row_mask:0xf bank_mask:0xf
	v_fmac_f32_dpp v239, v150, v190 row_ror:1 row_mask:0xf bank_mask:0xf
	v_fmac_f32_dpp v240, v151, v191 row_ror:1 row_mask:0xf bank_mask:0xf
	v_fmac_f32_dpp v237, v152, v196 row_ror:15 row_mask:0xf bank_mask:0xf
	v_fmac_f32_dpp v238, v153, v197 row_ror:15 row_mask:0xf bank_mask:0xf
	v_fmac_f32_dpp v239, v154, v198 row_ror:15 row_mask:0xf bank_mask:0xf
	v_fmac_f32_dpp v240, v155, v199 row_ror:15 row_mask:0xf bank_mask:0xf
	v_mul_f32_e32 v148, 0xbfb8aa3b, v156
	v_mul_f32_e32 v149, 0xbfb8aa3b, v157
	v_mul_f32_e32 v150, 0xbfb8aa3b, v158
	v_mul_f32_e32 v151, 0xbfb8aa3b, v159
	v_exp_f32_e32 v148, v148
	v_exp_f32_e32 v149, v149
	v_exp_f32_e32 v150, v150
	v_exp_f32_e32 v151, v151
	v_add_f32_e32 v148, 1.0, v148
	v_add_f32_e32 v149, 1.0, v149
	v_add_f32_e32 v150, 1.0, v150
	v_add_f32_e32 v151, 1.0, v151
	v_rcp_f32_e32 v148, v148
	v_rcp_f32_e32 v149, v149
	v_rcp_f32_e32 v150, v150
	v_rcp_f32_e32 v151, v151
	v_mul_f32_e32 v156, v156, v148
	v_mul_f32_e32 v157, v157, v149
	v_mul_f32_e32 v158, v158, v150
	v_mul_f32_e32 v159, v159, v151
	v_mul_f32_e32 v156, v156, v237
	v_mul_f32_e32 v157, v157, v238
	v_mul_f32_e32 v158, v158, v239
	v_mul_f32_e32 v159, v159, v240
	v_cvt_pk_bf16_f32 v72, v156, v157
	v_cvt_pk_bf16_f32 v73, v158, v159
	v_cndmask_b32_e32 v148, v56, v64, vcc
	v_cndmask_b32_e32 v149, v57, v65, vcc
	v_cndmask_b32_e32 v150, v58, v66, vcc
	v_cndmask_b32_e32 v151, v59, v67, vcc
	v_cndmask_b32_e64 v152, v56, v40, s[98:99]
	v_cndmask_b32_e64 v153, v57, v41, s[98:99]
	v_cndmask_b32_e64 v154, v58, v42, s[98:99]
	v_cndmask_b32_e64 v155, v59, v43, s[98:99]
	v_fma_f32 v156, v176, v56, v184
	v_fma_f32 v157, v177, v57, v185
	v_fma_f32 v158, v178, v58, v186
	v_fma_f32 v159, v179, v59, v187
	v_fmac_f32_dpp v156, v148, v172 row_ror:1 row_mask:0xf bank_mask:0xf
	v_fmac_f32_dpp v157, v149, v173 row_ror:1 row_mask:0xf bank_mask:0xf
	v_fmac_f32_dpp v158, v150, v174 row_ror:1 row_mask:0xf bank_mask:0xf
	v_fmac_f32_dpp v159, v151, v175 row_ror:1 row_mask:0xf bank_mask:0xf
	v_fmac_f32_dpp v156, v152, v180 row_ror:15 row_mask:0xf bank_mask:0xf
	v_fmac_f32_dpp v157, v153, v181 row_ror:15 row_mask:0xf bank_mask:0xf
	v_fmac_f32_dpp v158, v154, v182 row_ror:15 row_mask:0xf bank_mask:0xf
	v_fmac_f32_dpp v159, v155, v183 row_ror:15 row_mask:0xf bank_mask:0xf
	v_cndmask_b32_e32 v148, v28, v36, vcc
	v_cndmask_b32_e32 v149, v29, v37, vcc
	v_cndmask_b32_e32 v150, v30, v38, vcc
	v_cndmask_b32_e32 v151, v31, v39, vcc
	v_cndmask_b32_e64 v152, v28, v16, s[98:99]
	v_cndmask_b32_e64 v153, v29, v17, s[98:99]
	v_cndmask_b32_e64 v154, v30, v18, s[98:99]
	v_cndmask_b32_e64 v155, v31, v19, s[98:99]
	v_fma_f32 v237, v192, v28, v200
	v_fma_f32 v238, v193, v29, v201
	v_fma_f32 v239, v194, v30, v202
	v_fma_f32 v240, v195, v31, v203
	v_fmac_f32_dpp v237, v148, v188 row_ror:1 row_mask:0xf bank_mask:0xf
	v_fmac_f32_dpp v238, v149, v189 row_ror:1 row_mask:0xf bank_mask:0xf
	v_fmac_f32_dpp v239, v150, v190 row_ror:1 row_mask:0xf bank_mask:0xf
	v_fmac_f32_dpp v240, v151, v191 row_ror:1 row_mask:0xf bank_mask:0xf
	v_fmac_f32_dpp v237, v152, v196 row_ror:15 row_mask:0xf bank_mask:0xf
	v_fmac_f32_dpp v238, v153, v197 row_ror:15 row_mask:0xf bank_mask:0xf
	v_fmac_f32_dpp v239, v154, v198 row_ror:15 row_mask:0xf bank_mask:0xf
	v_fmac_f32_dpp v240, v155, v199 row_ror:15 row_mask:0xf bank_mask:0xf
	v_mul_f32_e32 v148, 0xbfb8aa3b, v156
	v_mul_f32_e32 v149, 0xbfb8aa3b, v157
	v_mul_f32_e32 v150, 0xbfb8aa3b, v158
	v_mul_f32_e32 v151, 0xbfb8aa3b, v159
	v_exp_f32_e32 v148, v148
	v_exp_f32_e32 v149, v149
	v_exp_f32_e32 v150, v150
	v_exp_f32_e32 v151, v151
	v_add_f32_e32 v148, 1.0, v148
	v_add_f32_e32 v149, 1.0, v149
	v_add_f32_e32 v150, 1.0, v150
	v_add_f32_e32 v151, 1.0, v151
	v_rcp_f32_e32 v148, v148
	v_rcp_f32_e32 v149, v149
	v_rcp_f32_e32 v150, v150
	v_rcp_f32_e32 v151, v151
	v_mul_f32_e32 v156, v156, v148
	v_mul_f32_e32 v157, v157, v149
	v_mul_f32_e32 v158, v158, v150
	v_mul_f32_e32 v159, v159, v151
	v_mul_f32_e32 v156, v156, v237
	v_mul_f32_e32 v157, v157, v238
	v_mul_f32_e32 v158, v158, v239
	v_mul_f32_e32 v159, v159, v240
	v_cvt_pk_bf16_f32 v74, v156, v157
	v_cvt_pk_bf16_f32 v75, v158, v159
	s_waitcnt lgkmcnt(2)
	v_cndmask_b32_e32 v148, v40, v56, vcc
	v_cndmask_b32_e32 v149, v41, v57, vcc
	v_cndmask_b32_e32 v150, v42, v58, vcc
	v_cndmask_b32_e32 v151, v43, v59, vcc
	v_cndmask_b32_e64 v152, v40, v160, s[98:99]
	v_cndmask_b32_e64 v153, v41, v161, s[98:99]
	v_cndmask_b32_e64 v154, v42, v162, s[98:99]
	v_cndmask_b32_e64 v155, v43, v163, s[98:99]
	v_fma_f32 v156, v176, v40, v184
	v_fma_f32 v157, v177, v41, v185
	v_fma_f32 v158, v178, v42, v186
	v_fma_f32 v159, v179, v43, v187
	v_fmac_f32_dpp v156, v148, v172 row_ror:1 row_mask:0xf bank_mask:0xf
	v_fmac_f32_dpp v157, v149, v173 row_ror:1 row_mask:0xf bank_mask:0xf
	v_fmac_f32_dpp v158, v150, v174 row_ror:1 row_mask:0xf bank_mask:0xf
	v_fmac_f32_dpp v159, v151, v175 row_ror:1 row_mask:0xf bank_mask:0xf
	v_fmac_f32_dpp v156, v152, v180 row_ror:15 row_mask:0xf bank_mask:0xf
	v_fmac_f32_dpp v157, v153, v181 row_ror:15 row_mask:0xf bank_mask:0xf
	v_fmac_f32_dpp v158, v154, v182 row_ror:15 row_mask:0xf bank_mask:0xf
	v_fmac_f32_dpp v159, v155, v183 row_ror:15 row_mask:0xf bank_mask:0xf
	v_cndmask_b32_e32 v148, v16, v28, vcc
	v_cndmask_b32_e32 v149, v17, v29, vcc
	v_cndmask_b32_e32 v150, v18, v30, vcc
	v_cndmask_b32_e32 v151, v19, v31, vcc
	v_cndmask_b32_e64 v152, v16, v164, s[98:99]
	v_cndmask_b32_e64 v153, v17, v165, s[98:99]
	v_cndmask_b32_e64 v154, v18, v166, s[98:99]
	v_cndmask_b32_e64 v155, v19, v167, s[98:99]
	v_fma_f32 v237, v192, v16, v200
	v_fma_f32 v238, v193, v17, v201
	v_fma_f32 v239, v194, v18, v202
	v_fma_f32 v240, v195, v19, v203
	v_fmac_f32_dpp v237, v148, v188 row_ror:1 row_mask:0xf bank_mask:0xf
	v_fmac_f32_dpp v238, v149, v189 row_ror:1 row_mask:0xf bank_mask:0xf
	v_fmac_f32_dpp v239, v150, v190 row_ror:1 row_mask:0xf bank_mask:0xf
	v_fmac_f32_dpp v240, v151, v191 row_ror:1 row_mask:0xf bank_mask:0xf
	v_fmac_f32_dpp v237, v152, v196 row_ror:15 row_mask:0xf bank_mask:0xf
	v_fmac_f32_dpp v238, v153, v197 row_ror:15 row_mask:0xf bank_mask:0xf
	v_fmac_f32_dpp v239, v154, v198 row_ror:15 row_mask:0xf bank_mask:0xf
	v_fmac_f32_dpp v240, v155, v199 row_ror:15 row_mask:0xf bank_mask:0xf
	v_mul_f32_e32 v148, 0xbfb8aa3b, v156
	v_mul_f32_e32 v149, 0xbfb8aa3b, v157
	v_mul_f32_e32 v150, 0xbfb8aa3b, v158
	v_mul_f32_e32 v151, 0xbfb8aa3b, v159
	v_exp_f32_e32 v148, v148
	v_exp_f32_e32 v149, v149
	v_exp_f32_e32 v150, v150
	v_exp_f32_e32 v151, v151
	v_add_f32_e32 v148, 1.0, v148
	v_add_f32_e32 v149, 1.0, v149
	v_add_f32_e32 v150, 1.0, v150
	v_add_f32_e32 v151, 1.0, v151
	v_rcp_f32_e32 v148, v148
	v_rcp_f32_e32 v149, v149
	v_rcp_f32_e32 v150, v150
	v_rcp_f32_e32 v151, v151
	v_mul_f32_e32 v156, v156, v148
	v_mul_f32_e32 v157, v157, v149
	v_mul_f32_e32 v158, v158, v150
	v_mul_f32_e32 v159, v159, v151
	v_mul_f32_e32 v156, v156, v237
	v_mul_f32_e32 v157, v157, v238
	v_mul_f32_e32 v158, v158, v239
	v_mul_f32_e32 v159, v159, v240
	v_cvt_pk_bf16_f32 v48, v156, v157
	v_cvt_pk_bf16_f32 v49, v158, v159
	ds_read_b128 v[160:163], v249 offset:3136
	ds_read_b128 v[164:167], v249 offset:3648
	s_waitcnt vmcnt(0) lgkmcnt(0)
	v_mbcnt_lo_u32_b32 v146, -1, 0
	v_mbcnt_hi_u32_b32 v146, -1, v146
	v_bfe_i32 v146, v146, 4, 1
	v_cndmask_b32_e32 v148, v108, v204, vcc
	v_cndmask_b32_e32 v149, v109, v205, vcc
	v_cndmask_b32_e32 v150, v110, v206, vcc
	v_cndmask_b32_e32 v151, v111, v207, vcc
	v_cndmask_b32_e64 v152, v108, v96, s[98:99]
	v_cndmask_b32_e64 v153, v109, v97, s[98:99]
	v_cndmask_b32_e64 v154, v110, v98, s[98:99]
	v_cndmask_b32_e64 v155, v111, v99, s[98:99]
	v_fma_f32 v156, v120, v108, v104
	v_fma_f32 v157, v121, v109, v105
	v_fma_f32 v158, v122, v110, v106
	v_fma_f32 v159, v123, v111, v107
	v_fmac_f32_dpp v156, v148, v124 row_ror:1 row_mask:0xf bank_mask:0xf
	v_fmac_f32_dpp v157, v149, v125 row_ror:1 row_mask:0xf bank_mask:0xf
	v_fmac_f32_dpp v158, v150, v126 row_ror:1 row_mask:0xf bank_mask:0xf
	v_fmac_f32_dpp v159, v151, v127 row_ror:1 row_mask:0xf bank_mask:0xf
	v_fmac_f32_dpp v156, v152, v116 row_ror:15 row_mask:0xf bank_mask:0xf
	v_fmac_f32_dpp v157, v153, v117 row_ror:15 row_mask:0xf bank_mask:0xf
	v_fmac_f32_dpp v158, v154, v118 row_ror:15 row_mask:0xf bank_mask:0xf
	v_fmac_f32_dpp v159, v155, v119 row_ror:15 row_mask:0xf bank_mask:0xf
	v_cndmask_b32_e32 v148, v84, v208, vcc
	v_cndmask_b32_e32 v149, v85, v209, vcc
	v_cndmask_b32_e32 v150, v86, v210, vcc
	v_cndmask_b32_e32 v151, v87, v211, vcc
	v_cndmask_b32_e64 v152, v84, v68, s[98:99]
	v_cndmask_b32_e64 v153, v85, v69, s[98:99]
	v_cndmask_b32_e64 v154, v86, v70, s[98:99]
	v_cndmask_b32_e64 v155, v87, v71, s[98:99]
	v_fma_f32 v237, v100, v84, v80
	v_fma_f32 v238, v101, v85, v81
	v_fma_f32 v239, v102, v86, v82
	v_fma_f32 v240, v103, v87, v83
	v_fmac_f32_dpp v237, v148, v112 row_ror:1 row_mask:0xf bank_mask:0xf
	v_fmac_f32_dpp v238, v149, v113 row_ror:1 row_mask:0xf bank_mask:0xf
	v_fmac_f32_dpp v239, v150, v114 row_ror:1 row_mask:0xf bank_mask:0xf
	v_fmac_f32_dpp v240, v151, v115 row_ror:1 row_mask:0xf bank_mask:0xf
	v_fmac_f32_dpp v237, v152, v92 row_ror:15 row_mask:0xf bank_mask:0xf
	v_fmac_f32_dpp v238, v153, v93 row_ror:15 row_mask:0xf bank_mask:0xf
	v_fmac_f32_dpp v239, v154, v94 row_ror:15 row_mask:0xf bank_mask:0xf
	v_fmac_f32_dpp v240, v155, v95 row_ror:15 row_mask:0xf bank_mask:0xf
	v_mul_f32_e32 v148, 0xbfb8aa3b, v156
	v_mul_f32_e32 v149, 0xbfb8aa3b, v157
	v_mul_f32_e32 v150, 0xbfb8aa3b, v158
	v_mul_f32_e32 v151, 0xbfb8aa3b, v159
	v_exp_f32_e32 v148, v148
	v_exp_f32_e32 v149, v149
	v_exp_f32_e32 v150, v150
	v_exp_f32_e32 v151, v151
	v_add_f32_e32 v148, 1.0, v148
	v_add_f32_e32 v149, 1.0, v149
	v_add_f32_e32 v150, 1.0, v150
	v_add_f32_e32 v151, 1.0, v151
	v_rcp_f32_e32 v148, v148
	v_rcp_f32_e32 v149, v149
	v_rcp_f32_e32 v150, v150
	v_rcp_f32_e32 v151, v151
	v_mul_f32_e32 v156, v156, v148
	v_mul_f32_e32 v157, v157, v149
	v_mul_f32_e32 v158, v158, v150
	v_mul_f32_e32 v159, v159, v151
	v_mul_f32_e32 v156, v156, v237
	v_mul_f32_e32 v157, v157, v238
	v_mul_f32_e32 v158, v158, v239
	v_mul_f32_e32 v159, v159, v240
	v_cvt_pk_bf16_f32 v40, v156, v157
	v_cvt_pk_bf16_f32 v41, v158, v159
	v_bfi_b32 v18, v146, v241, v40
	v_bfi_b32 v19, v146, v242, v41
	ds_swizzle_b32 v16, v18 offset:0x401f
	ds_swizzle_b32 v17, v19 offset:0x401f
	v_mov_b32_e32 v42, v250
	v_lshrrev_b32_e32 v152, 6, v251
	s_nop 1
	v_readfirstlane_b32 s100, v152
	s_waitcnt lgkmcnt(0)
	v_bfi_b32 v148, v146, v16, v241
	v_bfi_b32 v149, v146, v17, v242
	v_bfi_b32 v150, v146, v40, v16
	v_bfi_b32 v151, v146, v41, v17
	s_cmp_eq_u32 s100, 0
	s_cselect_b64 s[100:101], s[98:99], 0
	s_andn2_b64 exec, exec, s[100:101]
	global_store_dwordx4 v42, v[148:151], s[12:13] sc1
	s_mov_b64 exec, -1
	s_nop 1
	ds_read_b128 v[204:207], v249 offset:4160
	ds_read_b128 v[208:211], v249 offset:4672
	v_cndmask_b32_e32 v148, v96, v108, vcc
	v_cndmask_b32_e32 v149, v97, v109, vcc
	v_cndmask_b32_e32 v150, v98, v110, vcc
	v_cndmask_b32_e32 v151, v99, v111, vcc
	v_cndmask_b32_e64 v152, v96, v88, s[98:99]
	v_cndmask_b32_e64 v153, v97, v89, s[98:99]
	v_cndmask_b32_e64 v154, v98, v90, s[98:99]
	v_cndmask_b32_e64 v155, v99, v91, s[98:99]
	v_fma_f32 v156, v120, v96, v104
	v_fma_f32 v157, v121, v97, v105
	v_fma_f32 v158, v122, v98, v106
	v_fma_f32 v159, v123, v99, v107
	v_fmac_f32_dpp v156, v148, v124 row_ror:1 row_mask:0xf bank_mask:0xf
	v_fmac_f32_dpp v157, v149, v125 row_ror:1 row_mask:0xf bank_mask:0xf
	v_fmac_f32_dpp v158, v150, v126 row_ror:1 row_mask:0xf bank_mask:0xf
	v_fmac_f32_dpp v159, v151, v127 row_ror:1 row_mask:0xf bank_mask:0xf
	v_fmac_f32_dpp v156, v152, v116 row_ror:15 row_mask:0xf bank_mask:0xf
	v_fmac_f32_dpp v157, v153, v117 row_ror:15 row_mask:0xf bank_mask:0xf
	v_fmac_f32_dpp v158, v154, v118 row_ror:15 row_mask:0xf bank_mask:0xf
	v_fmac_f32_dpp v159, v155, v119 row_ror:15 row_mask:0xf bank_mask:0xf
	v_cndmask_b32_e32 v148, v68, v84, vcc
	v_cndmask_b32_e32 v149, v69, v85, vcc
	v_cndmask_b32_e32 v150, v70, v86, vcc
	v_cndmask_b32_e32 v151, v71, v87, vcc
	v_cndmask_b32_e64 v152, v68, v60, s[98:99]
	v_cndmask_b32_e64 v153, v69, v61, s[98:99]
	v_cndmask_b32_e64 v154, v70, v62, s[98:99]
	v_cndmask_b32_e64 v155, v71, v63, s[98:99]
	v_fma_f32 v237, v100, v68, v80
	v_fma_f32 v238, v101, v69, v81
	v_fma_f32 v239, v102, v70, v82
	v_fma_f32 v240, v103, v71, v83
	v_fmac_f32_dpp v237, v148, v112 row_ror:1 row_mask:0xf bank_mask:0xf
	v_fmac_f32_dpp v238, v149, v113 row_ror:1 row_mask:0xf bank_mask:0xf
	v_fmac_f32_dpp v239, v150, v114 row_ror:1 row_mask:0xf bank_mask:0xf
	v_fmac_f32_dpp v240, v151, v115 row_ror:1 row_mask:0xf bank_mask:0xf
	v_fmac_f32_dpp v237, v152, v92 row_ror:15 row_mask:0xf bank_mask:0xf
	v_fmac_f32_dpp v238, v153, v93 row_ror:15 row_mask:0xf bank_mask:0xf
	v_fmac_f32_dpp v239, v154, v94 row_ror:15 row_mask:0xf bank_mask:0xf
	v_fmac_f32_dpp v240, v155, v95 row_ror:15 row_mask:0xf bank_mask:0xf
	v_mul_f32_e32 v148, 0xbfb8aa3b, v156
	v_mul_f32_e32 v149, 0xbfb8aa3b, v157
	v_mul_f32_e32 v150, 0xbfb8aa3b, v158
	v_mul_f32_e32 v151, 0xbfb8aa3b, v159
	v_exp_f32_e32 v148, v148
	v_exp_f32_e32 v149, v149
	v_exp_f32_e32 v150, v150
	v_exp_f32_e32 v151, v151
	v_add_f32_e32 v148, 1.0, v148
	v_add_f32_e32 v149, 1.0, v149
	v_add_f32_e32 v150, 1.0, v150
	v_add_f32_e32 v151, 1.0, v151
	v_rcp_f32_e32 v148, v148
	v_rcp_f32_e32 v149, v149
	v_rcp_f32_e32 v150, v150
	v_rcp_f32_e32 v151, v151
	v_mul_f32_e32 v156, v156, v148
	v_mul_f32_e32 v157, v157, v149
	v_mul_f32_e32 v158, v158, v150
	v_mul_f32_e32 v159, v159, v151
	v_mul_f32_e32 v156, v156, v237
	v_mul_f32_e32 v157, v157, v238
	v_mul_f32_e32 v158, v158, v239
	v_mul_f32_e32 v159, v159, v240
	v_cvt_pk_bf16_f32 v40, v156, v157
	v_cvt_pk_bf16_f32 v41, v158, v159
	v_bfi_b32 v18, v146, v243, v40
	v_bfi_b32 v19, v146, v244, v41
	ds_swizzle_b32 v16, v18 offset:0x401f
	ds_swizzle_b32 v17, v19 offset:0x401f
	v_add_u32_e32 v42, 0x16000, v250
	s_waitcnt lgkmcnt(0)
	v_bfi_b32 v148, v146, v16, v243
	v_bfi_b32 v149, v146, v17, v244
	v_bfi_b32 v150, v146, v40, v16
	v_bfi_b32 v151, v146, v41, v17
	global_store_dwordx4 v42, v[148:151], s[12:13] sc1
	s_nop 1
	v_cndmask_b32_e32 v148, v88, v96, vcc
	v_cndmask_b32_e32 v149, v89, v97, vcc
	v_cndmask_b32_e32 v150, v90, v98, vcc
	v_cndmask_b32_e32 v151, v91, v99, vcc
	v_cndmask_b32_e64 v152, v88, v76, s[98:99]
	v_cndmask_b32_e64 v153, v89, v77, s[98:99]
	v_cndmask_b32_e64 v154, v90, v78, s[98:99]
	v_cndmask_b32_e64 v155, v91, v79, s[98:99]
	v_fma_f32 v156, v120, v88, v104
	v_fma_f32 v157, v121, v89, v105
	v_fma_f32 v158, v122, v90, v106
	v_fma_f32 v159, v123, v91, v107
	v_fmac_f32_dpp v156, v148, v124 row_ror:1 row_mask:0xf bank_mask:0xf
	v_fmac_f32_dpp v157, v149, v125 row_ror:1 row_mask:0xf bank_mask:0xf
	v_fmac_f32_dpp v158, v150, v126 row_ror:1 row_mask:0xf bank_mask:0xf
	v_fmac_f32_dpp v159, v151, v127 row_ror:1 row_mask:0xf bank_mask:0xf
	v_fmac_f32_dpp v156, v152, v116 row_ror:15 row_mask:0xf bank_mask:0xf
	v_fmac_f32_dpp v157, v153, v117 row_ror:15 row_mask:0xf bank_mask:0xf
	v_fmac_f32_dpp v158, v154, v118 row_ror:15 row_mask:0xf bank_mask:0xf
	v_fmac_f32_dpp v159, v155, v119 row_ror:15 row_mask:0xf bank_mask:0xf
	v_cndmask_b32_e32 v148, v60, v68, vcc
	v_cndmask_b32_e32 v149, v61, v69, vcc
	v_cndmask_b32_e32 v150, v62, v70, vcc
	v_cndmask_b32_e32 v151, v63, v71, vcc
	v_cndmask_b32_e64 v152, v60, v52, s[98:99]
	v_cndmask_b32_e64 v153, v61, v53, s[98:99]
	v_cndmask_b32_e64 v154, v62, v54, s[98:99]
	v_cndmask_b32_e64 v155, v63, v55, s[98:99]
	v_fma_f32 v237, v100, v60, v80
	v_fma_f32 v238, v101, v61, v81
	v_fma_f32 v239, v102, v62, v82
	v_fma_f32 v240, v103, v63, v83
	v_fmac_f32_dpp v237, v148, v112 row_ror:1 row_mask:0xf bank_mask:0xf
	v_fmac_f32_dpp v238, v149, v113 row_ror:1 row_mask:0xf bank_mask:0xf
	v_fmac_f32_dpp v239, v150, v114 row_ror:1 row_mask:0xf bank_mask:0xf
	v_fmac_f32_dpp v240, v151, v115 row_ror:1 row_mask:0xf bank_mask:0xf
	v_fmac_f32_dpp v237, v152, v92 row_ror:15 row_mask:0xf bank_mask:0xf
	v_fmac_f32_dpp v238, v153, v93 row_ror:15 row_mask:0xf bank_mask:0xf
	v_fmac_f32_dpp v239, v154, v94 row_ror:15 row_mask:0xf bank_mask:0xf
	v_fmac_f32_dpp v240, v155, v95 row_ror:15 row_mask:0xf bank_mask:0xf
	v_mul_f32_e32 v148, 0xbfb8aa3b, v156
	v_mul_f32_e32 v149, 0xbfb8aa3b, v157
	v_mul_f32_e32 v150, 0xbfb8aa3b, v158
	v_mul_f32_e32 v151, 0xbfb8aa3b, v159
	v_exp_f32_e32 v148, v148
	v_exp_f32_e32 v149, v149
	v_exp_f32_e32 v150, v150
	v_exp_f32_e32 v151, v151
	v_add_f32_e32 v148, 1.0, v148
	v_add_f32_e32 v149, 1.0, v149
	v_add_f32_e32 v150, 1.0, v150
	v_add_f32_e32 v151, 1.0, v151
	v_rcp_f32_e32 v148, v148
	v_rcp_f32_e32 v149, v149
	v_rcp_f32_e32 v150, v150
	v_rcp_f32_e32 v151, v151
	v_mul_f32_e32 v156, v156, v148
	v_mul_f32_e32 v157, v157, v149
	v_mul_f32_e32 v158, v158, v150
	v_mul_f32_e32 v159, v159, v151
	v_mul_f32_e32 v156, v156, v237
	v_mul_f32_e32 v157, v157, v238
	v_mul_f32_e32 v158, v158, v239
	v_mul_f32_e32 v159, v159, v240
	v_cvt_pk_bf16_f32 v40, v156, v157
	v_cvt_pk_bf16_f32 v41, v158, v159
	v_bfi_b32 v18, v146, v253, v40
	v_bfi_b32 v19, v146, v254, v41
	ds_swizzle_b32 v16, v18 offset:0x401f
	ds_swizzle_b32 v17, v19 offset:0x401f
	v_add_u32_e32 v42, 0x2c000, v250
	s_waitcnt lgkmcnt(0)
	v_bfi_b32 v148, v146, v16, v253
	v_bfi_b32 v149, v146, v17, v254
	v_bfi_b32 v150, v146, v40, v16
	v_bfi_b32 v151, v146, v41, v17
	global_store_dwordx4 v42, v[148:151], s[12:13] sc1
	s_nop 1
	v_cndmask_b32_e32 v148, v76, v88, vcc
	v_cndmask_b32_e32 v149, v77, v89, vcc
	v_cndmask_b32_e32 v150, v78, v90, vcc
	v_cndmask_b32_e32 v151, v79, v91, vcc
	v_cndmask_b32_e64 v152, v76, v160, s[98:99]
	v_cndmask_b32_e64 v153, v77, v161, s[98:99]
	v_cndmask_b32_e64 v154, v78, v162, s[98:99]
	v_cndmask_b32_e64 v155, v79, v163, s[98:99]
	v_fma_f32 v156, v120, v76, v104
	v_fma_f32 v157, v121, v77, v105
	v_fma_f32 v158, v122, v78, v106
	v_fma_f32 v159, v123, v79, v107
	v_fmac_f32_dpp v156, v148, v124 row_ror:1 row_mask:0xf bank_mask:0xf
	v_fmac_f32_dpp v157, v149, v125 row_ror:1 row_mask:0xf bank_mask:0xf
	v_fmac_f32_dpp v158, v150, v126 row_ror:1 row_mask:0xf bank_mask:0xf
	v_fmac_f32_dpp v159, v151, v127 row_ror:1 row_mask:0xf bank_mask:0xf
	v_fmac_f32_dpp v156, v152, v116 row_ror:15 row_mask:0xf bank_mask:0xf
	v_fmac_f32_dpp v157, v153, v117 row_ror:15 row_mask:0xf bank_mask:0xf
	v_fmac_f32_dpp v158, v154, v118 row_ror:15 row_mask:0xf bank_mask:0xf
	v_fmac_f32_dpp v159, v155, v119 row_ror:15 row_mask:0xf bank_mask:0xf
	v_cndmask_b32_e32 v148, v52, v60, vcc
	v_cndmask_b32_e32 v149, v53, v61, vcc
	v_cndmask_b32_e32 v150, v54, v62, vcc
	v_cndmask_b32_e32 v151, v55, v63, vcc
	v_cndmask_b32_e64 v152, v52, v164, s[98:99]
	v_cndmask_b32_e64 v153, v53, v165, s[98:99]
	v_cndmask_b32_e64 v154, v54, v166, s[98:99]
	v_cndmask_b32_e64 v155, v55, v167, s[98:99]
	v_fma_f32 v237, v100, v52, v80
	v_fma_f32 v238, v101, v53, v81
	v_fma_f32 v239, v102, v54, v82
	v_fma_f32 v240, v103, v55, v83
	v_fmac_f32_dpp v237, v148, v112 row_ror:1 row_mask:0xf bank_mask:0xf
	v_fmac_f32_dpp v238, v149, v113 row_ror:1 row_mask:0xf bank_mask:0xf
	v_fmac_f32_dpp v239, v150, v114 row_ror:1 row_mask:0xf bank_mask:0xf
	v_fmac_f32_dpp v240, v151, v115 row_ror:1 row_mask:0xf bank_mask:0xf
	v_fmac_f32_dpp v237, v152, v92 row_ror:15 row_mask:0xf bank_mask:0xf
	v_fmac_f32_dpp v238, v153, v93 row_ror:15 row_mask:0xf bank_mask:0xf
	v_fmac_f32_dpp v239, v154, v94 row_ror:15 row_mask:0xf bank_mask:0xf
	v_fmac_f32_dpp v240, v155, v95 row_ror:15 row_mask:0xf bank_mask:0xf
	v_mul_f32_e32 v148, 0xbfb8aa3b, v156
	v_mul_f32_e32 v149, 0xbfb8aa3b, v157
	v_mul_f32_e32 v150, 0xbfb8aa3b, v158
	v_mul_f32_e32 v151, 0xbfb8aa3b, v159
	v_exp_f32_e32 v148, v148
	v_exp_f32_e32 v149, v149
	v_exp_f32_e32 v150, v150
	v_exp_f32_e32 v151, v151
	v_add_f32_e32 v148, 1.0, v148
	v_add_f32_e32 v149, 1.0, v149
	v_add_f32_e32 v150, 1.0, v150
	v_add_f32_e32 v151, 1.0, v151
	v_rcp_f32_e32 v148, v148
	v_rcp_f32_e32 v149, v149
	v_rcp_f32_e32 v150, v150
	v_rcp_f32_e32 v151, v151
	v_mul_f32_e32 v156, v156, v148
	v_mul_f32_e32 v157, v157, v149
	v_mul_f32_e32 v158, v158, v150
	v_mul_f32_e32 v159, v159, v151
	v_mul_f32_e32 v156, v156, v237
	v_mul_f32_e32 v157, v157, v238
	v_mul_f32_e32 v158, v158, v239
	v_mul_f32_e32 v159, v159, v240
	v_cvt_pk_bf16_f32 v40, v156, v157
	v_cvt_pk_bf16_f32 v41, v158, v159
	v_bfi_b32 v18, v146, v255, v40
	v_bfi_b32 v19, v146, v246, v41
	ds_swizzle_b32 v16, v18 offset:0x401f
	ds_swizzle_b32 v17, v19 offset:0x401f
	v_add_u32_e32 v42, 0x42000, v250
	s_waitcnt lgkmcnt(0)
	v_bfi_b32 v148, v146, v16, v255
	v_bfi_b32 v149, v146, v17, v246
	v_bfi_b32 v150, v146, v40, v16
	v_bfi_b32 v151, v146, v41, v17
	global_store_dwordx4 v42, v[148:151], s[12:13] sc1
	s_nop 1
	ds_read_b128 v[160:163], v249 offset:7232
	ds_read_b128 v[164:167], v249 offset:7744
	s_waitcnt lgkmcnt(2)
	v_cndmask_b32_e32 v148, v44, v204, vcc
	v_cndmask_b32_e32 v149, v45, v205, vcc
	v_cndmask_b32_e32 v150, v46, v206, vcc
	v_cndmask_b32_e32 v151, v47, v207, vcc
	v_cndmask_b32_e64 v152, v44, v32, s[98:99]
	v_cndmask_b32_e64 v153, v45, v33, s[98:99]
	v_cndmask_b32_e64 v154, v46, v34, s[98:99]
	v_cndmask_b32_e64 v155, v47, v35, s[98:99]
	v_fma_f32 v156, v120, v44, v104
	v_fma_f32 v157, v121, v45, v105
	v_fma_f32 v158, v122, v46, v106
	v_fma_f32 v159, v123, v47, v107
	v_fmac_f32_dpp v156, v148, v124 row_ror:1 row_mask:0xf bank_mask:0xf
	v_fmac_f32_dpp v157, v149, v125 row_ror:1 row_mask:0xf bank_mask:0xf
	v_fmac_f32_dpp v158, v150, v126 row_ror:1 row_mask:0xf bank_mask:0xf
	v_fmac_f32_dpp v159, v151, v127 row_ror:1 row_mask:0xf bank_mask:0xf
	v_fmac_f32_dpp v156, v152, v116 row_ror:15 row_mask:0xf bank_mask:0xf
	v_fmac_f32_dpp v157, v153, v117 row_ror:15 row_mask:0xf bank_mask:0xf
	v_fmac_f32_dpp v158, v154, v118 row_ror:15 row_mask:0xf bank_mask:0xf
	v_fmac_f32_dpp v159, v155, v119 row_ror:15 row_mask:0xf bank_mask:0xf
	v_cndmask_b32_e32 v148, v20, v208, vcc
	v_cndmask_b32_e32 v149, v21, v209, vcc
	v_cndmask_b32_e32 v150, v22, v210, vcc
	v_cndmask_b32_e32 v151, v23, v211, vcc
	v_cndmask_b32_e64 v152, v20, v8, s[98:99]
	v_cndmask_b32_e64 v153, v21, v9, s[98:99]
	v_cndmask_b32_e64 v154, v22, v10, s[98:99]
	v_cndmask_b32_e64 v155, v23, v11, s[98:99]
	v_fma_f32 v237, v100, v20, v80
	v_fma_f32 v238, v101, v21, v81
	v_fma_f32 v239, v102, v22, v82
	v_fma_f32 v240, v103, v23, v83
	v_fmac_f32_dpp v237, v148, v112 row_ror:1 row_mask:0xf bank_mask:0xf
	v_fmac_f32_dpp v238, v149, v113 row_ror:1 row_mask:0xf bank_mask:0xf
	v_fmac_f32_dpp v239, v150, v114 row_ror:1 row_mask:0xf bank_mask:0xf
	v_fmac_f32_dpp v240, v151, v115 row_ror:1 row_mask:0xf bank_mask:0xf
	v_fmac_f32_dpp v237, v152, v92 row_ror:15 row_mask:0xf bank_mask:0xf
	v_fmac_f32_dpp v238, v153, v93 row_ror:15 row_mask:0xf bank_mask:0xf
	v_fmac_f32_dpp v239, v154, v94 row_ror:15 row_mask:0xf bank_mask:0xf
	v_fmac_f32_dpp v240, v155, v95 row_ror:15 row_mask:0xf bank_mask:0xf
	v_mul_f32_e32 v148, 0xbfb8aa3b, v156
	v_mul_f32_e32 v149, 0xbfb8aa3b, v157
	v_mul_f32_e32 v150, 0xbfb8aa3b, v158
	v_mul_f32_e32 v151, 0xbfb8aa3b, v159
	v_exp_f32_e32 v148, v148
	v_exp_f32_e32 v149, v149
	v_exp_f32_e32 v150, v150
	v_exp_f32_e32 v151, v151
	v_add_f32_e32 v148, 1.0, v148
	v_add_f32_e32 v149, 1.0, v149
	v_add_f32_e32 v150, 1.0, v150
	v_add_f32_e32 v151, 1.0, v151
	v_rcp_f32_e32 v148, v148
	v_rcp_f32_e32 v149, v149
	v_rcp_f32_e32 v150, v150
	v_rcp_f32_e32 v151, v151
	v_mul_f32_e32 v156, v156, v148
	v_mul_f32_e32 v157, v157, v149
	v_mul_f32_e32 v158, v158, v150
	v_mul_f32_e32 v159, v159, v151
	v_mul_f32_e32 v156, v156, v237
	v_mul_f32_e32 v157, v157, v238
	v_mul_f32_e32 v158, v158, v239
	v_mul_f32_e32 v159, v159, v240
	v_cvt_pk_bf16_f32 v40, v156, v157
	v_cvt_pk_bf16_f32 v41, v158, v159
	v_bfi_b32 v18, v146, v247, v40
	v_bfi_b32 v19, v146, v248, v41
	ds_swizzle_b32 v16, v18 offset:0x401f
	ds_swizzle_b32 v17, v19 offset:0x401f
	v_add_u32_e32 v42, 0xb0000, v250
	s_waitcnt lgkmcnt(0)
	v_bfi_b32 v148, v146, v16, v247
	v_bfi_b32 v149, v146, v17, v248
	v_bfi_b32 v150, v146, v40, v16
	v_bfi_b32 v151, v146, v41, v17
	global_store_dwordx4 v42, v[148:151], s[12:13] sc1
	s_nop 1
	v_cndmask_b32_e32 v148, v32, v44, vcc
	v_cndmask_b32_e32 v149, v33, v45, vcc
	v_cndmask_b32_e32 v150, v34, v46, vcc
	v_cndmask_b32_e32 v151, v35, v47, vcc
	v_cndmask_b32_e64 v152, v32, v24, s[98:99]
	v_cndmask_b32_e64 v153, v33, v25, s[98:99]
	v_cndmask_b32_e64 v154, v34, v26, s[98:99]
	v_cndmask_b32_e64 v155, v35, v27, s[98:99]
	v_fma_f32 v156, v120, v32, v104
	v_fma_f32 v157, v121, v33, v105
	v_fma_f32 v158, v122, v34, v106
	v_fma_f32 v159, v123, v35, v107
	v_fmac_f32_dpp v156, v148, v124 row_ror:1 row_mask:0xf bank_mask:0xf
	v_fmac_f32_dpp v157, v149, v125 row_ror:1 row_mask:0xf bank_mask:0xf
	v_fmac_f32_dpp v158, v150, v126 row_ror:1 row_mask:0xf bank_mask:0xf
	v_fmac_f32_dpp v159, v151, v127 row_ror:1 row_mask:0xf bank_mask:0xf
	v_fmac_f32_dpp v156, v152, v116 row_ror:15 row_mask:0xf bank_mask:0xf
	v_fmac_f32_dpp v157, v153, v117 row_ror:15 row_mask:0xf bank_mask:0xf
	v_fmac_f32_dpp v158, v154, v118 row_ror:15 row_mask:0xf bank_mask:0xf
	v_fmac_f32_dpp v159, v155, v119 row_ror:15 row_mask:0xf bank_mask:0xf
	v_cndmask_b32_e32 v148, v8, v20, vcc
	v_cndmask_b32_e32 v149, v9, v21, vcc
	v_cndmask_b32_e32 v150, v10, v22, vcc
	v_cndmask_b32_e32 v151, v11, v23, vcc
	v_cndmask_b32_e64 v152, v8, v4, s[98:99]
	v_cndmask_b32_e64 v153, v9, v5, s[98:99]
	v_cndmask_b32_e64 v154, v10, v6, s[98:99]
	v_cndmask_b32_e64 v155, v11, v7, s[98:99]
	v_fma_f32 v237, v100, v8, v80
	v_fma_f32 v238, v101, v9, v81
	v_fma_f32 v239, v102, v10, v82
	v_fma_f32 v240, v103, v11, v83
	v_fmac_f32_dpp v237, v148, v112 row_ror:1 row_mask:0xf bank_mask:0xf
	v_fmac_f32_dpp v238, v149, v113 row_ror:1 row_mask:0xf bank_mask:0xf
	v_fmac_f32_dpp v239, v150, v114 row_ror:1 row_mask:0xf bank_mask:0xf
	v_fmac_f32_dpp v240, v151, v115 row_ror:1 row_mask:0xf bank_mask:0xf
	v_fmac_f32_dpp v237, v152, v92 row_ror:15 row_mask:0xf bank_mask:0xf
	v_fmac_f32_dpp v238, v153, v93 row_ror:15 row_mask:0xf bank_mask:0xf
	v_fmac_f32_dpp v239, v154, v94 row_ror:15 row_mask:0xf bank_mask:0xf
	v_fmac_f32_dpp v240, v155, v95 row_ror:15 row_mask:0xf bank_mask:0xf
	v_mul_f32_e32 v148, 0xbfb8aa3b, v156
	v_mul_f32_e32 v149, 0xbfb8aa3b, v157
	v_mul_f32_e32 v150, 0xbfb8aa3b, v158
	v_mul_f32_e32 v151, 0xbfb8aa3b, v159
	v_exp_f32_e32 v148, v148
	v_exp_f32_e32 v149, v149
	v_exp_f32_e32 v150, v150
	v_exp_f32_e32 v151, v151
	v_add_f32_e32 v148, 1.0, v148
	v_add_f32_e32 v149, 1.0, v149
	v_add_f32_e32 v150, 1.0, v150
	v_add_f32_e32 v151, 1.0, v151
	v_rcp_f32_e32 v148, v148
	v_rcp_f32_e32 v149, v149
	v_rcp_f32_e32 v150, v150
	v_rcp_f32_e32 v151, v151
	v_mul_f32_e32 v156, v156, v148
	v_mul_f32_e32 v157, v157, v149
	v_mul_f32_e32 v158, v158, v150
	v_mul_f32_e32 v159, v159, v151
	v_mul_f32_e32 v156, v156, v237
	v_mul_f32_e32 v157, v157, v238
	v_mul_f32_e32 v158, v158, v239
	v_mul_f32_e32 v159, v159, v240
	v_cvt_pk_bf16_f32 v40, v156, v157
	v_cvt_pk_bf16_f32 v41, v158, v159
	v_bfi_b32 v18, v146, v72, v40
	v_bfi_b32 v19, v146, v73, v41
	ds_swizzle_b32 v16, v18 offset:0x401f
	ds_swizzle_b32 v17, v19 offset:0x401f
	v_add_u32_e32 v42, 0xc6000, v250
	s_waitcnt lgkmcnt(0)
	v_bfi_b32 v148, v146, v16, v72
	v_bfi_b32 v149, v146, v17, v73
	v_bfi_b32 v150, v146, v40, v16
	v_bfi_b32 v151, v146, v41, v17
	global_store_dwordx4 v42, v[148:151], s[12:13] sc1
	s_nop 1
	v_cndmask_b32_e32 v148, v24, v32, vcc
	v_cndmask_b32_e32 v149, v25, v33, vcc
	v_cndmask_b32_e32 v150, v26, v34, vcc
	v_cndmask_b32_e32 v151, v27, v35, vcc
	v_cndmask_b32_e64 v152, v24, v12, s[98:99]
	v_cndmask_b32_e64 v153, v25, v13, s[98:99]
	v_cndmask_b32_e64 v154, v26, v14, s[98:99]
	v_cndmask_b32_e64 v155, v27, v15, s[98:99]
	v_fma_f32 v156, v120, v24, v104
	v_fma_f32 v157, v121, v25, v105
	v_fma_f32 v158, v122, v26, v106
	v_fma_f32 v159, v123, v27, v107
	v_fmac_f32_dpp v156, v148, v124 row_ror:1 row_mask:0xf bank_mask:0xf
	v_fmac_f32_dpp v157, v149, v125 row_ror:1 row_mask:0xf bank_mask:0xf
	v_fmac_f32_dpp v158, v150, v126 row_ror:1 row_mask:0xf bank_mask:0xf
	v_fmac_f32_dpp v159, v151, v127 row_ror:1 row_mask:0xf bank_mask:0xf
	v_fmac_f32_dpp v156, v152, v116 row_ror:15 row_mask:0xf bank_mask:0xf
	v_fmac_f32_dpp v157, v153, v117 row_ror:15 row_mask:0xf bank_mask:0xf
	v_fmac_f32_dpp v158, v154, v118 row_ror:15 row_mask:0xf bank_mask:0xf
	v_fmac_f32_dpp v159, v155, v119 row_ror:15 row_mask:0xf bank_mask:0xf
	v_cndmask_b32_e32 v148, v4, v8, vcc
	v_cndmask_b32_e32 v149, v5, v9, vcc
	v_cndmask_b32_e32 v150, v6, v10, vcc
	v_cndmask_b32_e32 v151, v7, v11, vcc
	v_cndmask_b32_e64 v152, v4, v0, s[98:99]
	v_cndmask_b32_e64 v153, v5, v1, s[98:99]
	v_cndmask_b32_e64 v154, v6, v2, s[98:99]
	v_cndmask_b32_e64 v155, v7, v3, s[98:99]
	v_fma_f32 v237, v100, v4, v80
	v_fma_f32 v238, v101, v5, v81
	v_fma_f32 v239, v102, v6, v82
	v_fma_f32 v240, v103, v7, v83
	v_fmac_f32_dpp v237, v148, v112 row_ror:1 row_mask:0xf bank_mask:0xf
	v_fmac_f32_dpp v238, v149, v113 row_ror:1 row_mask:0xf bank_mask:0xf
	v_fmac_f32_dpp v239, v150, v114 row_ror:1 row_mask:0xf bank_mask:0xf
	v_fmac_f32_dpp v240, v151, v115 row_ror:1 row_mask:0xf bank_mask:0xf
	v_fmac_f32_dpp v237, v152, v92 row_ror:15 row_mask:0xf bank_mask:0xf
	v_fmac_f32_dpp v238, v153, v93 row_ror:15 row_mask:0xf bank_mask:0xf
	v_fmac_f32_dpp v239, v154, v94 row_ror:15 row_mask:0xf bank_mask:0xf
	v_fmac_f32_dpp v240, v155, v95 row_ror:15 row_mask:0xf bank_mask:0xf
	v_mul_f32_e32 v148, 0xbfb8aa3b, v156
	v_mul_f32_e32 v149, 0xbfb8aa3b, v157
	v_mul_f32_e32 v150, 0xbfb8aa3b, v158
	v_mul_f32_e32 v151, 0xbfb8aa3b, v159
	v_exp_f32_e32 v148, v148
	v_exp_f32_e32 v149, v149
	v_exp_f32_e32 v150, v150
	v_exp_f32_e32 v151, v151
	v_add_f32_e32 v148, 1.0, v148
	v_add_f32_e32 v149, 1.0, v149
	v_add_f32_e32 v150, 1.0, v150
	v_add_f32_e32 v151, 1.0, v151
	v_rcp_f32_e32 v148, v148
	v_rcp_f32_e32 v149, v149
	v_rcp_f32_e32 v150, v150
	v_rcp_f32_e32 v151, v151
	v_mul_f32_e32 v156, v156, v148
	v_mul_f32_e32 v157, v157, v149
	v_mul_f32_e32 v158, v158, v150
	v_mul_f32_e32 v159, v159, v151
	v_mul_f32_e32 v156, v156, v237
	v_mul_f32_e32 v157, v157, v238
	v_mul_f32_e32 v158, v158, v239
	v_mul_f32_e32 v159, v159, v240
	v_cvt_pk_bf16_f32 v40, v156, v157
	v_cvt_pk_bf16_f32 v41, v158, v159
	v_bfi_b32 v18, v146, v74, v40
	v_bfi_b32 v19, v146, v75, v41
	ds_swizzle_b32 v16, v18 offset:0x401f
	ds_swizzle_b32 v17, v19 offset:0x401f
	v_add_u32_e32 v42, 0xdc000, v250
	s_waitcnt lgkmcnt(0)
	v_bfi_b32 v148, v146, v16, v74
	v_bfi_b32 v149, v146, v17, v75
	v_bfi_b32 v150, v146, v40, v16
	v_bfi_b32 v151, v146, v41, v17
	global_store_dwordx4 v42, v[148:151], s[12:13] sc1
	s_nop 1
	s_waitcnt lgkmcnt(0)
	v_cndmask_b32_e32 v148, v12, v24, vcc
	v_cndmask_b32_e32 v149, v13, v25, vcc
	v_cndmask_b32_e32 v150, v14, v26, vcc
	v_cndmask_b32_e32 v151, v15, v27, vcc
	v_cndmask_b32_e64 v152, v12, v160, s[98:99]
	v_cndmask_b32_e64 v153, v13, v161, s[98:99]
	v_cndmask_b32_e64 v154, v14, v162, s[98:99]
	v_cndmask_b32_e64 v155, v15, v163, s[98:99]
	v_fma_f32 v156, v120, v12, v104
	v_fma_f32 v157, v121, v13, v105
	v_fma_f32 v158, v122, v14, v106
	v_fma_f32 v159, v123, v15, v107
	v_fmac_f32_dpp v156, v148, v124 row_ror:1 row_mask:0xf bank_mask:0xf
	v_fmac_f32_dpp v157, v149, v125 row_ror:1 row_mask:0xf bank_mask:0xf
	v_fmac_f32_dpp v158, v150, v126 row_ror:1 row_mask:0xf bank_mask:0xf
	v_fmac_f32_dpp v159, v151, v127 row_ror:1 row_mask:0xf bank_mask:0xf
	v_fmac_f32_dpp v156, v152, v116 row_ror:15 row_mask:0xf bank_mask:0xf
	v_fmac_f32_dpp v157, v153, v117 row_ror:15 row_mask:0xf bank_mask:0xf
	v_fmac_f32_dpp v158, v154, v118 row_ror:15 row_mask:0xf bank_mask:0xf
	v_fmac_f32_dpp v159, v155, v119 row_ror:15 row_mask:0xf bank_mask:0xf
	v_cndmask_b32_e32 v148, v0, v4, vcc
	v_cndmask_b32_e32 v149, v1, v5, vcc
	v_cndmask_b32_e32 v150, v2, v6, vcc
	v_cndmask_b32_e32 v151, v3, v7, vcc
	v_cndmask_b32_e64 v152, v0, v164, s[98:99]
	v_cndmask_b32_e64 v153, v1, v165, s[98:99]
	v_cndmask_b32_e64 v154, v2, v166, s[98:99]
	v_cndmask_b32_e64 v155, v3, v167, s[98:99]
	v_fma_f32 v237, v100, v0, v80
	v_fma_f32 v238, v101, v1, v81
	v_fma_f32 v239, v102, v2, v82
	v_fma_f32 v240, v103, v3, v83
	v_fmac_f32_dpp v237, v148, v112 row_ror:1 row_mask:0xf bank_mask:0xf
	v_fmac_f32_dpp v238, v149, v113 row_ror:1 row_mask:0xf bank_mask:0xf
	v_fmac_f32_dpp v239, v150, v114 row_ror:1 row_mask:0xf bank_mask:0xf
	v_fmac_f32_dpp v240, v151, v115 row_ror:1 row_mask:0xf bank_mask:0xf
	v_fmac_f32_dpp v237, v152, v92 row_ror:15 row_mask:0xf bank_mask:0xf
	v_fmac_f32_dpp v238, v153, v93 row_ror:15 row_mask:0xf bank_mask:0xf
	v_fmac_f32_dpp v239, v154, v94 row_ror:15 row_mask:0xf bank_mask:0xf
	v_fmac_f32_dpp v240, v155, v95 row_ror:15 row_mask:0xf bank_mask:0xf
	v_mul_f32_e32 v148, 0xbfb8aa3b, v156
	v_mul_f32_e32 v149, 0xbfb8aa3b, v157
	v_mul_f32_e32 v150, 0xbfb8aa3b, v158
	v_mul_f32_e32 v151, 0xbfb8aa3b, v159
	v_exp_f32_e32 v148, v148
	v_exp_f32_e32 v149, v149
	v_exp_f32_e32 v150, v150
	v_exp_f32_e32 v151, v151
	v_add_f32_e32 v148, 1.0, v148
	v_add_f32_e32 v149, 1.0, v149
	v_add_f32_e32 v150, 1.0, v150
	v_add_f32_e32 v151, 1.0, v151
	v_rcp_f32_e32 v148, v148
	v_rcp_f32_e32 v149, v149
	v_rcp_f32_e32 v150, v150
	v_rcp_f32_e32 v151, v151
	v_mul_f32_e32 v156, v156, v148
	v_mul_f32_e32 v157, v157, v149
	v_mul_f32_e32 v158, v158, v150
	v_mul_f32_e32 v159, v159, v151
	v_mul_f32_e32 v156, v156, v237
	v_mul_f32_e32 v157, v157, v238
	v_mul_f32_e32 v158, v158, v239
	v_mul_f32_e32 v159, v159, v240
	v_cvt_pk_bf16_f32 v40, v156, v157
	v_cvt_pk_bf16_f32 v41, v158, v159
	v_bfi_b32 v18, v146, v48, v40
	v_bfi_b32 v19, v146, v49, v41
	ds_swizzle_b32 v16, v18 offset:0x401f
	ds_swizzle_b32 v17, v19 offset:0x401f
	v_add_u32_e32 v42, 0xf2000, v250
	v_lshrrev_b32_e32 v152, 6, v251
	s_nop 1
	v_readfirstlane_b32 s100, v152
	s_waitcnt lgkmcnt(0)
	v_bfi_b32 v148, v146, v16, v48
	v_bfi_b32 v149, v146, v17, v49
	v_bfi_b32 v150, v146, v40, v16
	v_bfi_b32 v151, v146, v41, v17
	s_cmp_eq_u32 s100, 1
	s_cselect_b64 s[100:101], vcc, 0
	s_andn2_b64 exec, exec, s[100:101]
	global_store_dwordx4 v42, v[148:151], s[12:13] sc1
	s_mov_b64 exec, -1
	s_nop 1
	s_branch .LBB0_2210

.LBB0_2279:
	ds_read_b128 v[148:151], v145
	ds_read_b128 v[152:155], v145 offset:1024
	ds_read_b128 v[156:159], v145 offset:2048
	ds_read_b128 v[160:163], v145 offset:3072
	s_add_u32 s14, s12, 0x100
	s_addc_u32 s15, s13, 0
	s_cmp_eq_u32 s43, 40
	s_cselect_b32 s19, s7, s15
	s_cselect_b32 s18, s6, s14
	s_cselect_b32 s17, s1, s42
	s_cselect_b32 s16, s0, s41
	s_mov_b32 m0, s36
	v_lshl_add_u64 v[168:169], s[12:13], 0, v[136:137]
	ds_read_b128 v[164:167], v146
	ds_read_b128 v[172:175], v146 offset:1024
	ds_read_b128 v[176:179], v146 offset:2048
	ds_read_b128 v[180:183], v146 offset:3072
	ds_read_b128 v[184:187], v146 offset:4096
	ds_read_b128 v[188:191], v146 offset:5120
	ds_read_b128 v[192:195], v146 offset:6144
	ds_read_b128 v[196:199], v146 offset:7168
	global_load_lds_dwordx4 v[168:169], off
	v_lshl_add_u64 v[168:169], s[12:13], 0, v[134:135]
	s_mov_b32 m0, s37
	s_nop 0
	global_load_lds_dwordx4 v[168:169], off
	s_waitcnt lgkmcnt(8)
	s_barrier
	s_waitcnt lgkmcnt(0)
	s_setprio 1
	s_waitcnt lgkmcnt(0)
	v_mfma_f32_16x16x32_bf16 v[124:127], v[148:151], v[164:167], v[124:127]
	v_mfma_f32_16x16x32_bf16 v[120:123], v[156:159], v[164:167], v[120:123]
	v_mfma_f32_16x16x32_bf16 v[116:119], v[148:151], v[176:179], v[116:119]
	v_mfma_f32_16x16x32_bf16 v[108:111], v[156:159], v[176:179], v[108:111]
	v_mfma_f32_16x16x32_bf16 v[100:103], v[148:151], v[184:187], v[100:103]
	v_mfma_f32_16x16x32_bf16 v[92:95], v[156:159], v[184:187], v[92:95]
	v_mfma_f32_16x16x32_bf16 v[84:87], v[148:151], v[192:195], v[84:87]
	v_mfma_f32_16x16x32_bf16 v[76:79], v[156:159], v[192:195], v[76:79]
	v_mfma_f32_16x16x32_bf16 v[124:127], v[152:155], v[172:175], v[124:127]
	v_mfma_f32_16x16x32_bf16 v[120:123], v[160:163], v[172:175], v[120:123]
	v_mfma_f32_16x16x32_bf16 v[116:119], v[152:155], v[180:183], v[116:119]
	v_mfma_f32_16x16x32_bf16 v[108:111], v[160:163], v[180:183], v[108:111]
	v_mfma_f32_16x16x32_bf16 v[100:103], v[152:155], v[188:191], v[100:103]
	v_mfma_f32_16x16x32_bf16 v[92:95], v[160:163], v[188:191], v[92:95]
	v_mfma_f32_16x16x32_bf16 v[84:87], v[152:155], v[196:199], v[84:87]
	v_mfma_f32_16x16x32_bf16 v[76:79], v[160:163], v[196:199], v[76:79]
	s_setprio 0
	s_barrier
	s_add_i32 s12, s34, s25
	v_lshl_add_u64 v[168:169], s[16:17], 0, v[130:131]
	s_mov_b32 m0, s12
	ds_read_b128 v[200:203], v147
	ds_read_b128 v[204:207], v147 offset:1024
	ds_read_b128 v[208:211], v147 offset:2048
	ds_read_b128 v[212:215], v147 offset:3072
	global_load_lds_dwordx4 v[168:169], off
	v_lshl_add_u64 v[216:217], s[16:17], 0, v[128:129]
	s_add_i32 m0, s12, 0x2000
	s_nop 0
	global_load_lds_dwordx4 v[216:217], off
	s_barrier
	s_waitcnt lgkmcnt(0)
	s_setprio 1
	s_waitcnt lgkmcnt(0)
	v_mfma_f32_16x16x32_bf16 v[112:115], v[200:203], v[164:167], v[112:115]
	v_mfma_f32_16x16x32_bf16 v[104:107], v[208:211], v[164:167], v[104:107]
	v_mfma_f32_16x16x32_bf16 v[96:99], v[200:203], v[176:179], v[96:99]
	v_mfma_f32_16x16x32_bf16 v[88:91], v[208:211], v[176:179], v[88:91]
	v_mfma_f32_16x16x32_bf16 v[80:83], v[200:203], v[184:187], v[80:83]
	v_mfma_f32_16x16x32_bf16 v[72:75], v[208:211], v[184:187], v[72:75]
	v_mfma_f32_16x16x32_bf16 v[68:71], v[200:203], v[192:195], v[68:71]
	v_mfma_f32_16x16x32_bf16 v[64:67], v[208:211], v[192:195], v[64:67]
	v_mfma_f32_16x16x32_bf16 v[112:115], v[204:207], v[172:175], v[112:115]
	v_mfma_f32_16x16x32_bf16 v[104:107], v[212:215], v[172:175], v[104:107]
	v_mfma_f32_16x16x32_bf16 v[96:99], v[204:207], v[180:183], v[96:99]
	v_mfma_f32_16x16x32_bf16 v[88:91], v[212:215], v[180:183], v[88:91]
	v_mfma_f32_16x16x32_bf16 v[80:83], v[204:207], v[188:191], v[80:83]
	v_mfma_f32_16x16x32_bf16 v[72:75], v[212:215], v[188:191], v[72:75]
	v_mfma_f32_16x16x32_bf16 v[68:71], v[204:207], v[196:199], v[68:71]
	v_mfma_f32_16x16x32_bf16 v[64:67], v[212:215], v[196:199], v[64:67]
	s_setprio 0
	s_mov_b32 m0, s26
	v_lshl_add_u64 v[218:219], s[18:19], 0, v[130:131]
	s_barrier
	ds_read_b128 v[164:167], v146 offset:16384
	ds_read_b128 v[172:175], v146 offset:17408
	ds_read_b128 v[176:179], v146 offset:18432
	ds_read_b128 v[180:183], v146 offset:19456
	ds_read_b128 v[184:187], v146 offset:20480
	ds_read_b128 v[188:191], v146 offset:21504
	ds_read_b128 v[192:195], v146 offset:22528
	ds_read_b128 v[196:199], v146 offset:23552
	global_load_lds_dwordx4 v[218:219], off
	v_lshl_add_u64 v[220:221], s[18:19], 0, v[128:129]
	s_mov_b32 m0, s27
	s_nop 0
	global_load_lds_dwordx4 v[220:221], off
	s_barrier
	s_waitcnt lgkmcnt(0)
	s_setprio 1
	s_waitcnt lgkmcnt(0)
	v_mfma_f32_16x16x32_bf16 v[60:63], v[148:151], v[164:167], v[60:63]
	v_mfma_f32_16x16x32_bf16 v[56:59], v[156:159], v[164:167], v[56:59]
	v_mfma_f32_16x16x32_bf16 v[52:55], v[148:151], v[176:179], v[52:55]
	v_mfma_f32_16x16x32_bf16 v[44:47], v[156:159], v[176:179], v[44:47]
	v_mfma_f32_16x16x32_bf16 v[36:39], v[148:151], v[184:187], v[36:39]
	v_mfma_f32_16x16x32_bf16 v[28:31], v[156:159], v[184:187], v[28:31]
	v_mfma_f32_16x16x32_bf16 v[20:23], v[148:151], v[192:195], v[20:23]
	v_mfma_f32_16x16x32_bf16 v[12:15], v[156:159], v[192:195], v[12:15]
	v_mfma_f32_16x16x32_bf16 v[60:63], v[152:155], v[172:175], v[60:63]
	v_mfma_f32_16x16x32_bf16 v[56:59], v[160:163], v[172:175], v[56:59]
	v_mfma_f32_16x16x32_bf16 v[52:55], v[152:155], v[180:183], v[52:55]
	v_mfma_f32_16x16x32_bf16 v[44:47], v[160:163], v[180:183], v[44:47]
	v_mfma_f32_16x16x32_bf16 v[36:39], v[152:155], v[188:191], v[36:39]
	v_mfma_f32_16x16x32_bf16 v[28:31], v[160:163], v[188:191], v[28:31]
	v_mfma_f32_16x16x32_bf16 v[20:23], v[152:155], v[196:199], v[20:23]
	v_mfma_f32_16x16x32_bf16 v[12:15], v[160:163], v[196:199], v[12:15]
	s_setprio 0
	s_barrier
	s_add_u32 s12, s16, 0xb0000
	s_addc_u32 s13, s17, 0
	s_add_i32 s44, s35, s25
	v_lshl_add_u64 v[148:149], s[12:13], 0, v[130:131]
	s_mov_b32 m0, s44
	s_nop 0
	global_load_lds_dwordx4 v[148:149], off
	v_lshl_add_u64 v[148:149], s[12:13], 0, v[128:129]
	s_add_i32 m0, s44, 0x2000
	s_nop 0
	global_load_lds_dwordx4 v[148:149], off
	s_waitcnt vmcnt(6)
	s_barrier
	s_setprio 1
	v_mfma_f32_16x16x32_bf16 v[48:51], v[200:203], v[164:167], v[48:51]
	v_mfma_f32_16x16x32_bf16 v[40:43], v[208:211], v[164:167], v[40:43]
	v_mfma_f32_16x16x32_bf16 v[32:35], v[200:203], v[176:179], v[32:35]
	v_mfma_f32_16x16x32_bf16 v[24:27], v[208:211], v[176:179], v[24:27]
	v_mfma_f32_16x16x32_bf16 v[16:19], v[200:203], v[184:187], v[16:19]
	v_mfma_f32_16x16x32_bf16 v[8:11], v[208:211], v[184:187], v[8:11]
	v_mfma_f32_16x16x32_bf16 v[4:7], v[200:203], v[192:195], v[4:7]
	v_mfma_f32_16x16x32_bf16 v[0:3], v[208:211], v[192:195], v[0:3]
	v_mfma_f32_16x16x32_bf16 v[48:51], v[204:207], v[172:175], v[48:51]
	v_mfma_f32_16x16x32_bf16 v[40:43], v[212:215], v[172:175], v[40:43]
	v_mfma_f32_16x16x32_bf16 v[32:35], v[204:207], v[180:183], v[32:35]
	v_mfma_f32_16x16x32_bf16 v[24:27], v[212:215], v[180:183], v[24:27]
	v_mfma_f32_16x16x32_bf16 v[16:19], v[204:207], v[188:191], v[16:19]
	v_mfma_f32_16x16x32_bf16 v[8:11], v[212:215], v[188:191], v[8:11]
	v_mfma_f32_16x16x32_bf16 v[4:7], v[204:207], v[196:199], v[4:7]
	v_mfma_f32_16x16x32_bf16 v[0:3], v[212:215], v[196:199], v[0:3]
	s_setprio 0
	s_add_i32 s44, 0, 0x18000
	v_add_u32_e32 v160, s44, v144
	s_barrier
	ds_read_b128 v[148:151], v160
	ds_read_b128 v[152:155], v160 offset:1024
	ds_read_b128 v[156:159], v160 offset:2048
	ds_read_b128 v[160:163], v160 offset:3072
	s_add_u32 s12, s18, 0xb0000
	s_addc_u32 s13, s19, 0
	s_mov_b32 m0, s28
	v_lshl_add_u64 v[200:201], s[12:13], 0, v[130:131]
	ds_read_b128 v[164:167], v146 offset:32768
	ds_read_b128 v[172:175], v146 offset:33792
	ds_read_b128 v[176:179], v146 offset:34816
	ds_read_b128 v[180:183], v146 offset:35840
	ds_read_b128 v[184:187], v146 offset:36864
	ds_read_b128 v[188:191], v146 offset:37888
	ds_read_b128 v[192:195], v146 offset:38912
	ds_read_b128 v[196:199], v146 offset:39936
	global_load_lds_dwordx4 v[200:201], off
	v_lshl_add_u64 v[200:201], s[12:13], 0, v[128:129]
	s_mov_b32 m0, s29
	s_nop 0
	global_load_lds_dwordx4 v[200:201], off
	s_waitcnt lgkmcnt(8)
	s_barrier
	s_waitcnt lgkmcnt(0)
	s_setprio 1
	s_waitcnt lgkmcnt(0)
	v_mfma_f32_16x16x32_bf16 v[124:127], v[148:151], v[164:167], v[124:127]
	v_mfma_f32_16x16x32_bf16 v[120:123], v[156:159], v[164:167], v[120:123]
	v_mfma_f32_16x16x32_bf16 v[116:119], v[148:151], v[176:179], v[116:119]
	v_mfma_f32_16x16x32_bf16 v[108:111], v[156:159], v[176:179], v[108:111]
	v_mfma_f32_16x16x32_bf16 v[100:103], v[148:151], v[184:187], v[100:103]
	v_mfma_f32_16x16x32_bf16 v[92:95], v[156:159], v[184:187], v[92:95]
	v_mfma_f32_16x16x32_bf16 v[84:87], v[148:151], v[192:195], v[84:87]
	v_mfma_f32_16x16x32_bf16 v[76:79], v[156:159], v[192:195], v[76:79]
	v_mfma_f32_16x16x32_bf16 v[124:127], v[152:155], v[172:175], v[124:127]
	v_mfma_f32_16x16x32_bf16 v[120:123], v[160:163], v[172:175], v[120:123]
	v_mfma_f32_16x16x32_bf16 v[116:119], v[152:155], v[180:183], v[116:119]
	v_mfma_f32_16x16x32_bf16 v[108:111], v[160:163], v[180:183], v[108:111]
	v_mfma_f32_16x16x32_bf16 v[100:103], v[152:155], v[188:191], v[100:103]
	v_mfma_f32_16x16x32_bf16 v[92:95], v[160:163], v[188:191], v[92:95]
	v_mfma_f32_16x16x32_bf16 v[84:87], v[152:155], v[196:199], v[84:87]
	v_mfma_f32_16x16x32_bf16 v[76:79], v[160:163], v[196:199], v[76:79]
	s_setprio 0
	s_barrier
	s_add_i32 s18, 0, 0x1c000
	s_add_i32 s12, s44, s25
	v_add_u32_e32 v171, s18, v144
	v_lshl_add_u64 v[168:169], v[168:169], 0, s[10:11]
	s_mov_b32 m0, s12
	ds_read_b128 v[200:203], v171
	ds_read_b128 v[204:207], v171 offset:1024
	ds_read_b128 v[208:211], v171 offset:2048
	ds_read_b128 v[212:215], v171 offset:3072
	global_load_lds_dwordx4 v[168:169], off
	v_lshl_add_u64 v[168:169], v[216:217], 0, s[10:11]
	s_add_i32 m0, s12, 0x2000
	s_nop 0
	global_load_lds_dwordx4 v[168:169], off
	s_barrier
	s_waitcnt lgkmcnt(0)
	s_setprio 1
	s_waitcnt lgkmcnt(0)
	v_mfma_f32_16x16x32_bf16 v[112:115], v[200:203], v[164:167], v[112:115]
	v_mfma_f32_16x16x32_bf16 v[104:107], v[208:211], v[164:167], v[104:107]
	v_mfma_f32_16x16x32_bf16 v[96:99], v[200:203], v[176:179], v[96:99]
	v_mfma_f32_16x16x32_bf16 v[88:91], v[208:211], v[176:179], v[88:91]
	v_mfma_f32_16x16x32_bf16 v[80:83], v[200:203], v[184:187], v[80:83]
	v_mfma_f32_16x16x32_bf16 v[72:75], v[208:211], v[184:187], v[72:75]
	v_mfma_f32_16x16x32_bf16 v[68:71], v[200:203], v[192:195], v[68:71]
	v_mfma_f32_16x16x32_bf16 v[64:67], v[208:211], v[192:195], v[64:67]
	v_mfma_f32_16x16x32_bf16 v[112:115], v[204:207], v[172:175], v[112:115]
	v_mfma_f32_16x16x32_bf16 v[104:107], v[212:215], v[172:175], v[104:107]
	v_mfma_f32_16x16x32_bf16 v[96:99], v[204:207], v[180:183], v[96:99]
	v_mfma_f32_16x16x32_bf16 v[88:91], v[212:215], v[180:183], v[88:91]
	v_mfma_f32_16x16x32_bf16 v[80:83], v[204:207], v[188:191], v[80:83]
	v_mfma_f32_16x16x32_bf16 v[72:75], v[212:215], v[188:191], v[72:75]
	v_mfma_f32_16x16x32_bf16 v[68:71], v[204:207], v[196:199], v[68:71]
	v_mfma_f32_16x16x32_bf16 v[64:67], v[212:215], v[196:199], v[64:67]
	s_setprio 0
	s_mov_b32 m0, s30
	v_lshl_add_u64 v[168:169], v[218:219], 0, s[10:11]
	s_barrier
	ds_read_b128 v[164:167], v146 offset:49152
	ds_read_b128 v[172:175], v146 offset:50176
	ds_read_b128 v[176:179], v146 offset:51200
	ds_read_b128 v[180:183], v146 offset:52224
	ds_read_b128 v[184:187], v146 offset:53248
	ds_read_b128 v[188:191], v146 offset:54272
	ds_read_b128 v[192:195], v146 offset:55296
	ds_read_b128 v[196:199], v146 offset:56320
	global_load_lds_dwordx4 v[168:169], off
	v_lshl_add_u64 v[168:169], v[220:221], 0, s[10:11]
	s_mov_b32 m0, s31
	s_nop 0
	global_load_lds_dwordx4 v[168:169], off
	s_barrier
	s_waitcnt lgkmcnt(0)
	s_setprio 1
	s_waitcnt lgkmcnt(0)
	v_mfma_f32_16x16x32_bf16 v[60:63], v[148:151], v[164:167], v[60:63]
	v_mfma_f32_16x16x32_bf16 v[56:59], v[156:159], v[164:167], v[56:59]
	v_mfma_f32_16x16x32_bf16 v[52:55], v[148:151], v[176:179], v[52:55]
	v_mfma_f32_16x16x32_bf16 v[44:47], v[156:159], v[176:179], v[44:47]
	v_mfma_f32_16x16x32_bf16 v[36:39], v[148:151], v[184:187], v[36:39]
	v_mfma_f32_16x16x32_bf16 v[28:31], v[156:159], v[184:187], v[28:31]
	v_mfma_f32_16x16x32_bf16 v[20:23], v[148:151], v[192:195], v[20:23]
	v_mfma_f32_16x16x32_bf16 v[12:15], v[156:159], v[192:195], v[12:15]
	v_mfma_f32_16x16x32_bf16 v[60:63], v[152:155], v[172:175], v[60:63]
	v_mfma_f32_16x16x32_bf16 v[56:59], v[160:163], v[172:175], v[56:59]
	v_mfma_f32_16x16x32_bf16 v[52:55], v[152:155], v[180:183], v[52:55]
	v_mfma_f32_16x16x32_bf16 v[44:47], v[160:163], v[180:183], v[44:47]
	v_mfma_f32_16x16x32_bf16 v[36:39], v[152:155], v[188:191], v[36:39]
	v_mfma_f32_16x16x32_bf16 v[28:31], v[160:163], v[188:191], v[28:31]
	v_mfma_f32_16x16x32_bf16 v[20:23], v[152:155], v[196:199], v[20:23]
	v_mfma_f32_16x16x32_bf16 v[12:15], v[160:163], v[196:199], v[12:15]
	s_setprio 0
	s_barrier
	s_add_u32 s12, s16, 0xb0080
	s_addc_u32 s13, s17, 0
	s_add_i32 s16, s18, s25
	v_lshl_add_u64 v[148:149], s[12:13], 0, v[130:131]
	s_mov_b32 m0, s16
	s_nop 0
	global_load_lds_dwordx4 v[148:149], off
	v_lshl_add_u64 v[148:149], s[12:13], 0, v[128:129]
	s_add_i32 m0, s16, 0x2000
	s_nop 0
	global_load_lds_dwordx4 v[148:149], off
	s_waitcnt vmcnt(6)
	s_barrier
	s_setprio 1
	v_mfma_f32_16x16x32_bf16 v[48:51], v[200:203], v[164:167], v[48:51]
	v_mfma_f32_16x16x32_bf16 v[40:43], v[208:211], v[164:167], v[40:43]
	v_mfma_f32_16x16x32_bf16 v[32:35], v[200:203], v[176:179], v[32:35]
	v_mfma_f32_16x16x32_bf16 v[24:27], v[208:211], v[176:179], v[24:27]
	v_mfma_f32_16x16x32_bf16 v[16:19], v[200:203], v[184:187], v[16:19]
	v_mfma_f32_16x16x32_bf16 v[8:11], v[208:211], v[184:187], v[8:11]
	v_mfma_f32_16x16x32_bf16 v[4:7], v[200:203], v[192:195], v[4:7]
	v_mfma_f32_16x16x32_bf16 v[0:3], v[208:211], v[192:195], v[0:3]
	v_mfma_f32_16x16x32_bf16 v[48:51], v[204:207], v[172:175], v[48:51]
	v_mfma_f32_16x16x32_bf16 v[40:43], v[212:215], v[172:175], v[40:43]
	v_mfma_f32_16x16x32_bf16 v[32:35], v[204:207], v[180:183], v[32:35]
	v_mfma_f32_16x16x32_bf16 v[24:27], v[212:215], v[180:183], v[24:27]
	v_mfma_f32_16x16x32_bf16 v[16:19], v[204:207], v[188:191], v[16:19]
	v_mfma_f32_16x16x32_bf16 v[8:11], v[212:215], v[188:191], v[8:11]
	v_mfma_f32_16x16x32_bf16 v[4:7], v[204:207], v[196:199], v[4:7]
	v_mfma_f32_16x16x32_bf16 v[0:3], v[212:215], v[196:199], v[0:3]
	s_setprio 0
	s_add_i32 s43, s43, 2
	s_add_u32 s41, s41, 0x100
	s_addc_u32 s42, s42, 0
	s_cmp_gt_u32 s43, 41
	s_mov_b64 s[12:13], s[14:15]
	s_barrier
	s_cbranch_scc0 .LBB0_2279
	v_readlane_b32 s12, v235, 24
	v_lshl_add_u32 v148, s12, 8, v143
	v_readlane_b32 s12, v235, 16
	s_lshl_b32 s12, s12, 8
	v_ashrrev_i32_e32 v149, 31, v148
	s_ashr_i32 s13, s12, 31
	v_lshlrev_b64 v[150:151], 11, v[148:149]
	v_lshl_add_u64 v[150:151], s[2:3], 0, v[150:151]
	s_lshl_b64 s[12:13], s[12:13], 1
	v_lshl_add_u64 v[150:151], v[150:151], 0, s[12:13]
	v_lshl_add_u64 v[150:151], v[150:151], 0, s[8:9]
	v_lshl_add_u64 v[150:151], v[150:151], 0, v[132:133]
	v_mbcnt_lo_u32_b32 v237, -1, 0
	v_mbcnt_hi_u32_b32 v237, -1, v237
	v_bfe_i32 v237, v237, 4, 1
	v_and_b32_e32 v244, 24, v237
	v_add_co_u32_e32 v248, vcc, v244, v150
	s_nop 1
	v_addc_co_u32_e32 v249, vcc, 0, v151, vcc
	v_cvt_pk_bf16_f32 v124, v124, v125
	v_cvt_pk_bf16_f32 v125, v126, v127
	v_cvt_pk_bf16_f32 v120, v120, v121
	v_cvt_pk_bf16_f32 v121, v122, v123
	v_bfi_b32 v244, v237, v124, v120
	v_bfi_b32 v245, v237, v125, v121
	ds_swizzle_b32 v250, v244 offset:0x401f
	ds_swizzle_b32 v251, v245 offset:0x401f
	v_cvt_pk_bf16_f32 v112, v112, v113
	v_cvt_pk_bf16_f32 v113, v114, v115
	v_cvt_pk_bf16_f32 v104, v104, v105
	v_cvt_pk_bf16_f32 v105, v106, v107
	v_bfi_b32 v246, v237, v112, v104
	v_bfi_b32 v247, v237, v113, v105
	ds_swizzle_b32 v252, v246 offset:0x401f
	ds_swizzle_b32 v253, v247 offset:0x401f
	s_waitcnt lgkmcnt(0)
	v_bfi_b32 v240, v237, v250, v124
	v_bfi_b32 v241, v237, v251, v125
	v_bfi_b32 v242, v237, v120, v250
	v_bfi_b32 v243, v237, v121, v251
	global_store_dwordx4 v[248:249], v[240:243], off sc1
	s_nop 1
	v_bfi_b32 v240, v237, v252, v112
	v_bfi_b32 v241, v237, v253, v113
	v_bfi_b32 v242, v237, v104, v252
	v_bfi_b32 v243, v237, v105, v253
	global_store_dwordx4 v[248:249], v[240:243], off offset:256 sc1
	s_nop 1
	v_add_co_u32_e32 v238, vcc, 0x8000, v248
	s_nop 1
	v_addc_co_u32_e32 v239, vcc, 0, v249, vcc
	v_cvt_pk_bf16_f32 v116, v116, v117
	v_cvt_pk_bf16_f32 v117, v118, v119
	v_cvt_pk_bf16_f32 v108, v108, v109
	v_cvt_pk_bf16_f32 v109, v110, v111
	v_bfi_b32 v244, v237, v116, v108
	v_bfi_b32 v245, v237, v117, v109
	ds_swizzle_b32 v250, v244 offset:0x401f
	ds_swizzle_b32 v251, v245 offset:0x401f
	v_cvt_pk_bf16_f32 v96, v96, v97
	v_cvt_pk_bf16_f32 v97, v98, v99
	v_cvt_pk_bf16_f32 v88, v88, v89
	v_cvt_pk_bf16_f32 v89, v90, v91
	v_bfi_b32 v246, v237, v96, v88
	v_bfi_b32 v247, v237, v97, v89
	ds_swizzle_b32 v252, v246 offset:0x401f
	ds_swizzle_b32 v253, v247 offset:0x401f
	s_waitcnt lgkmcnt(0)
	v_bfi_b32 v240, v237, v250, v116
	v_bfi_b32 v241, v237, v251, v117
	v_bfi_b32 v242, v237, v108, v250
	v_bfi_b32 v243, v237, v109, v251
	global_store_dwordx4 v[238:239], v[240:243], off sc1
	s_nop 1
	v_bfi_b32 v240, v237, v252, v96
	v_bfi_b32 v241, v237, v253, v97
	v_bfi_b32 v242, v237, v88, v252
	v_bfi_b32 v243, v237, v89, v253
	global_store_dwordx4 v[238:239], v[240:243], off offset:256 sc1
	s_nop 1
	v_add_co_u32_e32 v238, vcc, 0x10000, v248
	s_nop 1
	v_addc_co_u32_e32 v239, vcc, 0, v249, vcc
	v_cvt_pk_bf16_f32 v100, v100, v101
	v_cvt_pk_bf16_f32 v101, v102, v103
	v_cvt_pk_bf16_f32 v92, v92, v93
	v_cvt_pk_bf16_f32 v93, v94, v95
	v_bfi_b32 v244, v237, v100, v92
	v_bfi_b32 v245, v237, v101, v93
	ds_swizzle_b32 v250, v244 offset:0x401f
	ds_swizzle_b32 v251, v245 offset:0x401f
	v_cvt_pk_bf16_f32 v80, v80, v81
	v_cvt_pk_bf16_f32 v81, v82, v83
	v_cvt_pk_bf16_f32 v72, v72, v73
	v_cvt_pk_bf16_f32 v73, v74, v75
	v_bfi_b32 v246, v237, v80, v72
	v_bfi_b32 v247, v237, v81, v73
	ds_swizzle_b32 v252, v246 offset:0x401f
	ds_swizzle_b32 v253, v247 offset:0x401f
	s_waitcnt lgkmcnt(0)
	v_bfi_b32 v240, v237, v250, v100
	v_bfi_b32 v241, v237, v251, v101
	v_bfi_b32 v242, v237, v92, v250
	v_bfi_b32 v243, v237, v93, v251
	global_store_dwordx4 v[238:239], v[240:243], off sc1
	s_nop 1
	v_bfi_b32 v240, v237, v252, v80
	v_bfi_b32 v241, v237, v253, v81
	v_bfi_b32 v242, v237, v72, v252
	v_bfi_b32 v243, v237, v73, v253
	global_store_dwordx4 v[238:239], v[240:243], off offset:256 sc1
	s_nop 1
	v_add_co_u32_e32 v238, vcc, 0x18000, v248
	s_nop 1
	v_addc_co_u32_e32 v239, vcc, 0, v249, vcc
	v_cvt_pk_bf16_f32 v84, v84, v85
	v_cvt_pk_bf16_f32 v85, v86, v87
	v_cvt_pk_bf16_f32 v76, v76, v77
	v_cvt_pk_bf16_f32 v77, v78, v79
	v_bfi_b32 v244, v237, v84, v76
	v_bfi_b32 v245, v237, v85, v77
	ds_swizzle_b32 v250, v244 offset:0x401f
	ds_swizzle_b32 v251, v245 offset:0x401f
	v_cvt_pk_bf16_f32 v68, v68, v69
	v_cvt_pk_bf16_f32 v69, v70, v71
	v_cvt_pk_bf16_f32 v64, v64, v65
	v_cvt_pk_bf16_f32 v65, v66, v67
	v_bfi_b32 v246, v237, v68, v64
	v_bfi_b32 v247, v237, v69, v65
	ds_swizzle_b32 v252, v246 offset:0x401f
	ds_swizzle_b32 v253, v247 offset:0x401f
	s_waitcnt lgkmcnt(0)
	v_bfi_b32 v240, v237, v250, v84
	v_bfi_b32 v241, v237, v251, v85
	v_bfi_b32 v242, v237, v76, v250
	v_bfi_b32 v243, v237, v77, v251
	global_store_dwordx4 v[238:239], v[240:243], off sc1
	s_nop 1
	v_bfi_b32 v240, v237, v252, v68
	v_bfi_b32 v241, v237, v253, v69
	v_bfi_b32 v242, v237, v64, v252
	v_bfi_b32 v243, v237, v65, v253
	global_store_dwordx4 v[238:239], v[240:243], off offset:256 sc1
	s_nop 1
	v_add_co_u32_e32 v238, vcc, 0x40000, v248
	s_nop 1
	v_addc_co_u32_e32 v239, vcc, 0, v249, vcc
	v_cvt_pk_bf16_f32 v60, v60, v61
	v_cvt_pk_bf16_f32 v61, v62, v63
	v_cvt_pk_bf16_f32 v56, v56, v57
	v_cvt_pk_bf16_f32 v57, v58, v59
	v_bfi_b32 v244, v237, v60, v56
	v_bfi_b32 v245, v237, v61, v57
	ds_swizzle_b32 v250, v244 offset:0x401f
	ds_swizzle_b32 v251, v245 offset:0x401f
	v_cvt_pk_bf16_f32 v48, v48, v49
	v_cvt_pk_bf16_f32 v49, v50, v51
	v_cvt_pk_bf16_f32 v40, v40, v41
	v_cvt_pk_bf16_f32 v41, v42, v43
	v_bfi_b32 v246, v237, v48, v40
	v_bfi_b32 v247, v237, v49, v41
	ds_swizzle_b32 v252, v246 offset:0x401f
	ds_swizzle_b32 v253, v247 offset:0x401f
	s_waitcnt lgkmcnt(0)
	v_bfi_b32 v240, v237, v250, v60
	v_bfi_b32 v241, v237, v251, v61
	v_bfi_b32 v242, v237, v56, v250
	v_bfi_b32 v243, v237, v57, v251
	global_store_dwordx4 v[238:239], v[240:243], off sc1
	s_nop 1
	v_bfi_b32 v240, v237, v252, v48
	v_bfi_b32 v241, v237, v253, v49
	v_bfi_b32 v242, v237, v40, v252
	v_bfi_b32 v243, v237, v41, v253
	global_store_dwordx4 v[238:239], v[240:243], off offset:256 sc1
	s_nop 1
	v_add_co_u32_e32 v238, vcc, 0x48000, v248
	s_nop 1
	v_addc_co_u32_e32 v239, vcc, 0, v249, vcc
	v_cvt_pk_bf16_f32 v52, v52, v53
	v_cvt_pk_bf16_f32 v53, v54, v55
	v_cvt_pk_bf16_f32 v44, v44, v45
	v_cvt_pk_bf16_f32 v45, v46, v47
	v_bfi_b32 v244, v237, v52, v44
	v_bfi_b32 v245, v237, v53, v45
	ds_swizzle_b32 v250, v244 offset:0x401f
	ds_swizzle_b32 v251, v245 offset:0x401f
	v_cvt_pk_bf16_f32 v32, v32, v33
	v_cvt_pk_bf16_f32 v33, v34, v35
	v_cvt_pk_bf16_f32 v24, v24, v25
	v_cvt_pk_bf16_f32 v25, v26, v27
	v_bfi_b32 v246, v237, v32, v24
	v_bfi_b32 v247, v237, v33, v25
	ds_swizzle_b32 v252, v246 offset:0x401f
	ds_swizzle_b32 v253, v247 offset:0x401f
	s_waitcnt lgkmcnt(0)
	v_bfi_b32 v240, v237, v250, v52
	v_bfi_b32 v241, v237, v251, v53
	v_bfi_b32 v242, v237, v44, v250
	v_bfi_b32 v243, v237, v45, v251
	global_store_dwordx4 v[238:239], v[240:243], off sc1
	s_nop 1
	v_bfi_b32 v240, v237, v252, v32
	v_bfi_b32 v241, v237, v253, v33
	v_bfi_b32 v242, v237, v24, v252
	v_bfi_b32 v243, v237, v25, v253
	global_store_dwordx4 v[238:239], v[240:243], off offset:256 sc1
	s_nop 1
	v_add_co_u32_e32 v238, vcc, 0x50000, v248
	s_nop 1
	v_addc_co_u32_e32 v239, vcc, 0, v249, vcc
	v_cvt_pk_bf16_f32 v36, v36, v37
	v_cvt_pk_bf16_f32 v37, v38, v39
	v_cvt_pk_bf16_f32 v28, v28, v29
	v_cvt_pk_bf16_f32 v29, v30, v31
	v_bfi_b32 v244, v237, v36, v28
	v_bfi_b32 v245, v237, v37, v29
	ds_swizzle_b32 v250, v244 offset:0x401f
	ds_swizzle_b32 v251, v245 offset:0x401f
	v_cvt_pk_bf16_f32 v16, v16, v17
	v_cvt_pk_bf16_f32 v17, v18, v19
	v_cvt_pk_bf16_f32 v8, v8, v9
	v_cvt_pk_bf16_f32 v9, v10, v11
	v_bfi_b32 v246, v237, v16, v8
	v_bfi_b32 v247, v237, v17, v9
	ds_swizzle_b32 v252, v246 offset:0x401f
	ds_swizzle_b32 v253, v247 offset:0x401f
	s_waitcnt lgkmcnt(0)
	v_bfi_b32 v240, v237, v250, v36
	v_bfi_b32 v241, v237, v251, v37
	v_bfi_b32 v242, v237, v28, v250
	v_bfi_b32 v243, v237, v29, v251
	global_store_dwordx4 v[238:239], v[240:243], off sc1
	s_nop 1
	v_bfi_b32 v240, v237, v252, v16
	v_bfi_b32 v241, v237, v253, v17
	v_bfi_b32 v242, v237, v8, v252
	v_bfi_b32 v243, v237, v9, v253
	global_store_dwordx4 v[238:239], v[240:243], off offset:256 sc1
	s_nop 1
	v_add_co_u32_e32 v238, vcc, 0x58000, v248
	s_nop 1
	v_addc_co_u32_e32 v239, vcc, 0, v249, vcc
	v_cvt_pk_bf16_f32 v20, v20, v21
	v_cvt_pk_bf16_f32 v21, v22, v23
	v_cvt_pk_bf16_f32 v12, v12, v13
	v_cvt_pk_bf16_f32 v13, v14, v15
	v_bfi_b32 v244, v237, v20, v12
	v_bfi_b32 v245, v237, v21, v13
	ds_swizzle_b32 v250, v244 offset:0x401f
	ds_swizzle_b32 v251, v245 offset:0x401f
	v_cvt_pk_bf16_f32 v4, v4, v5
	v_cvt_pk_bf16_f32 v5, v6, v7
	v_cvt_pk_bf16_f32 v0, v0, v1
	v_cvt_pk_bf16_f32 v1, v2, v3
	v_bfi_b32 v246, v237, v4, v0
	v_bfi_b32 v247, v237, v5, v1
	ds_swizzle_b32 v252, v246 offset:0x401f
	ds_swizzle_b32 v253, v247 offset:0x401f
	s_waitcnt lgkmcnt(0)
	v_bfi_b32 v240, v237, v250, v20
	v_bfi_b32 v241, v237, v251, v21
	v_bfi_b32 v242, v237, v12, v250
	v_bfi_b32 v243, v237, v13, v251
	global_store_dwordx4 v[238:239], v[240:243], off sc1
	s_nop 1
	v_bfi_b32 v240, v237, v252, v4
	v_bfi_b32 v241, v237, v253, v5
	v_bfi_b32 v242, v237, v0, v252
	v_bfi_b32 v243, v237, v1, v253
	global_store_dwordx4 v[238:239], v[240:243], off offset:256 sc1
	s_nop 1
	s_and_b64 vcc, exec, s[4:5]
	v_writelane_b32 v235, s39, 16
	s_mov_b64 s[14:15], s[0:1]
	s_mov_b64 s[12:13], s[6:7]
	v_writelane_b32 v235, s40, 24
	s_cbranch_vccz .LBB0_2272
	s_waitcnt vmcnt(0)
	s_cmpk_gt_u32 s20, 0xff
	s_cbranch_scc1 .LBB0_2283
	s_barrier
